# diff-attn and MLA bodies: ring slots as immediates (x3 unroll), m0 from SALU add, unclamped pointer advance, MLA running max folded into MFMA C init
# speedup vs baseline: 1.0323x; 1.0191x over previous
; template <int MODE>
; __device__ __forceinline__ void attn_phase(LAS unsigned char* lds, const bf16* Qp, const bf16* Kp, const bf16* KPEp, const bf16* Vtp, bf16* CAT, float lam, int vcu, int G) {
;     ...
;         int tid_ = threadIdx.x; asm volatile("" : "+v"(tid_)); const int tid = tid_, lane = tid & 63, wave = __builtin_amdgcn_readfirstlane(tid >> 6), r = lane & 31, hh = lane >> 5;
;         int b, h, q0, wq, map, bh;
;         if (MODE == 0) { const int qb = unit & 31; bh = unit >> 5; b = bh >> 2; h = bh & 3; q0 = qb * 256; wq = wave; map = 0; }
;         else { const int qb = unit & 63; bh = unit >> 6; b = bh >> 3; h = bh & 7; q0 = qb * 128; wq = wave & 3; map = wave >> 2; }
;         const size_t rowbase = (size_t)b * SEQ;
;         const size_t qrow = rowbase + q0 + 32 * wq + r;
;         bf16x8 qf[NKS];
;         {
;             const bf16* qp = MODE == 0 ? Qp + qrow * 768 + h * 192 + 8 * hh : Qp + qrow * 1024 + (2 * h + map) * 64 + 8 * hh;
; #pragma unroll
;             for (int ks = 0; ks < NKS; ++ks) qf[ks] = *(const bf16x8*)(qp + 16 * ks);
;         }
;         const bf16* kp[NKI]; int kadv[NKI];
; #pragma unroll
;         for (int n = 0; n < NKI; ++n) {
;             const int P = 64 * (wave + 8 * n) + lane;
;             if (MODE == 0) {
;                 const int row = P / 24, cp = P - row * 24, c = (cp & ~7) | ((cp & 7) ^ ((row >> 1) & 7));
;                 if (c < 16) { kp[n] = Kp + (rowbase + row) * 512 + h * 128 + c * 8; kadv[n] = 64 * 512; }
;                 else { kp[n] = KPEp + (rowbase + row) * 64 + (c - 16) * 8; kadv[n] = 64 * 64; }
;             } else {
;                 const int row = P >> 4, c = (P & 15) ^ (row & 15);
;                 kp[n] = Kp + (rowbase + row) * 1024 + h * 128 + c * 8; kadv[n] = 64 * 1024;
;             }
;         }
;         const bf16* vp[2];
; #pragma unroll
;         for (int n = 0; n < 2; ++n) { const int P = 64 * (wave + 8 * n) + lane, dv = P >> 3, c = (P & 7) ^ ((dv >> 1) & 7); vp[n] = Vtp + ((size_t)(bh * 128 + dv)) * SEQ + c * 8; }
;         const unsigned kdma = lds0 + wave * 1024, vdma = lds0 + 3 * KB + wave * 1024;
;     ...
;         const int ka = MODE == 0 ? r * RB + ((hh ^ ((r >> 1) & 7)) * 16) : r * RB + (((map * 8 + hh) ^ (r & 15)) * 16);
;         const int va = r * 128 + ((hh ^ ((r >> 1) & 7)) * 16);
;         const LAS unsigned char* vring = lds + 3 * KB;
;         f32x16 o[4], S0, S1;
.LBB0_759:
	v_mov_b32_e32 v76, v235
	s_lshl_b32 s9, s0, 7
	v_readfirstlane_b32 s16, v76
	s_ashr_i32 s3, s16, 6
	s_and_b32 s19, s3, 3
	s_ashr_i32 s10, s0, 9
	s_and_b32 s9, s9, 0x1f80
	s_lshl_b32 s17, s19, 5
	v_and_b32_e32 v4, 31, v76
	s_ashr_i32 s11, s10, 31
	s_or_b32 s9, s17, s9
	s_ashr_i32 s18, s16, 8
	s_lshl_b64 s[10:11], s[10:11], 13
	v_or_b32_e32 v0, s9, v4
	s_lshl_b32 s9, s0, 1
	v_or_b32_e32 v0, s10, v0
	v_mov_b32_e32 v1, s11
	s_and_b32 s20, s9, 0xffffff80
	s_and_b32 s17, s9, 0x380
	s_lshl_b32 s9, s18, 6
	v_lshlrev_b64 v[172:173], 10, v[0:1]
	v_lshlrev_b64 v[0:1], 11, v[0:1]
	s_add_i32 s38, s9, s17
	v_bfe_u32 v253, v76, 5, 1
	v_lshl_add_u64 v[0:1], s[54:55], 0, v[0:1]
	s_ashr_i32 s39, s38, 31
	v_lshl_add_u64 v[0:1], s[38:39], 1, v[0:1]
	v_lshlrev_b32_e32 v232, 4, v253
	v_lshl_add_u64 v[0:1], v[0:1], 0, v[232:233]
	global_load_dwordx4 v[108:111], v[0:1], off
	global_load_dwordx4 v[104:107], v[0:1], off offset:32
	global_load_dwordx4 v[100:103], v[0:1], off offset:64
	global_load_dwordx4 v[96:99], v[0:1], off offset:96
	v_mov_b32_e32 v0, s16
	s_movk_i32 s9, 0xffc0
	v_bfi_b32 v2, s9, v0, v76
	v_ashrrev_i32_e32 v0, 4, v2
	s_and_b32 s8, s5, 0xffffff80
	s_lshl_b32 s9, s17, 1
	v_ashrrev_i32_e32 v1, 31, v0
	s_add_u32 s38, s1, s9
	v_xor_b32_e32 v3, v0, v76
	v_lshl_add_u64 v[0:1], s[10:11], 0, v[0:1]
	s_addc_u32 s39, s4, 0
	v_lshlrev_b64 v[0:1], 11, v[0:1]
	v_lshlrev_b32_e32 v3, 4, v3
	v_lshl_add_u64 v[0:1], s[38:39], 0, v[0:1]
	v_and_b32_e32 v232, 0xf0, v3
	v_add_u32_e32 v3, 0x200, v2
	v_lshl_add_u64 v[48:49], v[0:1], 0, v[232:233]
	v_ashrrev_i32_e32 v0, 4, v3
	v_ashrrev_i32_e32 v1, 31, v0
	v_xor_b32_e32 v5, v0, v76
	v_lshl_add_u64 v[0:1], s[10:11], 0, v[0:1]
	s_lshl_b32 s3, s3, 10
	v_lshlrev_b64 v[0:1], 11, v[0:1]
	v_lshlrev_b32_e32 v5, 4, v5
	v_lshrrev_b32_e32 v78, 4, v2
	s_add_i32 s58, s3, 0
	s_lshl_b32 s3, s18, 3
	v_and_b32_e32 v6, 15, v76
	v_lshl_add_u64 v[0:1], s[38:39], 0, v[0:1]
	v_and_b32_e32 v232, 0xf0, v5
	v_ashrrev_i32_e32 v77, 3, v2
	v_xor_b32_e32 v2, v78, v76
	v_lshlrev_b32_e32 v5, 8, v4
	v_bitop3_b32 v6, s3, v6, v253 bitop3:0x36
	v_lshl_add_u64 v[50:51], v[0:1], 0, v[232:233]
	v_add_u32_e32 v0, s20, v77
	v_lshlrev_b32_e32 v2, 4, v2
	v_ashrrev_i32_e32 v79, 3, v3
	v_lshl_add_u32 v132, v6, 4, v5
	v_lshrrev_b32_e32 v5, 1, v76
	v_subrev_u32_e32 v60, s1, v48
	v_lshrrev_b32_e32 v61, 3, v60
	v_and_b32_e32 v61, 0x1fff00, v61
	v_bfe_u32 v62, v60, 8, 3
	v_lshl_or_b32 v61, v62, 21, v61
	v_and_b32_e32 v60, 0x30000ff, v60
	v_or_b32_e32 v60, v60, v61
	v_mov_b32_e32 v49, s4
	v_add_co_u32_e32 v48, vcc, s1, v60
	s_nop 1
	v_addc_co_u32_e32 v49, vcc, 0, v49, vcc
	v_subrev_u32_e32 v60, s1, v50
	v_lshrrev_b32_e32 v61, 3, v60
	v_and_b32_e32 v61, 0x1fff00, v61
	v_bfe_u32 v62, v60, 8, 3
	v_lshl_or_b32 v61, v62, 21, v61
	v_and_b32_e32 v60, 0x30000ff, v60
	v_or_b32_e32 v60, v60, v61
	v_mov_b32_e32 v51, s4
	v_add_co_u32_e32 v50, vcc, s1, v60
	s_nop 1
	v_addc_co_u32_e32 v51, vcc, 0, v51, vcc
	s_mov_b32 s3, m0
	s_mov_b32 m0, s58
	s_nop 0
	global_load_lds_dwordx4 v[48:49], off
	s_mov_b32 m0, s3
	v_ashrrev_i32_e32 v1, 31, v0
	v_and_b32_e32 v232, 0x70, v2
	v_add_u32_e32 v2, s20, v79
	v_bitop3_b32 v5, v253, v5, 7 bitop3:0x78
	s_add_i32 s59, s58, 0x2000
	s_mov_b32 s3, m0
	s_mov_b32 m0, s59
	s_nop 0
	global_load_lds_dwordx4 v[50:51], off
	s_mov_b32 m0, s3
	s_mov_b64 s[10:11], 0x4000
	v_lshlrev_b64 v[0:1], 14, v[0:1]
	v_ashrrev_i32_e32 v3, 31, v2
	v_lshlrev_b32_e32 v80, 4, v5
	v_lshlrev_b32_e32 v81, 7, v4
	v_lshl_add_u64 v[4:5], v[48:49], 0, s[10:11]
	s_add_i32 s3, s58, 0x4000
	s_mov_b32 s9, m0
	s_mov_b32 m0, s3
	s_nop 0
	global_load_lds_dwordx4 v[4:5], off
	s_mov_b32 m0, s9
	v_lshl_add_u64 v[0:1], s[72:73], 0, v[0:1]
	v_lshlrev_b64 v[2:3], 14, v[2:3]
	v_lshl_add_u64 v[6:7], v[50:51], 0, s[10:11]
	s_add_i32 s3, s58, 0x6000
	s_mov_b32 s9, m0
	s_mov_b32 m0, s3
	s_nop 0
	global_load_lds_dwordx4 v[6:7], off
	s_mov_b32 m0, s9
	v_lshl_add_u64 v[0:1], v[0:1], 0, v[232:233]
	v_lshl_add_u64 v[2:3], s[72:73], 0, v[2:3]
	s_add_i32 s65, s58, 0xc000
	s_mov_b32 s3, m0
	s_mov_b32 m0, s65
	s_nop 0
	global_load_lds_dwordx4 v[0:1], off
	s_mov_b32 m0, s3
	v_lshl_add_u64 v[2:3], v[2:3], 0, v[232:233]
	s_add_i32 s3, s58, 0xe000
	s_mov_b32 s9, m0
	s_mov_b32 m0, s3
	s_nop 0
	global_load_lds_dwordx4 v[2:3], off
	s_mov_b32 m0, s9
	v_xor_b32_e32 v137, 32, v132
	v_xor_b32_e32 v138, 64, v132
	v_xor_b32_e32 v139, 0x60, v132
	v_subrev_u32_e32 v128, s1, v48
	v_subrev_u32_e32 v129, s1, v50
	v_subrev_u32_e32 v130, s72, v0
	v_subrev_u32_e32 v131, s72, v2
	v_or_b32_e32 v176, v80, v81
	v_xor_b32_e32 v177, 32, v176
	v_xor_b32_e32 v178, 64, v176
	v_xor_b32_e32 v179, 0x60, v176
	v_add_u32_e32 v216, 0xc000, v176
	v_add_u32_e32 v217, 0xc000, v177
	v_add_u32_e32 v218, 0xc000, v178
	v_add_u32_e32 v219, 0xc000, v179
	v_mov_b32_e32 v234, v235
	v_and_b32_e32 v235, 63, v76
	s_mov_b32 s42, m0
	s_add_u32 s8, s1, 0x8000
	s_addc_u32 s9, s4, 0
	s_add_u32 s10, s72, 0x80
	s_addc_u32 s11, s73, 0
	s_mov_b32 s41, 0
	s_waitcnt vmcnt(0) lgkmcnt(0)
	s_barrier
; #define ATT_DMA_K(slotoff) do { _Pragma("unroll") for (int n = 0; n < NKI; ++n) glds16(kp[n], (unsigned)__builtin_amdgcn_readfirstlane(kdma + (slotoff) + n * 8192)); } while (0)
; #define ATT_DMA_V(slotoff) do { _Pragma("unroll") for (int n = 0; n < 2; ++n) glds16(vp[n], (unsigned)__builtin_amdgcn_readfirstlane(vdma + (slotoff) + n * 8192)); } while (0)
; #define ATT_ADV_K() do { _Pragma("unroll") for (int n = 0; n < NKI; ++n) kp[n] += kadv[n]; } while (0)
; #define ATT_ADV_V() do { _Pragma("unroll") for (int n = 0; n < 2; ++n) vp[n] += 64; } while (0)
; template <int MODE>
; __device__ __forceinline__ void attn_phase(LAS unsigned char* lds, const bf16* Qp, const bf16* Kp, const bf16* KPEp, const bf16* Vtp, bf16* CAT, float lam, int vcu, int G) {
;     ...
;         ATT_DMA_K(0); ATT_ADV_K(); ATT_DMA_K(KB); ATT_ADV_K(); ATT_DMA_V(0); ATT_ADV_V();
;         asm volatile("s_waitcnt vmcnt(0) lgkmcnt(0)\n\ts_barrier" ::: "memory");
;         int kr = 0, kw = 2 * KB, vr = 2 * VB, vw = VB;
;         if constexpr (MODE == 1) {
;             bf16x8 pfB[4];
;             bf16x8 kf[8], vf[8], vg[8];
;             float fp = 1.f; bool pend = false;
;     ...
;             ATT1_ITER(pfB, pf, 0, false);
	ds_read_b128 v[140:143], v132
	ds_read_b128 v[144:147], v137
	ds_read_b128 v[148:151], v138
	ds_read_b128 v[152:155], v139
	ds_read_b128 v[156:159], v132 offset:8192
	ds_read_b128 v[160:163], v137 offset:8192
	ds_read_b128 v[164:167], v138 offset:8192
	ds_read_b128 v[168:171], v139 offset:8192
	v_mov_b64_e32 v[0:1], 0
	v_mov_b64_e32 v[2:3], 0
	v_mov_b64_e32 v[4:5], 0
	v_mov_b64_e32 v[6:7], 0
	v_mov_b64_e32 v[8:9], 0
	v_mov_b64_e32 v[10:11], 0
	v_mov_b64_e32 v[12:13], 0
	v_mov_b64_e32 v[14:15], 0
	v_mov_b64_e32 v[16:17], 0
	v_mov_b64_e32 v[18:19], 0
	v_mov_b64_e32 v[20:21], 0
	v_mov_b64_e32 v[22:23], 0
	v_mov_b64_e32 v[24:25], 0
	v_mov_b64_e32 v[26:27], 0
	v_mov_b64_e32 v[28:29], 0
	v_mov_b64_e32 v[30:31], 0
	v_mov_b64_e32 v[32:33], 0
	v_mov_b64_e32 v[34:35], 0
	v_mov_b64_e32 v[36:37], 0
	v_mov_b64_e32 v[38:39], 0
	v_mov_b64_e32 v[40:41], 0
	v_mov_b64_e32 v[42:43], 0
	v_mov_b64_e32 v[44:45], 0
	v_mov_b64_e32 v[46:47], 0
	v_mov_b64_e32 v[48:49], 0
	v_mov_b64_e32 v[50:51], 0
	v_mov_b64_e32 v[52:53], 0
	v_mov_b64_e32 v[54:55], 0
	v_mov_b64_e32 v[56:57], 0
	v_mov_b64_e32 v[58:59], 0
	v_mov_b64_e32 v[60:61], 0
	v_mov_b64_e32 v[62:63], 0
	s_waitcnt lgkmcnt(7)
	v_mfma_f32_32x32x16_bf16 v[64:79], v[140:143], v[108:111], 0
	s_add_i32 m0, s58, 0x8000
	s_nop 0
	global_load_lds_dwordx4 v128, s[8:9]
	s_waitcnt lgkmcnt(6)
	v_mfma_f32_32x32x16_bf16 v[64:79], v[144:147], v[104:107], v[64:79]
	s_add_i32 m0, s58, 0xa000
	s_nop 0
	global_load_lds_dwordx4 v129, s[8:9]
	s_waitcnt lgkmcnt(5)
	v_mfma_f32_32x32x16_bf16 v[64:79], v[148:151], v[100:103], v[64:79]
	s_add_u32 s8, s8, 0x4000
	s_addc_u32 s9, s9, 0
	s_waitcnt lgkmcnt(4)
	v_mfma_f32_32x32x16_bf16 v[64:79], v[152:155], v[96:99], v[64:79]
	s_add_i32 m0, s65, 0x4000
	s_nop 0
	global_load_lds_dwordx4 v130, s[10:11]
	s_waitcnt lgkmcnt(3)
	v_mfma_f32_32x32x16_bf16 v[80:95], v[156:159], v[108:111], 0
	s_add_i32 m0, s65, 0x6000
	s_nop 0
	global_load_lds_dwordx4 v131, s[10:11]
	s_waitcnt lgkmcnt(2)
	v_mfma_f32_32x32x16_bf16 v[80:95], v[160:163], v[104:107], v[80:95]
	s_add_u32 s10, s10, 0x80
	s_addc_u32 s11, s11, 0
	s_waitcnt lgkmcnt(1)
	v_mfma_f32_32x32x16_bf16 v[80:95], v[164:167], v[100:103], v[80:95]
	s_waitcnt lgkmcnt(0)
	v_mfma_f32_32x32x16_bf16 v[80:95], v[168:171], v[96:99], v[80:95]
	s_nop 11
	v_max3_f32 v224, v64, v65, v66
	v_max3_f32 v225, v67, v68, v69
	v_max3_f32 v224, v224, v70, v71
	v_max3_f32 v225, v225, v72, v73
	v_max3_f32 v224, v224, v74, v75
	v_max3_f32 v225, v225, v76, v77
	v_max3_f32 v224, v224, v78, v79
	v_max3_f32 v224, v224, v80, v81
	v_max3_f32 v225, v225, v82, v83
	v_max3_f32 v224, v224, v84, v85
	v_max3_f32 v225, v225, v86, v87
	v_max3_f32 v224, v224, v88, v89
	v_max3_f32 v225, v225, v90, v91
	v_max3_f32 v224, v224, v92, v93
	v_max3_f32 v225, v225, v94, v95
	v_max_f32_e32 v224, v224, v225
	v_mov_b32_e32 v225, v224
	s_nop 1
	v_permlane32_swap_b32_e32 v224, v225
	v_max_f32_e32 v224, v224, v225
	v_sub_f32_e32 v236, 0, v224
	v_sub_f32_e32 v237, 0, v224
	v_sub_f32_e32 v238, 0, v224
	v_sub_f32_e32 v239, 0, v224
	v_sub_f32_e32 v240, 0, v224
	v_sub_f32_e32 v241, 0, v224
	v_sub_f32_e32 v242, 0, v224
	v_sub_f32_e32 v243, 0, v224
	v_sub_f32_e32 v244, 0, v224
	v_sub_f32_e32 v245, 0, v224
	v_sub_f32_e32 v246, 0, v224
	v_sub_f32_e32 v247, 0, v224
	v_sub_f32_e32 v248, 0, v224
	v_sub_f32_e32 v249, 0, v224
	v_sub_f32_e32 v250, 0, v224
	v_sub_f32_e32 v251, 0, v224
	v_sub_f32_e32 v64, v64, v224
	v_sub_f32_e32 v65, v65, v224
	v_sub_f32_e32 v66, v66, v224
	v_sub_f32_e32 v67, v67, v224
	v_sub_f32_e32 v68, v68, v224
	v_sub_f32_e32 v69, v69, v224
	v_sub_f32_e32 v70, v70, v224
	v_sub_f32_e32 v71, v71, v224
	v_sub_f32_e32 v72, v72, v224
	v_sub_f32_e32 v73, v73, v224
	v_sub_f32_e32 v74, v74, v224
	v_sub_f32_e32 v75, v75, v224
	v_sub_f32_e32 v76, v76, v224
	v_sub_f32_e32 v77, v77, v224
	v_sub_f32_e32 v78, v78, v224
	v_sub_f32_e32 v79, v79, v224
	v_sub_f32_e32 v80, v80, v224
	v_sub_f32_e32 v81, v81, v224
	v_sub_f32_e32 v82, v82, v224
	v_sub_f32_e32 v83, v83, v224
	v_sub_f32_e32 v84, v84, v224
	v_sub_f32_e32 v85, v85, v224
	v_sub_f32_e32 v86, v86, v224
	v_sub_f32_e32 v87, v87, v224
	v_sub_f32_e32 v88, v88, v224
	v_sub_f32_e32 v89, v89, v224
	v_sub_f32_e32 v90, v90, v224
	v_sub_f32_e32 v91, v91, v224
	v_sub_f32_e32 v92, v92, v224
	v_sub_f32_e32 v93, v93, v224
	v_sub_f32_e32 v94, v94, v224
	v_sub_f32_e32 v95, v95, v224
	v_mov_b32_e32 v133, 0
	v_mov_b32_e32 v136, 0
	v_exp_f32_e32 v64, v64
	v_exp_f32_e32 v65, v65
	v_add_f32_e32 v133, v133, v64
	v_add_f32_e32 v136, v136, v65
	v_exp_f32_e32 v66, v66
	v_exp_f32_e32 v67, v67
	v_add_f32_e32 v133, v133, v66
	v_add_f32_e32 v136, v136, v67
	v_exp_f32_e32 v68, v68
	v_exp_f32_e32 v69, v69
	v_add_f32_e32 v133, v133, v68
	v_add_f32_e32 v136, v136, v69
	v_exp_f32_e32 v70, v70
	v_exp_f32_e32 v71, v71
	v_add_f32_e32 v133, v133, v70
	v_add_f32_e32 v136, v136, v71
	v_exp_f32_e32 v72, v72
	v_exp_f32_e32 v73, v73
	v_add_f32_e32 v133, v133, v72
	v_add_f32_e32 v136, v136, v73
	v_exp_f32_e32 v74, v74
	v_exp_f32_e32 v75, v75
	v_add_f32_e32 v133, v133, v74
	v_add_f32_e32 v136, v136, v75
	v_exp_f32_e32 v76, v76
	v_exp_f32_e32 v77, v77
	v_add_f32_e32 v133, v133, v76
	v_add_f32_e32 v136, v136, v77
	v_exp_f32_e32 v78, v78
	v_exp_f32_e32 v79, v79
	v_add_f32_e32 v133, v133, v78
	v_add_f32_e32 v136, v136, v79
	v_cvt_pk_bf16_f32 v112, v64, v65
	v_cvt_pk_bf16_f32 v113, v66, v67
	v_cvt_pk_bf16_f32 v114, v68, v69
	v_cvt_pk_bf16_f32 v115, v70, v71
	v_cvt_pk_bf16_f32 v116, v72, v73
	v_cvt_pk_bf16_f32 v117, v74, v75
	v_cvt_pk_bf16_f32 v118, v76, v77
	v_cvt_pk_bf16_f32 v119, v78, v79
	s_mov_b32 s66, 0
	s_waitcnt vmcnt(4) lgkmcnt(0)
	s_barrier
; #define LAS __attribute__((address_space(3)))
; #define MFMA32(a, b, c) __builtin_amdgcn_mfma_f32_32x32x16_bf16((a), (b), (c), 0, 0, 0)
; __device__ __forceinline__ void att1_load(bf16x8 (&kf)[8], bf16x8 (&vf)[8], const LAS unsigned char* kslot, int ka, const LAS unsigned char* vslot, int va) {
; #pragma unroll
;     for (int ks = 0; ks < 4; ++ks) { const LAS unsigned char* p = kslot + (ka ^ (ks * 32)); kf[2 * ks] = *(const LAS bf16x8*)p; kf[2 * ks + 1] = *(const LAS bf16x8*)(p + 32 * 256); }
; #pragma unroll
;     for (int kk = 0; kk < 2; ++kk)
; #pragma unroll
;         for (int db = 0; db < 4; ++db) vf[kk * 4 + db] = *(const LAS bf16x8*)(vslot + ((va ^ (kk * 32)) + db * 4096));
; }
; __device__ __forceinline__ void att1_load2(bf16x8 (&vg)[8], const LAS unsigned char* vslot, int va) {
; #pragma unroll
;     for (int kk = 2; kk < 4; ++kk)
; #pragma unroll
;         for (int db = 0; db < 4; ++db) vg[(kk - 2) * 4 + db] = *(const LAS bf16x8*)(vslot + ((va ^ (kk * 32)) + db * 4096));
; }
; __device__ __forceinline__ void att1_qk(f32x16& s0, f32x16& s1, const bf16x8 (&kf)[8], const bf16x8 (&qf)[4]) {
;     f32x16 z;
; #pragma unroll
;     for (int i = 0; i < 16; ++i) z[i] = 0.f;
;     s0 = MFMA32(kf[0], qf[0], z); s1 = MFMA32(kf[1], qf[0], z);
; #pragma unroll
;     for (int ks = 1; ks < 4; ++ks) { s0 = MFMA32(kf[2 * ks], qf[ks], s0); s1 = MFMA32(kf[2 * ks + 1], qf[ks], s1); }
; }
; __device__ __forceinline__ void att1_pv(f32x16 (&o)[4], const bf16x8 (&vf)[8], const bf16x8 (&vg)[8], const bf16x8 (&pf)[4]) {
; #pragma unroll
;     for (int kk = 0; kk < 2; ++kk)
; #pragma unroll
;         for (int db = 0; db < 4; ++db) o[db] = MFMA32(vf[kk * 4 + db], pf[kk], o[db]);
; #pragma unroll
;     for (int kk = 2; kk < 4; ++kk)
; #pragma unroll
;         for (int db = 0; db < 4; ++db) o[db] = MFMA32(vg[(kk - 2) * 4 + db], pf[kk], o[db]);
; }
.Lda_loop:
	ds_read_b128 v[140:143], v132 offset:16384
	ds_read_b128 v[144:147], v137 offset:16384
	ds_read_b128 v[148:151], v138 offset:16384
	ds_read_b128 v[152:155], v139 offset:16384
	ds_read_b128 v[156:159], v132 offset:24576
	ds_read_b128 v[160:163], v137 offset:24576
	ds_read_b128 v[164:167], v138 offset:24576
	ds_read_b128 v[168:171], v139 offset:24576
	ds_read_b128 v[184:187], v216
	ds_read_b128 v[188:191], v216 offset:4096
	ds_read_b128 v[192:195], v216 offset:8192
	ds_read_b128 v[196:199], v216 offset:12288
	v_exp_f32_e32 v80, v80
	v_exp_f32_e32 v81, v81
	v_add_f32_e32 v133, v133, v80
	v_add_f32_e32 v136, v136, v81
	v_exp_f32_e32 v82, v82
	v_exp_f32_e32 v83, v83
	v_add_f32_e32 v133, v133, v82
	v_add_f32_e32 v136, v136, v83
	s_waitcnt lgkmcnt(8)
	v_mfma_f32_32x32x16_bf16 v[64:79], v[140:143], v[108:111], v[236:251]
	v_exp_f32_e32 v84, v84
	v_exp_f32_e32 v85, v85
	v_add_f32_e32 v133, v133, v84
	v_add_f32_e32 v136, v136, v85
	ds_read_b128 v[200:203], v217
	v_mfma_f32_32x32x16_bf16 v[64:79], v[144:147], v[104:107], v[64:79]
	v_exp_f32_e32 v86, v86
	v_exp_f32_e32 v87, v87
	v_add_f32_e32 v133, v133, v86
	v_add_f32_e32 v136, v136, v87
	ds_read_b128 v[204:207], v217 offset:4096
	v_mfma_f32_32x32x16_bf16 v[64:79], v[148:151], v[100:103], v[64:79]
	v_exp_f32_e32 v88, v88
	v_exp_f32_e32 v89, v89
	v_add_f32_e32 v133, v133, v88
	v_add_f32_e32 v136, v136, v89
	v_cvt_pk_bf16_f32 v120, v80, v81
	v_cvt_pk_bf16_f32 v121, v82, v83
	ds_read_b128 v[208:211], v217 offset:8192
	v_mfma_f32_32x32x16_bf16 v[64:79], v[152:155], v[96:99], v[64:79]
	v_exp_f32_e32 v90, v90
	v_exp_f32_e32 v91, v91
	v_add_f32_e32 v133, v133, v90
	v_add_f32_e32 v136, v136, v91
	v_cvt_pk_bf16_f32 v122, v84, v85
	v_cvt_pk_bf16_f32 v123, v86, v87
	ds_read_b128 v[212:215], v217 offset:12288
	s_waitcnt lgkmcnt(4)
	v_mfma_f32_32x32x16_bf16 v[48:63], v[184:187], v[112:115], v[48:63]
	v_exp_f32_e32 v92, v92
	v_exp_f32_e32 v93, v93
	v_add_f32_e32 v133, v133, v92
	v_add_f32_e32 v136, v136, v93
	ds_read_b128 v[140:143], v218
	v_mfma_f32_32x32x16_bf16 v[32:47], v[188:191], v[112:115], v[32:47]
	v_exp_f32_e32 v94, v94
	v_exp_f32_e32 v95, v95
	v_add_f32_e32 v133, v133, v94
	v_add_f32_e32 v136, v136, v95
	ds_read_b128 v[144:147], v218 offset:4096
	v_mfma_f32_32x32x16_bf16 v[16:31], v[192:195], v[112:115], v[16:31]
	v_cvt_pk_bf16_f32 v124, v88, v89
	v_cvt_pk_bf16_f32 v125, v90, v91
	ds_read_b128 v[148:151], v218 offset:8192
	v_mfma_f32_32x32x16_bf16 v[0:15], v[196:199], v[112:115], v[0:15]
	v_cvt_pk_bf16_f32 v126, v92, v93
	v_cvt_pk_bf16_f32 v127, v94, v95
	ds_read_b128 v[152:155], v218 offset:12288
	v_max3_f32 v224, v64, v65, v66
	v_max3_f32 v225, v67, v68, v69
	v_max3_f32 v224, v224, v70, v71
	v_mfma_f32_32x32x16_bf16 v[80:95], v[156:159], v[108:111], v[236:251]
	s_add_i32 m0, s58, 0x0
	v_max3_f32 v225, v225, v72, v73
	global_load_lds_dwordx4 v128, s[8:9]
	v_mfma_f32_32x32x16_bf16 v[80:95], v[160:163], v[104:107], v[80:95]
	s_add_i32 m0, s58, 0x2000
	v_max3_f32 v224, v224, v74, v75
	global_load_lds_dwordx4 v129, s[8:9]
	ds_read_b128 v[156:159], v219
	v_mfma_f32_32x32x16_bf16 v[80:95], v[164:167], v[100:103], v[80:95]
	s_add_i32 m0, s65, 0x8000
	v_max3_f32 v225, v225, v76, v77
	global_load_lds_dwordx4 v130, s[10:11]
	ds_read_b128 v[160:163], v219 offset:4096
	v_mfma_f32_32x32x16_bf16 v[80:95], v[168:171], v[96:99], v[80:95]
	s_add_i32 m0, s65, 0xa000
	v_max3_f32 v224, v224, v78, v79
	global_load_lds_dwordx4 v131, s[10:11]
	ds_read_b128 v[164:167], v219 offset:8192
	s_waitcnt lgkmcnt(7)
	v_mfma_f32_32x32x16_bf16 v[48:63], v[200:203], v[116:119], v[48:63]
	ds_read_b128 v[168:171], v219 offset:12288
	s_add_u32 s8, s8, 0x4000
	s_addc_u32 s9, s9, 0
	s_add_u32 s10, s10, 0x80
	s_addc_u32 s11, s11, 0
	v_mfma_f32_32x32x16_bf16 v[32:47], v[204:207], v[116:119], v[32:47]
	s_nop 1
	v_max3_f32 v224, v224, v80, v81
	v_max3_f32 v225, v225, v82, v83
	v_max3_f32 v224, v224, v84, v85
	v_max3_f32 v225, v225, v86, v87
	v_mfma_f32_32x32x16_bf16 v[16:31], v[208:211], v[116:119], v[16:31]
	v_max3_f32 v224, v224, v88, v89
	v_max3_f32 v225, v225, v90, v91
	v_max3_f32 v224, v224, v92, v93
	v_max3_f32 v225, v225, v94, v95
	v_max_f32_e32 v224, v224, v225
	v_mov_b32_e32 v225, v224
	s_nop 1
	v_permlane32_swap_b32_e32 v224, v225
	v_max_f32_e32 v224, v224, v225
	v_cmp_lt_f32_e32 vcc, 0x41000000, v224
	v_mfma_f32_32x32x16_bf16 v[0:15], v[212:215], v[116:119], v[0:15]
	s_nop 1
	s_cmp_lg_u64 vcc, 0
	s_cbranch_scc1 .Lda_rareA_0
; __device__ __forceinline__ void att_exp(f32x16& s0, f32x16& s1, float mhat, float& lrun, bf16x8 (&pf)[4]) {
;     float p0 = 0.f, p1 = 0.f;
; #pragma unroll
;     for (int i = 0; i < 16; ++i) { s0[i] = __builtin_amdgcn_exp2f(s0[i] - mhat); s1[i] = __builtin_amdgcn_exp2f(s1[i] - mhat); p0 += s0[i]; p1 += s1[i]; }
;     lrun += p0 + p1;
;     pf[0] = pack8((f32x4){s0[0], s0[1], s0[2], s0[3]}, (f32x4){s0[4], s0[5], s0[6], s0[7]});
;     pf[1] = pack8((f32x4){s0[8], s0[9], s0[10], s0[11]}, (f32x4){s0[12], s0[13], s0[14], s0[15]});
;     pf[2] = pack8((f32x4){s1[0], s1[1], s1[2], s1[3]}, (f32x4){s1[4], s1[5], s1[6], s1[7]});
;     pf[3] = pack8((f32x4){s1[8], s1[9], s1[10], s1[11]}, (f32x4){s1[12], s1[13], s1[14], s1[15]});
; }
; __device__ __forceinline__ void att_pv(f32x16 (&o)[4], const LAS unsigned char* vslot, int va, const bf16x8 (&pf)[4]) {
; #pragma unroll
;     for (int db = 0; db < 4; ++db)
; #pragma unroll
;         for (int kk = 0; kk < 4; ++kk) {
;             const bf16x8 v = *(const LAS bf16x8*)(vslot + ((va ^ (kk * 32)) + db * 4096));
;             o[db] = MFMA32(v, pf[kk], o[db]);
;         }
; }
; __device__ __forceinline__ void att1_load(bf16x8 (&kf)[8], bf16x8 (&vf)[8], const LAS unsigned char* kslot, int ka, const LAS unsigned char* vslot, int va) {
; #pragma unroll
;     for (int ks = 0; ks < 4; ++ks) { const LAS unsigned char* p = kslot + (ka ^ (ks * 32)); kf[2 * ks] = *(const LAS bf16x8*)p; kf[2 * ks + 1] = *(const LAS bf16x8*)(p + 32 * 256); }
; #pragma unroll
;     for (int kk = 0; kk < 2; ++kk)
; #pragma unroll
;         for (int db = 0; db < 4; ++db) vf[kk * 4 + db] = *(const LAS bf16x8*)(vslot + ((va ^ (kk * 32)) + db * 4096));
; }
; __device__ __forceinline__ void att1_load2(bf16x8 (&vg)[8], const LAS unsigned char* vslot, int va) {
; #pragma unroll
;     for (int kk = 2; kk < 4; ++kk)
; #pragma unroll
;         for (int db = 0; db < 4; ++db) vg[(kk - 2) * 4 + db] = *(const LAS bf16x8*)(vslot + ((va ^ (kk * 32)) + db * 4096));
; }
; __device__ __forceinline__ void att1_qk(f32x16& s0, f32x16& s1, const bf16x8 (&kf)[8], const bf16x8 (&qf)[4]) {
;     f32x16 z;
; #pragma unroll
;     for (int i = 0; i < 16; ++i) z[i] = 0.f;
;     s0 = MFMA32(kf[0], qf[0], z); s1 = MFMA32(kf[1], qf[0], z);
; #pragma unroll
;     for (int ks = 1; ks < 4; ++ks) { s0 = MFMA32(kf[2 * ks], qf[ks], s0); s1 = MFMA32(kf[2 * ks + 1], qf[ks], s1); }
; }
.Lda_backA_0:
	v_exp_f32_e32 v64, v64
	v_exp_f32_e32 v65, v65
	v_add_f32_e32 v133, v133, v64
	v_add_f32_e32 v136, v136, v65
	s_waitcnt lgkmcnt(4)
	v_mfma_f32_32x32x16_bf16 v[48:63], v[140:143], v[120:123], v[48:63]
	v_exp_f32_e32 v66, v66
	v_exp_f32_e32 v67, v67
	v_add_f32_e32 v133, v133, v66
	v_add_f32_e32 v136, v136, v67
	v_mfma_f32_32x32x16_bf16 v[32:47], v[144:147], v[120:123], v[32:47]
	v_exp_f32_e32 v68, v68
	v_exp_f32_e32 v69, v69
	v_add_f32_e32 v133, v133, v68
	v_add_f32_e32 v136, v136, v69
	v_mfma_f32_32x32x16_bf16 v[16:31], v[148:151], v[120:123], v[16:31]
	v_exp_f32_e32 v70, v70
	v_exp_f32_e32 v71, v71
	v_add_f32_e32 v133, v133, v70
	v_add_f32_e32 v136, v136, v71
	v_mfma_f32_32x32x16_bf16 v[0:15], v[152:155], v[120:123], v[0:15]
	v_exp_f32_e32 v72, v72
	v_exp_f32_e32 v73, v73
	v_add_f32_e32 v133, v133, v72
	v_add_f32_e32 v136, v136, v73
	v_cvt_pk_bf16_f32 v112, v64, v65
	v_cvt_pk_bf16_f32 v113, v66, v67
	s_waitcnt lgkmcnt(0)
	v_mfma_f32_32x32x16_bf16 v[48:63], v[156:159], v[124:127], v[48:63]
	v_exp_f32_e32 v74, v74
	v_exp_f32_e32 v75, v75
	v_add_f32_e32 v133, v133, v74
	v_add_f32_e32 v136, v136, v75
	v_cvt_pk_bf16_f32 v114, v68, v69
	v_cvt_pk_bf16_f32 v115, v70, v71
	v_mfma_f32_32x32x16_bf16 v[32:47], v[160:163], v[124:127], v[32:47]
	v_exp_f32_e32 v76, v76
	v_exp_f32_e32 v77, v77
	v_add_f32_e32 v133, v133, v76
	v_add_f32_e32 v136, v136, v77
	v_mfma_f32_32x32x16_bf16 v[16:31], v[164:167], v[124:127], v[16:31]
	v_exp_f32_e32 v78, v78
	v_exp_f32_e32 v79, v79
	v_add_f32_e32 v133, v133, v78
	v_add_f32_e32 v136, v136, v79
	v_mfma_f32_32x32x16_bf16 v[0:15], v[168:171], v[124:127], v[0:15]
	v_cvt_pk_bf16_f32 v116, v72, v73
	v_cvt_pk_bf16_f32 v117, v74, v75
	v_cvt_pk_bf16_f32 v118, v76, v77
	v_cvt_pk_bf16_f32 v119, v78, v79
	s_cmp_eq_u32 s41, 0
	s_cbranch_scc1 .Lda_skipB_0
	s_nop 11
	v_mul_f32_e32 v0, v227, v0
	v_mul_f32_e32 v1, v227, v1
	v_mul_f32_e32 v2, v227, v2
	v_mul_f32_e32 v3, v227, v3
	v_mul_f32_e32 v4, v227, v4
	v_mul_f32_e32 v5, v227, v5
	v_mul_f32_e32 v6, v227, v6
	v_mul_f32_e32 v7, v227, v7
	v_mul_f32_e32 v8, v227, v8
	v_mul_f32_e32 v9, v227, v9
	v_mul_f32_e32 v10, v227, v10
	v_mul_f32_e32 v11, v227, v11
	v_mul_f32_e32 v12, v227, v12
	v_mul_f32_e32 v13, v227, v13
	v_mul_f32_e32 v14, v227, v14
	v_mul_f32_e32 v15, v227, v15
	v_mul_f32_e32 v16, v227, v16
	v_mul_f32_e32 v17, v227, v17
	v_mul_f32_e32 v18, v227, v18
	v_mul_f32_e32 v19, v227, v19
	v_mul_f32_e32 v20, v227, v20
	v_mul_f32_e32 v21, v227, v21
	v_mul_f32_e32 v22, v227, v22
	v_mul_f32_e32 v23, v227, v23
	v_mul_f32_e32 v24, v227, v24
	v_mul_f32_e32 v25, v227, v25
	v_mul_f32_e32 v26, v227, v26
	v_mul_f32_e32 v27, v227, v27
	v_mul_f32_e32 v28, v227, v28
	v_mul_f32_e32 v29, v227, v29
	v_mul_f32_e32 v30, v227, v30
	v_mul_f32_e32 v31, v227, v31
	v_mul_f32_e32 v32, v227, v32
	v_mul_f32_e32 v33, v227, v33
	v_mul_f32_e32 v34, v227, v34
	v_mul_f32_e32 v35, v227, v35
	v_mul_f32_e32 v36, v227, v36
	v_mul_f32_e32 v37, v227, v37
	v_mul_f32_e32 v38, v227, v38
	v_mul_f32_e32 v39, v227, v39
	v_mul_f32_e32 v40, v227, v40
	v_mul_f32_e32 v41, v227, v41
	v_mul_f32_e32 v42, v227, v42
	v_mul_f32_e32 v43, v227, v43
	v_mul_f32_e32 v44, v227, v44
	v_mul_f32_e32 v45, v227, v45
	v_mul_f32_e32 v46, v227, v46
	v_mul_f32_e32 v47, v227, v47
	v_mul_f32_e32 v48, v227, v48
	v_mul_f32_e32 v49, v227, v49
	v_mul_f32_e32 v50, v227, v50
	v_mul_f32_e32 v51, v227, v51
	v_mul_f32_e32 v52, v227, v52
	v_mul_f32_e32 v53, v227, v53
	v_mul_f32_e32 v54, v227, v54
	v_mul_f32_e32 v55, v227, v55
	v_mul_f32_e32 v56, v227, v56
	v_mul_f32_e32 v57, v227, v57
	v_mul_f32_e32 v58, v227, v58
	v_mul_f32_e32 v59, v227, v59
	v_mul_f32_e32 v60, v227, v60
	v_mul_f32_e32 v61, v227, v61
	v_mul_f32_e32 v62, v227, v62
	v_mul_f32_e32 v63, v227, v63
	s_mov_b32 s41, 0
; template <int MODE>
; __device__ __forceinline__ void attn_phase(LAS unsigned char* lds, const bf16* Qp, const bf16* Kp, const bf16* KPEp, const bf16* Vtp, bf16* CAT, float lam, int vcu, int G) {
;     ...
;             ATT1_ITER(pfB, pf, 0, false);
;             for (int i2 = 1; i2 < 127; i2 += 2) {
;                 ATT1_ITER(pf, pfB, i2, true);
;                 ATT1_ITER(pfB, pf, i2 + 1, true);
.Lda_skipB_0:
	s_waitcnt vmcnt(4) lgkmcnt(0)
	s_barrier
	ds_read_b128 v[140:143], v132 offset:32768
	ds_read_b128 v[144:147], v137 offset:32768
	ds_read_b128 v[148:151], v138 offset:32768
	ds_read_b128 v[152:155], v139 offset:32768
	ds_read_b128 v[156:159], v132 offset:40960
	ds_read_b128 v[160:163], v137 offset:40960
	ds_read_b128 v[164:167], v138 offset:40960
	ds_read_b128 v[168:171], v139 offset:40960
	ds_read_b128 v[184:187], v216 offset:16384
	ds_read_b128 v[188:191], v216 offset:20480
	ds_read_b128 v[192:195], v216 offset:24576
	ds_read_b128 v[196:199], v216 offset:28672
	v_exp_f32_e32 v80, v80
	v_exp_f32_e32 v81, v81
	v_add_f32_e32 v133, v133, v80
	v_add_f32_e32 v136, v136, v81
	v_exp_f32_e32 v82, v82
	v_exp_f32_e32 v83, v83
	v_add_f32_e32 v133, v133, v82
	v_add_f32_e32 v136, v136, v83
	s_waitcnt lgkmcnt(8)
	v_mfma_f32_32x32x16_bf16 v[64:79], v[140:143], v[108:111], v[236:251]
	v_exp_f32_e32 v84, v84
	v_exp_f32_e32 v85, v85
	v_add_f32_e32 v133, v133, v84
	v_add_f32_e32 v136, v136, v85
	ds_read_b128 v[200:203], v217 offset:16384
	v_mfma_f32_32x32x16_bf16 v[64:79], v[144:147], v[104:107], v[64:79]
	v_exp_f32_e32 v86, v86
	v_exp_f32_e32 v87, v87
	v_add_f32_e32 v133, v133, v86
	v_add_f32_e32 v136, v136, v87
	ds_read_b128 v[204:207], v217 offset:20480
	v_mfma_f32_32x32x16_bf16 v[64:79], v[148:151], v[100:103], v[64:79]
	v_exp_f32_e32 v88, v88
	v_exp_f32_e32 v89, v89
	v_add_f32_e32 v133, v133, v88
	v_add_f32_e32 v136, v136, v89
	v_cvt_pk_bf16_f32 v120, v80, v81
	v_cvt_pk_bf16_f32 v121, v82, v83
	ds_read_b128 v[208:211], v217 offset:24576
	v_mfma_f32_32x32x16_bf16 v[64:79], v[152:155], v[96:99], v[64:79]
	v_exp_f32_e32 v90, v90
	v_exp_f32_e32 v91, v91
	v_add_f32_e32 v133, v133, v90
	v_add_f32_e32 v136, v136, v91
	v_cvt_pk_bf16_f32 v122, v84, v85
	v_cvt_pk_bf16_f32 v123, v86, v87
	ds_read_b128 v[212:215], v217 offset:28672
	s_waitcnt lgkmcnt(4)
	v_mfma_f32_32x32x16_bf16 v[48:63], v[184:187], v[112:115], v[48:63]
	v_exp_f32_e32 v92, v92
	v_exp_f32_e32 v93, v93
	v_add_f32_e32 v133, v133, v92
	v_add_f32_e32 v136, v136, v93
	ds_read_b128 v[140:143], v218 offset:16384
	v_mfma_f32_32x32x16_bf16 v[32:47], v[188:191], v[112:115], v[32:47]
	v_exp_f32_e32 v94, v94
	v_exp_f32_e32 v95, v95
	v_add_f32_e32 v133, v133, v94
	v_add_f32_e32 v136, v136, v95
	ds_read_b128 v[144:147], v218 offset:20480
	v_mfma_f32_32x32x16_bf16 v[16:31], v[192:195], v[112:115], v[16:31]
	v_cvt_pk_bf16_f32 v124, v88, v89
	v_cvt_pk_bf16_f32 v125, v90, v91
	ds_read_b128 v[148:151], v218 offset:24576
	v_mfma_f32_32x32x16_bf16 v[0:15], v[196:199], v[112:115], v[0:15]
	v_cvt_pk_bf16_f32 v126, v92, v93
	v_cvt_pk_bf16_f32 v127, v94, v95
	ds_read_b128 v[152:155], v218 offset:28672
	v_max3_f32 v224, v64, v65, v66
	v_max3_f32 v225, v67, v68, v69
	v_max3_f32 v224, v224, v70, v71
	v_mfma_f32_32x32x16_bf16 v[80:95], v[156:159], v[108:111], v[236:251]
	s_add_i32 m0, s58, 0x4000
	v_max3_f32 v225, v225, v72, v73
	global_load_lds_dwordx4 v128, s[8:9]
	v_mfma_f32_32x32x16_bf16 v[80:95], v[160:163], v[104:107], v[80:95]
	s_add_i32 m0, s58, 0x6000
	v_max3_f32 v224, v224, v74, v75
	global_load_lds_dwordx4 v129, s[8:9]
	ds_read_b128 v[156:159], v219 offset:16384
	v_mfma_f32_32x32x16_bf16 v[80:95], v[164:167], v[100:103], v[80:95]
	s_add_i32 m0, s65, 0x0
	v_max3_f32 v225, v225, v76, v77
	global_load_lds_dwordx4 v130, s[10:11]
	ds_read_b128 v[160:163], v219 offset:20480
	v_mfma_f32_32x32x16_bf16 v[80:95], v[168:171], v[96:99], v[80:95]
	s_add_i32 m0, s65, 0x2000
	v_max3_f32 v224, v224, v78, v79
	global_load_lds_dwordx4 v131, s[10:11]
	ds_read_b128 v[164:167], v219 offset:24576
	s_waitcnt lgkmcnt(7)
	v_mfma_f32_32x32x16_bf16 v[48:63], v[200:203], v[116:119], v[48:63]
	ds_read_b128 v[168:171], v219 offset:28672
	s_add_u32 s8, s8, 0x4000
	s_addc_u32 s9, s9, 0
	s_add_u32 s10, s10, 0x80
	s_addc_u32 s11, s11, 0
	v_mfma_f32_32x32x16_bf16 v[32:47], v[204:207], v[116:119], v[32:47]
	s_nop 1
	v_max3_f32 v224, v224, v80, v81
	v_max3_f32 v225, v225, v82, v83
	v_max3_f32 v224, v224, v84, v85
	v_max3_f32 v225, v225, v86, v87
	v_mfma_f32_32x32x16_bf16 v[16:31], v[208:211], v[116:119], v[16:31]
	v_max3_f32 v224, v224, v88, v89
	v_max3_f32 v225, v225, v90, v91
	v_max3_f32 v224, v224, v92, v93
	v_max3_f32 v225, v225, v94, v95
	v_max_f32_e32 v224, v224, v225
	v_mov_b32_e32 v225, v224
	s_nop 1
	v_permlane32_swap_b32_e32 v224, v225
	v_max_f32_e32 v224, v224, v225
	v_cmp_lt_f32_e32 vcc, 0x41000000, v224
	v_mfma_f32_32x32x16_bf16 v[0:15], v[212:215], v[116:119], v[0:15]
	s_nop 1
	s_cmp_lg_u64 vcc, 0
	s_cbranch_scc1 .Lda_rareA_1

; template <int MODE>
; __device__ __forceinline__ void attn_phase(LAS unsigned char* lds, const bf16* Qp, const bf16* Kp, const bf16* KPEp, const bf16* Vtp, bf16* CAT, float lam, int vcu, int G) {
;     ...
;             ATT1_ITER(pfB, pf, 0, false);
;             for (int i2 = 1; i2 < 127; i2 += 2) {
;                 ATT1_ITER(pf, pfB, i2, true);
;                 ATT1_ITER(pfB, pf, i2 + 1, true);
.Lda_skipB_1:
	s_waitcnt vmcnt(4) lgkmcnt(0)
	s_barrier
	ds_read_b128 v[140:143], v132
	ds_read_b128 v[144:147], v137
	ds_read_b128 v[148:151], v138
	ds_read_b128 v[152:155], v139
	ds_read_b128 v[156:159], v132 offset:8192
	ds_read_b128 v[160:163], v137 offset:8192
	ds_read_b128 v[164:167], v138 offset:8192
	ds_read_b128 v[168:171], v139 offset:8192
	ds_read_b128 v[184:187], v216 offset:32768
	ds_read_b128 v[188:191], v216 offset:36864
	ds_read_b128 v[192:195], v216 offset:40960
	ds_read_b128 v[196:199], v216 offset:45056
	v_exp_f32_e32 v80, v80
	v_exp_f32_e32 v81, v81
	v_add_f32_e32 v133, v133, v80
	v_add_f32_e32 v136, v136, v81
	v_exp_f32_e32 v82, v82
	v_exp_f32_e32 v83, v83
	v_add_f32_e32 v133, v133, v82
	v_add_f32_e32 v136, v136, v83
	s_waitcnt lgkmcnt(8)
	v_mfma_f32_32x32x16_bf16 v[64:79], v[140:143], v[108:111], v[236:251]
	v_exp_f32_e32 v84, v84
	v_exp_f32_e32 v85, v85
	v_add_f32_e32 v133, v133, v84
	v_add_f32_e32 v136, v136, v85
	ds_read_b128 v[200:203], v217 offset:32768
	v_mfma_f32_32x32x16_bf16 v[64:79], v[144:147], v[104:107], v[64:79]
	v_exp_f32_e32 v86, v86
	v_exp_f32_e32 v87, v87
	v_add_f32_e32 v133, v133, v86
	v_add_f32_e32 v136, v136, v87
	ds_read_b128 v[204:207], v217 offset:36864
	v_mfma_f32_32x32x16_bf16 v[64:79], v[148:151], v[100:103], v[64:79]
	v_exp_f32_e32 v88, v88
	v_exp_f32_e32 v89, v89
	v_add_f32_e32 v133, v133, v88
	v_add_f32_e32 v136, v136, v89
	v_cvt_pk_bf16_f32 v120, v80, v81
	v_cvt_pk_bf16_f32 v121, v82, v83
	ds_read_b128 v[208:211], v217 offset:40960
	v_mfma_f32_32x32x16_bf16 v[64:79], v[152:155], v[96:99], v[64:79]
	v_exp_f32_e32 v90, v90
	v_exp_f32_e32 v91, v91
	v_add_f32_e32 v133, v133, v90
	v_add_f32_e32 v136, v136, v91
	v_cvt_pk_bf16_f32 v122, v84, v85
	v_cvt_pk_bf16_f32 v123, v86, v87
	ds_read_b128 v[212:215], v217 offset:45056
	s_waitcnt lgkmcnt(4)
	v_mfma_f32_32x32x16_bf16 v[48:63], v[184:187], v[112:115], v[48:63]
	v_exp_f32_e32 v92, v92
	v_exp_f32_e32 v93, v93
	v_add_f32_e32 v133, v133, v92
	v_add_f32_e32 v136, v136, v93
	ds_read_b128 v[140:143], v218 offset:32768
	v_mfma_f32_32x32x16_bf16 v[32:47], v[188:191], v[112:115], v[32:47]
	v_exp_f32_e32 v94, v94
	v_exp_f32_e32 v95, v95
	v_add_f32_e32 v133, v133, v94
	v_add_f32_e32 v136, v136, v95
	ds_read_b128 v[144:147], v218 offset:36864
	v_mfma_f32_32x32x16_bf16 v[16:31], v[192:195], v[112:115], v[16:31]
	v_cvt_pk_bf16_f32 v124, v88, v89
	v_cvt_pk_bf16_f32 v125, v90, v91
	ds_read_b128 v[148:151], v218 offset:40960
	v_mfma_f32_32x32x16_bf16 v[0:15], v[196:199], v[112:115], v[0:15]
	v_cvt_pk_bf16_f32 v126, v92, v93
	v_cvt_pk_bf16_f32 v127, v94, v95
	ds_read_b128 v[152:155], v218 offset:45056
	v_max3_f32 v224, v64, v65, v66
	v_max3_f32 v225, v67, v68, v69
	v_max3_f32 v224, v224, v70, v71
	v_mfma_f32_32x32x16_bf16 v[80:95], v[156:159], v[108:111], v[236:251]
	s_add_i32 m0, s58, 0x8000
	v_max3_f32 v225, v225, v72, v73
	global_load_lds_dwordx4 v128, s[8:9]
	v_mfma_f32_32x32x16_bf16 v[80:95], v[160:163], v[104:107], v[80:95]
	s_add_i32 m0, s58, 0xa000
	v_max3_f32 v224, v224, v74, v75
	global_load_lds_dwordx4 v129, s[8:9]
	ds_read_b128 v[156:159], v219 offset:32768
	v_mfma_f32_32x32x16_bf16 v[80:95], v[164:167], v[100:103], v[80:95]
	s_add_i32 m0, s65, 0x4000
	v_max3_f32 v225, v225, v76, v77
	global_load_lds_dwordx4 v130, s[10:11]
	ds_read_b128 v[160:163], v219 offset:36864
	v_mfma_f32_32x32x16_bf16 v[80:95], v[168:171], v[96:99], v[80:95]
	s_add_i32 m0, s65, 0x6000
	v_max3_f32 v224, v224, v78, v79
	global_load_lds_dwordx4 v131, s[10:11]
	ds_read_b128 v[164:167], v219 offset:40960
	s_waitcnt lgkmcnt(7)
	v_mfma_f32_32x32x16_bf16 v[48:63], v[200:203], v[116:119], v[48:63]
	ds_read_b128 v[168:171], v219 offset:45056
	s_add_u32 s8, s8, 0x4000
	s_addc_u32 s9, s9, 0
	s_add_u32 s10, s10, 0x80
	s_addc_u32 s11, s11, 0
	v_mfma_f32_32x32x16_bf16 v[32:47], v[204:207], v[116:119], v[32:47]
	s_nop 1
	v_max3_f32 v224, v224, v80, v81
	v_max3_f32 v225, v225, v82, v83
	v_max3_f32 v224, v224, v84, v85
	v_max3_f32 v225, v225, v86, v87
	v_mfma_f32_32x32x16_bf16 v[16:31], v[208:211], v[116:119], v[16:31]
	v_max3_f32 v224, v224, v88, v89
	v_max3_f32 v225, v225, v90, v91
	v_max3_f32 v224, v224, v92, v93
	v_max3_f32 v225, v225, v94, v95
	v_max_f32_e32 v224, v224, v225
	v_mov_b32_e32 v225, v224
	s_nop 1
	v_permlane32_swap_b32_e32 v224, v225
	v_max_f32_e32 v224, v224, v225
	v_cmp_lt_f32_e32 vcc, 0x41000000, v224
	v_mfma_f32_32x32x16_bf16 v[0:15], v[212:215], v[116:119], v[0:15]
	s_nop 1
	s_cmp_lg_u64 vcc, 0
	s_cbranch_scc1 .Lda_rareA_2

; template <int MODE>
; __device__ __forceinline__ void attn_phase(LAS unsigned char* lds, const bf16* Qp, const bf16* Kp, const bf16* KPEp, const bf16* Vtp, bf16* CAT, float lam, int vcu, int G) {
;     ...
;             for (int i2 = 1; i2 < 127; i2 += 2) {
;                 ATT1_ITER(pf, pfB, i2, true);
;                 ATT1_ITER(pfB, pf, i2 + 1, true);
;             }
;             ATT1_ITER(pf, pfB, 127, true);
.Lda_skipB_2:
	s_add_i32 s66, s66, 1
	s_cmpk_lt_u32 s66, 42
	s_waitcnt vmcnt(4) lgkmcnt(0)
	s_barrier
	s_cbranch_scc1 .Lda_loop
	ds_read_b128 v[140:143], v132 offset:16384
	ds_read_b128 v[144:147], v137 offset:16384
	ds_read_b128 v[148:151], v138 offset:16384
	ds_read_b128 v[152:155], v139 offset:16384
	ds_read_b128 v[156:159], v132 offset:24576
	ds_read_b128 v[160:163], v137 offset:24576
	ds_read_b128 v[164:167], v138 offset:24576
	ds_read_b128 v[168:171], v139 offset:24576
	ds_read_b128 v[184:187], v216
	ds_read_b128 v[188:191], v216 offset:4096
	ds_read_b128 v[192:195], v216 offset:8192
	ds_read_b128 v[196:199], v216 offset:12288
	v_exp_f32_e32 v80, v80
	v_exp_f32_e32 v81, v81
	v_add_f32_e32 v133, v133, v80
	v_add_f32_e32 v136, v136, v81
	v_exp_f32_e32 v82, v82
	v_exp_f32_e32 v83, v83
	v_add_f32_e32 v133, v133, v82
	v_add_f32_e32 v136, v136, v83
	s_waitcnt lgkmcnt(8)
	v_mfma_f32_32x32x16_bf16 v[64:79], v[140:143], v[108:111], v[236:251]
	v_exp_f32_e32 v84, v84
	v_exp_f32_e32 v85, v85
	v_add_f32_e32 v133, v133, v84
	v_add_f32_e32 v136, v136, v85
	ds_read_b128 v[200:203], v217
	v_mfma_f32_32x32x16_bf16 v[64:79], v[144:147], v[104:107], v[64:79]
	v_exp_f32_e32 v86, v86
	v_exp_f32_e32 v87, v87
	v_add_f32_e32 v133, v133, v86
	v_add_f32_e32 v136, v136, v87
	ds_read_b128 v[204:207], v217 offset:4096
	v_mfma_f32_32x32x16_bf16 v[64:79], v[148:151], v[100:103], v[64:79]
	v_exp_f32_e32 v88, v88
	v_exp_f32_e32 v89, v89
	v_add_f32_e32 v133, v133, v88
	v_add_f32_e32 v136, v136, v89
	v_cvt_pk_bf16_f32 v120, v80, v81
	v_cvt_pk_bf16_f32 v121, v82, v83
	ds_read_b128 v[208:211], v217 offset:8192
	v_mfma_f32_32x32x16_bf16 v[64:79], v[152:155], v[96:99], v[64:79]
	v_exp_f32_e32 v90, v90
	v_exp_f32_e32 v91, v91
	v_add_f32_e32 v133, v133, v90
	v_add_f32_e32 v136, v136, v91
	v_cvt_pk_bf16_f32 v122, v84, v85
	v_cvt_pk_bf16_f32 v123, v86, v87
	ds_read_b128 v[212:215], v217 offset:12288
	s_waitcnt lgkmcnt(4)
	v_mfma_f32_32x32x16_bf16 v[48:63], v[184:187], v[112:115], v[48:63]
	v_exp_f32_e32 v92, v92
	v_exp_f32_e32 v93, v93
	v_add_f32_e32 v133, v133, v92
	v_add_f32_e32 v136, v136, v93
	ds_read_b128 v[140:143], v218
	v_mfma_f32_32x32x16_bf16 v[32:47], v[188:191], v[112:115], v[32:47]
	v_exp_f32_e32 v94, v94
	v_exp_f32_e32 v95, v95
	v_add_f32_e32 v133, v133, v94
	v_add_f32_e32 v136, v136, v95
	ds_read_b128 v[144:147], v218 offset:4096
	v_mfma_f32_32x32x16_bf16 v[16:31], v[192:195], v[112:115], v[16:31]
	v_cvt_pk_bf16_f32 v124, v88, v89
	v_cvt_pk_bf16_f32 v125, v90, v91
	ds_read_b128 v[148:151], v218 offset:8192
	v_mfma_f32_32x32x16_bf16 v[0:15], v[196:199], v[112:115], v[0:15]
	v_cvt_pk_bf16_f32 v126, v92, v93
	v_cvt_pk_bf16_f32 v127, v94, v95
	ds_read_b128 v[152:155], v218 offset:12288
	v_max3_f32 v224, v64, v65, v66
	v_max3_f32 v225, v67, v68, v69
	v_max3_f32 v224, v224, v70, v71
	v_mfma_f32_32x32x16_bf16 v[80:95], v[156:159], v[108:111], v[236:251]
	s_add_i32 m0, s58, 0x0
	v_max3_f32 v225, v225, v72, v73
	global_load_lds_dwordx4 v128, s[8:9]
	v_mfma_f32_32x32x16_bf16 v[80:95], v[160:163], v[104:107], v[80:95]
	s_add_i32 m0, s58, 0x2000
	v_max3_f32 v224, v224, v74, v75
	global_load_lds_dwordx4 v129, s[8:9]
	ds_read_b128 v[156:159], v219
	v_mfma_f32_32x32x16_bf16 v[80:95], v[164:167], v[100:103], v[80:95]
	s_add_i32 m0, s65, 0x8000
	v_max3_f32 v225, v225, v76, v77
	global_load_lds_dwordx4 v130, s[10:11]
	ds_read_b128 v[160:163], v219 offset:4096
	v_mfma_f32_32x32x16_bf16 v[80:95], v[168:171], v[96:99], v[80:95]
	s_add_i32 m0, s65, 0xa000
	v_max3_f32 v224, v224, v78, v79
	global_load_lds_dwordx4 v131, s[10:11]
	ds_read_b128 v[164:167], v219 offset:8192
	s_waitcnt lgkmcnt(7)
	v_mfma_f32_32x32x16_bf16 v[48:63], v[200:203], v[116:119], v[48:63]
	ds_read_b128 v[168:171], v219 offset:12288
	s_add_u32 s8, s8, 0x4000
	s_addc_u32 s9, s9, 0
	s_add_u32 s10, s10, 0x80
	s_addc_u32 s11, s11, 0
	v_mfma_f32_32x32x16_bf16 v[32:47], v[204:207], v[116:119], v[32:47]
	s_nop 1
	v_max3_f32 v224, v224, v80, v81
	v_max3_f32 v225, v225, v82, v83
	v_max3_f32 v224, v224, v84, v85
	v_max3_f32 v225, v225, v86, v87
	v_mfma_f32_32x32x16_bf16 v[16:31], v[208:211], v[116:119], v[16:31]
	v_max3_f32 v224, v224, v88, v89
	v_max3_f32 v225, v225, v90, v91
	v_max3_f32 v224, v224, v92, v93
	v_max3_f32 v225, v225, v94, v95
	v_max_f32_e32 v224, v224, v225
	v_mov_b32_e32 v225, v224
	s_nop 1
	v_permlane32_swap_b32_e32 v224, v225
	v_max_f32_e32 v224, v224, v225
	v_cmp_lt_f32_e32 vcc, 0x41000000, v224
	v_mfma_f32_32x32x16_bf16 v[0:15], v[212:215], v[116:119], v[0:15]
	s_nop 1
	s_cmp_lg_u64 vcc, 0
	s_cbranch_scc1 .Lda_rareA_3

; __device__ __forceinline__ float xor32_add(float v) { auto rr = __builtin_amdgcn_permlane32_swap(__float_as_uint(v), __float_as_uint(v), false, false); return __uint_as_float(rr[0]) + __uint_as_float(rr[1]); }
; #define ATT_DMA_K(slotoff) do { _Pragma("unroll") for (int n = 0; n < NKI; ++n) glds16(kp[n], (unsigned)__builtin_amdgcn_readfirstlane(kdma + (slotoff) + n * 8192)); } while (0)
; #define ATT_DMA_V(slotoff) do { _Pragma("unroll") for (int n = 0; n < 2; ++n) glds16(vp[n], (unsigned)__builtin_amdgcn_readfirstlane(vdma + (slotoff) + n * 8192)); } while (0)
; #define ATT_ADV_K() do { _Pragma("unroll") for (int n = 0; n < NKI; ++n) kp[n] += kadv[n]; } while (0)
; #define ATT_ADV_V() do { _Pragma("unroll") for (int n = 0; n < 2; ++n) vp[n] += 64; } while (0)
; template <int MODE>
; __device__ __forceinline__ void attn_phase(LAS unsigned char* lds, const bf16* Qp, const bf16* Kp, const bf16* KPEp, const bf16* Vtp, bf16* CAT, float lam, int vcu, int G) {
;     ...
;             ATT1_ITER(pf, pfB, 127, true);
;     ...
; #pragma unroll
;             for (int q = 0; q < 4; ++q) pf[q] = pfB[q];
;         } else {
;         for (int i = 0; i < 128; ++i) {
;             att_qk<MODE>(S0, S1, lds + kr, ka, qf);
;             const float rm = att_rowmax(S0, S1);
;             if (i == 0) mhat = rm;
;             else if (__any(rm - mhat > THR)) { const float dl = fmaxf(rm - mhat, 0.f), f = __builtin_amdgcn_exp2f(-dl); lrun *= f; mhat += dl; fpend = f; havepend = true; }
;             if (i > 0) att_pv(o, vring + vr, va, pf);
;             att_exp(S0, S1, mhat, lrun, pf);
;             ATT_RESC_O();
;             ATT_DMA_K(kw); ATT_DMA_V(vw);
;             if (i + 2 < 127) ATT_ADV_K();
;             if (i + 1 < 127) ATT_ADV_V();
;             kr = (kr == 2 * KB) ? 0 : kr + KB; kw = (kw == 2 * KB) ? 0 : kw + KB;
;             vr = (vr == 2 * VB) ? 0 : vr + VB; vw = (vw == 2 * VB) ? 0 : vw + VB;
;             asm volatile("s_waitcnt vmcnt(5) lgkmcnt(0)\n\ts_barrier" ::: "memory");
;         }
;         }
;         att_pv(o, vring + vr, va, pf);
;         asm volatile("s_waitcnt vmcnt(0) lgkmcnt(0)\n\ts_barrier" ::: "memory");
;     ...
;         lrun = xor32_add(lrun);
;         const float inv = 1.0f / lrun;
.Lda_skipB_3:
	s_waitcnt vmcnt(4) lgkmcnt(0)
	s_barrier
	ds_read_b128 v[140:143], v216 offset:16384
	ds_read_b128 v[144:147], v216 offset:20480
	ds_read_b128 v[148:151], v216 offset:24576
	ds_read_b128 v[152:155], v216 offset:28672
	ds_read_b128 v[156:159], v217 offset:16384
	ds_read_b128 v[160:163], v217 offset:20480
	ds_read_b128 v[164:167], v217 offset:24576
	ds_read_b128 v[168:171], v217 offset:28672
	ds_read_b128 v[184:187], v218 offset:16384
	ds_read_b128 v[188:191], v218 offset:20480
	ds_read_b128 v[192:195], v218 offset:24576
	ds_read_b128 v[196:199], v218 offset:28672
	ds_read_b128 v[200:203], v219 offset:16384
	ds_read_b128 v[204:207], v219 offset:20480
	ds_read_b128 v[208:211], v219 offset:24576
	v_exp_f32_e32 v80, v80
	v_exp_f32_e32 v81, v81
	v_add_f32_e32 v133, v133, v80
	v_add_f32_e32 v136, v136, v81
	v_exp_f32_e32 v82, v82
	v_exp_f32_e32 v83, v83
	v_add_f32_e32 v133, v133, v82
	v_add_f32_e32 v136, v136, v83
	v_exp_f32_e32 v84, v84
	v_exp_f32_e32 v85, v85
	v_add_f32_e32 v133, v133, v84
	v_add_f32_e32 v136, v136, v85
	v_exp_f32_e32 v86, v86
	v_exp_f32_e32 v87, v87
	v_add_f32_e32 v133, v133, v86
	v_add_f32_e32 v136, v136, v87
	v_exp_f32_e32 v88, v88
	v_exp_f32_e32 v89, v89
	v_add_f32_e32 v133, v133, v88
	v_add_f32_e32 v136, v136, v89
	v_exp_f32_e32 v90, v90
	v_exp_f32_e32 v91, v91
	v_add_f32_e32 v133, v133, v90
	v_add_f32_e32 v136, v136, v91
	v_exp_f32_e32 v92, v92
	v_exp_f32_e32 v93, v93
	v_add_f32_e32 v133, v133, v92
	v_add_f32_e32 v136, v136, v93
	v_exp_f32_e32 v94, v94
	v_exp_f32_e32 v95, v95
	v_add_f32_e32 v133, v133, v94
	v_add_f32_e32 v136, v136, v95
	v_cvt_pk_bf16_f32 v120, v80, v81
	v_cvt_pk_bf16_f32 v121, v82, v83
	v_cvt_pk_bf16_f32 v122, v84, v85
	v_cvt_pk_bf16_f32 v123, v86, v87
	v_cvt_pk_bf16_f32 v124, v88, v89
	v_cvt_pk_bf16_f32 v125, v90, v91
	v_cvt_pk_bf16_f32 v126, v92, v93
	v_cvt_pk_bf16_f32 v127, v94, v95
	s_nop 1
	s_waitcnt lgkmcnt(14)
	v_mfma_f32_32x32x16_bf16 v[48:63], v[140:143], v[112:115], v[48:63]
	ds_read_b128 v[212:215], v219 offset:28672
	s_waitcnt lgkmcnt(14)
	v_mfma_f32_32x32x16_bf16 v[32:47], v[144:147], v[112:115], v[32:47]
	s_waitcnt lgkmcnt(13)
	v_mfma_f32_32x32x16_bf16 v[16:31], v[148:151], v[112:115], v[16:31]
	s_waitcnt lgkmcnt(12)
	v_mfma_f32_32x32x16_bf16 v[0:15], v[152:155], v[112:115], v[0:15]
	s_waitcnt lgkmcnt(11)
	v_mfma_f32_32x32x16_bf16 v[48:63], v[156:159], v[116:119], v[48:63]
	s_waitcnt lgkmcnt(10)
	v_mfma_f32_32x32x16_bf16 v[32:47], v[160:163], v[116:119], v[32:47]
	s_waitcnt lgkmcnt(9)
	v_mfma_f32_32x32x16_bf16 v[16:31], v[164:167], v[116:119], v[16:31]
	s_waitcnt lgkmcnt(8)
	v_mfma_f32_32x32x16_bf16 v[0:15], v[168:171], v[116:119], v[0:15]
	s_waitcnt lgkmcnt(7)
	v_mfma_f32_32x32x16_bf16 v[48:63], v[184:187], v[120:123], v[48:63]
	s_waitcnt lgkmcnt(6)
	v_mfma_f32_32x32x16_bf16 v[32:47], v[188:191], v[120:123], v[32:47]
	s_waitcnt lgkmcnt(5)
	v_mfma_f32_32x32x16_bf16 v[16:31], v[192:195], v[120:123], v[16:31]
	s_waitcnt lgkmcnt(4)
	v_mfma_f32_32x32x16_bf16 v[0:15], v[196:199], v[120:123], v[0:15]
	s_waitcnt lgkmcnt(3)
	v_mfma_f32_32x32x16_bf16 v[48:63], v[200:203], v[124:127], v[48:63]
	s_waitcnt lgkmcnt(2)
	v_mfma_f32_32x32x16_bf16 v[32:47], v[204:207], v[124:127], v[32:47]
	s_waitcnt lgkmcnt(1)
	v_mfma_f32_32x32x16_bf16 v[16:31], v[208:211], v[124:127], v[16:31]
	s_waitcnt lgkmcnt(0)
	v_mfma_f32_32x32x16_bf16 v[0:15], v[212:215], v[124:127], v[0:15]
	s_waitcnt vmcnt(0) lgkmcnt(0)
	s_barrier
	v_add_f32_e32 v80, v133, v136
	s_mov_b32 m0, s42
	s_lshl_b32 s3, s19, 14
	s_cmp_lg_u32 s18, 1
	s_branch .Lda_epi
.Lda_rareA_0:
	v_max_f32_e32 v230, 0, v224
	v_exp_f32_e64 v227, -v230
	s_mov_b32 s41, 1
	v_sub_f32_e32 v236, v236, v230
	v_sub_f32_e32 v237, v237, v230
	v_sub_f32_e32 v238, v238, v230
	v_sub_f32_e32 v239, v239, v230
	v_sub_f32_e32 v240, v240, v230
	v_sub_f32_e32 v241, v241, v230
	v_sub_f32_e32 v242, v242, v230
	v_sub_f32_e32 v243, v243, v230
	v_sub_f32_e32 v244, v244, v230
	v_sub_f32_e32 v245, v245, v230
	v_sub_f32_e32 v246, v246, v230
	v_sub_f32_e32 v247, v247, v230
	v_sub_f32_e32 v248, v248, v230
	v_sub_f32_e32 v249, v249, v230
	v_sub_f32_e32 v250, v250, v230
	v_sub_f32_e32 v251, v251, v230
	v_sub_f32_e32 v64, v64, v230
	v_sub_f32_e32 v65, v65, v230
	v_sub_f32_e32 v66, v66, v230
	v_sub_f32_e32 v67, v67, v230
	v_sub_f32_e32 v68, v68, v230
	v_sub_f32_e32 v69, v69, v230
	v_sub_f32_e32 v70, v70, v230
	v_sub_f32_e32 v71, v71, v230
	v_sub_f32_e32 v72, v72, v230
	v_sub_f32_e32 v73, v73, v230
	v_sub_f32_e32 v74, v74, v230
	v_sub_f32_e32 v75, v75, v230
	v_sub_f32_e32 v76, v76, v230
	v_sub_f32_e32 v77, v77, v230
	v_sub_f32_e32 v78, v78, v230
	v_sub_f32_e32 v79, v79, v230
	v_sub_f32_e32 v80, v80, v230
	v_sub_f32_e32 v81, v81, v230
	v_sub_f32_e32 v82, v82, v230
	v_sub_f32_e32 v83, v83, v230
	v_sub_f32_e32 v84, v84, v230
	v_sub_f32_e32 v85, v85, v230
	v_sub_f32_e32 v86, v86, v230
	v_sub_f32_e32 v87, v87, v230
	v_sub_f32_e32 v88, v88, v230
	v_sub_f32_e32 v89, v89, v230
	v_sub_f32_e32 v90, v90, v230
	v_sub_f32_e32 v91, v91, v230
	v_sub_f32_e32 v92, v92, v230
	v_sub_f32_e32 v93, v93, v230
	v_sub_f32_e32 v94, v94, v230
	v_sub_f32_e32 v95, v95, v230
	v_mul_f32_e32 v133, v133, v227
	v_mul_f32_e32 v136, v136, v227
	s_branch .Lda_backA_0
.Lda_rareA_1:
	v_max_f32_e32 v230, 0, v224
	v_exp_f32_e64 v227, -v230
	s_mov_b32 s41, 1
	v_sub_f32_e32 v236, v236, v230
	v_sub_f32_e32 v237, v237, v230
	v_sub_f32_e32 v238, v238, v230
	v_sub_f32_e32 v239, v239, v230
	v_sub_f32_e32 v240, v240, v230
	v_sub_f32_e32 v241, v241, v230
	v_sub_f32_e32 v242, v242, v230
	v_sub_f32_e32 v243, v243, v230
	v_sub_f32_e32 v244, v244, v230
	v_sub_f32_e32 v245, v245, v230
	v_sub_f32_e32 v246, v246, v230
	v_sub_f32_e32 v247, v247, v230
	v_sub_f32_e32 v248, v248, v230
	v_sub_f32_e32 v249, v249, v230
	v_sub_f32_e32 v250, v250, v230
	v_sub_f32_e32 v251, v251, v230
	v_sub_f32_e32 v64, v64, v230
	v_sub_f32_e32 v65, v65, v230
	v_sub_f32_e32 v66, v66, v230
	v_sub_f32_e32 v67, v67, v230
	v_sub_f32_e32 v68, v68, v230
	v_sub_f32_e32 v69, v69, v230
	v_sub_f32_e32 v70, v70, v230
	v_sub_f32_e32 v71, v71, v230
	v_sub_f32_e32 v72, v72, v230
	v_sub_f32_e32 v73, v73, v230
	v_sub_f32_e32 v74, v74, v230
	v_sub_f32_e32 v75, v75, v230
	v_sub_f32_e32 v76, v76, v230
	v_sub_f32_e32 v77, v77, v230
	v_sub_f32_e32 v78, v78, v230
	v_sub_f32_e32 v79, v79, v230
	v_sub_f32_e32 v80, v80, v230
	v_sub_f32_e32 v81, v81, v230
	v_sub_f32_e32 v82, v82, v230
	v_sub_f32_e32 v83, v83, v230
	v_sub_f32_e32 v84, v84, v230
	v_sub_f32_e32 v85, v85, v230
	v_sub_f32_e32 v86, v86, v230
	v_sub_f32_e32 v87, v87, v230
	v_sub_f32_e32 v88, v88, v230
	v_sub_f32_e32 v89, v89, v230
	v_sub_f32_e32 v90, v90, v230
	v_sub_f32_e32 v91, v91, v230
	v_sub_f32_e32 v92, v92, v230
	v_sub_f32_e32 v93, v93, v230
	v_sub_f32_e32 v94, v94, v230
	v_sub_f32_e32 v95, v95, v230
	v_mul_f32_e32 v133, v133, v227
	v_mul_f32_e32 v136, v136, v227
	s_branch .Lda_backA_1
.Lda_rareA_2:
	v_max_f32_e32 v230, 0, v224
	v_exp_f32_e64 v227, -v230
	s_mov_b32 s41, 1
	v_sub_f32_e32 v236, v236, v230
	v_sub_f32_e32 v237, v237, v230
	v_sub_f32_e32 v238, v238, v230
	v_sub_f32_e32 v239, v239, v230
	v_sub_f32_e32 v240, v240, v230
	v_sub_f32_e32 v241, v241, v230
	v_sub_f32_e32 v242, v242, v230
	v_sub_f32_e32 v243, v243, v230
	v_sub_f32_e32 v244, v244, v230
	v_sub_f32_e32 v245, v245, v230
	v_sub_f32_e32 v246, v246, v230
	v_sub_f32_e32 v247, v247, v230
	v_sub_f32_e32 v248, v248, v230
	v_sub_f32_e32 v249, v249, v230
	v_sub_f32_e32 v250, v250, v230
	v_sub_f32_e32 v251, v251, v230
	v_sub_f32_e32 v64, v64, v230
	v_sub_f32_e32 v65, v65, v230
	v_sub_f32_e32 v66, v66, v230
	v_sub_f32_e32 v67, v67, v230
	v_sub_f32_e32 v68, v68, v230
	v_sub_f32_e32 v69, v69, v230
	v_sub_f32_e32 v70, v70, v230
	v_sub_f32_e32 v71, v71, v230
	v_sub_f32_e32 v72, v72, v230
	v_sub_f32_e32 v73, v73, v230
	v_sub_f32_e32 v74, v74, v230
	v_sub_f32_e32 v75, v75, v230
	v_sub_f32_e32 v76, v76, v230
	v_sub_f32_e32 v77, v77, v230
	v_sub_f32_e32 v78, v78, v230
	v_sub_f32_e32 v79, v79, v230
	v_sub_f32_e32 v80, v80, v230
	v_sub_f32_e32 v81, v81, v230
	v_sub_f32_e32 v82, v82, v230
	v_sub_f32_e32 v83, v83, v230
	v_sub_f32_e32 v84, v84, v230
	v_sub_f32_e32 v85, v85, v230
	v_sub_f32_e32 v86, v86, v230
	v_sub_f32_e32 v87, v87, v230
	v_sub_f32_e32 v88, v88, v230
	v_sub_f32_e32 v89, v89, v230
	v_sub_f32_e32 v90, v90, v230
	v_sub_f32_e32 v91, v91, v230
	v_sub_f32_e32 v92, v92, v230
	v_sub_f32_e32 v93, v93, v230
	v_sub_f32_e32 v94, v94, v230
	v_sub_f32_e32 v95, v95, v230
	v_mul_f32_e32 v133, v133, v227
	v_mul_f32_e32 v136, v136, v227
	s_branch .Lda_backA_2
.Lda_rareA_3:
	v_max_f32_e32 v230, 0, v224
	v_exp_f32_e64 v227, -v230
	s_mov_b32 s41, 1
	v_sub_f32_e32 v236, v236, v230
	v_sub_f32_e32 v237, v237, v230
	v_sub_f32_e32 v238, v238, v230
	v_sub_f32_e32 v239, v239, v230
	v_sub_f32_e32 v240, v240, v230
	v_sub_f32_e32 v241, v241, v230
	v_sub_f32_e32 v242, v242, v230
	v_sub_f32_e32 v243, v243, v230
	v_sub_f32_e32 v244, v244, v230
	v_sub_f32_e32 v245, v245, v230
	v_sub_f32_e32 v246, v246, v230
	v_sub_f32_e32 v247, v247, v230
	v_sub_f32_e32 v248, v248, v230
	v_sub_f32_e32 v249, v249, v230
	v_sub_f32_e32 v250, v250, v230
	v_sub_f32_e32 v251, v251, v230
	v_sub_f32_e32 v64, v64, v230
	v_sub_f32_e32 v65, v65, v230
	v_sub_f32_e32 v66, v66, v230
	v_sub_f32_e32 v67, v67, v230
	v_sub_f32_e32 v68, v68, v230
	v_sub_f32_e32 v69, v69, v230
	v_sub_f32_e32 v70, v70, v230
	v_sub_f32_e32 v71, v71, v230
	v_sub_f32_e32 v72, v72, v230
	v_sub_f32_e32 v73, v73, v230
	v_sub_f32_e32 v74, v74, v230
	v_sub_f32_e32 v75, v75, v230
	v_sub_f32_e32 v76, v76, v230
	v_sub_f32_e32 v77, v77, v230
	v_sub_f32_e32 v78, v78, v230
	v_sub_f32_e32 v79, v79, v230
	v_sub_f32_e32 v80, v80, v230
	v_sub_f32_e32 v81, v81, v230
	v_sub_f32_e32 v82, v82, v230
	v_sub_f32_e32 v83, v83, v230
	v_sub_f32_e32 v84, v84, v230
	v_sub_f32_e32 v85, v85, v230
	v_sub_f32_e32 v86, v86, v230
	v_sub_f32_e32 v87, v87, v230
	v_sub_f32_e32 v88, v88, v230
	v_sub_f32_e32 v89, v89, v230
	v_sub_f32_e32 v90, v90, v230
	v_sub_f32_e32 v91, v91, v230
	v_sub_f32_e32 v92, v92, v230
	v_sub_f32_e32 v93, v93, v230
	v_sub_f32_e32 v94, v94, v230
	v_sub_f32_e32 v95, v95, v230
	v_mul_f32_e32 v133, v133, v227
	v_mul_f32_e32 v136, v136, v227
	s_branch .Lda_backA_3

; template <int MODE>
; __device__ __forceinline__ void attn_phase(LAS unsigned char* lds, const bf16* Qp, const bf16* Kp, const bf16* KPEp, const bf16* Vtp, bf16* CAT, float lam, int vcu, int G) {
;     ...
;         int tid_ = threadIdx.x; asm volatile("" : "+v"(tid_)); const int tid = tid_, lane = tid & 63, wave = __builtin_amdgcn_readfirstlane(tid >> 6), r = lane & 31, hh = lane >> 5;
;         int b, h, q0, wq, map, bh;
;         if (MODE == 0) { const int qb = unit & 31; bh = unit >> 5; b = bh >> 2; h = bh & 3; q0 = qb * 256; wq = wave; map = 0; }
;         else { const int qb = unit & 63; bh = unit >> 6; b = bh >> 3; h = bh & 7; q0 = qb * 128; wq = wave & 3; map = wave >> 2; }
;         const size_t rowbase = (size_t)b * SEQ;
;         const size_t qrow = rowbase + q0 + 32 * wq + r;
;         bf16x8 qf[NKS];
;         {
;             const bf16* qp = MODE == 0 ? Qp + qrow * 768 + h * 192 + 8 * hh : Qp + qrow * 1024 + (2 * h + map) * 64 + 8 * hh;
; #pragma unroll
;             for (int ks = 0; ks < NKS; ++ks) qf[ks] = *(const bf16x8*)(qp + 16 * ks);
;         }
;         const bf16* kp[NKI]; int kadv[NKI];
; #pragma unroll
;         for (int n = 0; n < NKI; ++n) {
;             const int P = 64 * (wave + 8 * n) + lane;
;             if (MODE == 0) {
;                 const int row = P / 24, cp = P - row * 24, c = (cp & ~7) | ((cp & 7) ^ ((row >> 1) & 7));
;                 if (c < 16) { kp[n] = Kp + (rowbase + row) * 512 + h * 128 + c * 8; kadv[n] = 64 * 512; }
;                 else { kp[n] = KPEp + (rowbase + row) * 64 + (c - 16) * 8; kadv[n] = 64 * 64; }
;             } else {
;                 const int row = P >> 4, c = (P & 15) ^ (row & 15);
;                 kp[n] = Kp + (rowbase + row) * 1024 + h * 128 + c * 8; kadv[n] = 64 * 1024;
;             }
;         }
;         const bf16* vp[2];
; #pragma unroll
;         for (int n = 0; n < 2; ++n) { const int P = 64 * (wave + 8 * n) + lane, dv = P >> 3, c = (P & 7) ^ ((dv >> 1) & 7); vp[n] = Vtp + ((size_t)(bh * 128 + dv)) * SEQ + c * 8; }
;         const unsigned kdma = lds0 + wave * 1024, vdma = lds0 + 3 * KB + wave * 1024;
;     ...
;         const int ka = MODE == 0 ? r * RB + ((hh ^ ((r >> 1) & 7)) * 16) : r * RB + (((map * 8 + hh) ^ (r & 15)) * 16);
;         const int va = r * 128 + ((hh ^ ((r >> 1) & 7)) * 16);
;         const LAS unsigned char* vring = lds + 3 * KB;
;         f32x16 o[4], S0, S1;
.LBB0_1339:
	v_mov_b32_e32 v14, v235
	s_ashr_i32 s4, s17, 7
	v_readfirstlane_b32 s38, v14
	s_lshl_b32 s5, s17, 8
	s_ashr_i32 s40, s38, 6
	v_and_b32_e32 v3, 31, v14
	s_and_b32 s36, s5, 0x1f00
	s_ashr_i32 s5, s4, 31
	s_lshl_b64 s[6:7], s[4:5], 13
	s_lshl_b32 s4, s40, 5
	v_or_b32_e32 v0, s36, v3
	s_ashr_i32 s5, s4, 31
	v_or_b32_e32 v0, s6, v0
	v_mov_b32_e32 v1, s7
	s_ashr_i32 s41, s17, 5
	v_lshl_add_u64 v[160:161], v[0:1], 0, s[4:5]
	v_mov_b64_e32 v[0:1], s[12:13]
	s_and_b32 s42, s41, 3
	v_mad_u64_u32 v[0:1], s[4:5], v160, s61, v[0:1]
	v_bfe_u32 v179, v14, 5, 1
	v_mad_i32_i24 v1, v161, s61, v1
	s_mul_i32 s36, s42, 0x180
	v_lshl_add_u64 v[0:1], v[0:1], 0, s[36:37]
	v_lshlrev_b32_e32 v232, 4, v179
	v_lshl_add_u64 v[0:1], v[0:1], 0, v[232:233]
	global_load_dwordx4 v[96:99], v[0:1], off
	global_load_dwordx4 v[100:103], v[0:1], off offset:32
	global_load_dwordx4 v[104:107], v[0:1], off offset:64
	global_load_dwordx4 v[108:111], v[0:1], off offset:96
	global_load_dwordx4 v[112:115], v[0:1], off offset:128
	global_load_dwordx4 v[116:119], v[0:1], off offset:160
	global_load_dwordx4 v[120:123], v[0:1], off offset:192
	global_load_dwordx4 v[124:127], v[0:1], off offset:224
	global_load_dwordx4 v[128:131], v[0:1], off offset:256
	global_load_dwordx4 v[132:135], v[0:1], off offset:288
	global_load_dwordx4 v[136:139], v[0:1], off offset:320
	global_load_dwordx4 v[140:143], v[0:1], off offset:352
	v_mov_b32_e32 v0, s38
	s_movk_i32 s3, 0xffc0
	v_bfi_b32 v2, s3, v0, v14
	v_mul_hi_i32 v0, v2, s96
	v_lshrrev_b32_e32 v1, 31, v0
	v_ashrrev_i32_e32 v0, 2, v0
	v_add_u32_e32 v0, v0, v1
	s_lshl_b32 s4, s42, 8
	v_lshrrev_b32_e32 v1, 1, v0
	s_add_u32 s38, s18, s4
	v_mad_u64_u32 v[4:5], s[4:5], v0, s66, v[2:3]
	v_xor_b32_e32 v1, v1, v14
	v_bfi_b32 v4, -8, v4, v1
	v_ashrrev_i32_e32 v1, 31, v0
	s_addc_u32 s39, s19, 0
	v_cmp_lt_i32_e32 vcc, 15, v4
	v_lshl_add_u64 v[6:7], s[6:7], 0, v[0:1]
	v_lshlrev_b32_e32 v4, 3, v4
	s_and_saveexec_b64 s[4:5], vcc
	s_xor_b64 s[4:5], exec, s[4:5]
	v_lshlrev_b64 v[0:1], 7, v[6:7]
	v_lshl_add_u64 v[0:1], s[28:29], 0, v[0:1]
	v_add_u32_e32 v232, 0xffffff80, v4
	v_lshl_add_u64 v[0:1], v[232:233], 1, v[0:1]
	s_or_saveexec_b64 s[4:5], s[4:5]
	v_mov_b64_e32 v[162:163], 0x1000
	s_xor_b64 exec, exec, s[4:5]
	v_lshlrev_b64 v[0:1], 10, v[6:7]
	v_lshl_add_u64 v[0:1], s[38:39], 0, v[0:1]
	v_ashrrev_i32_e32 v5, 31, v4
	v_lshl_add_u64 v[0:1], v[4:5], 1, v[0:1]
	v_mov_b64_e32 v[162:163], 0x8000
	s_or_b64 exec, exec, s[4:5]
	v_add_u32_e32 v6, 0x200, v2
	v_mul_hi_i32 v4, v6, s96
	v_lshrrev_b32_e32 v5, 31, v4
	v_ashrrev_i32_e32 v4, 2, v4
	v_add_u32_e32 v4, v4, v5
	v_lshrrev_b32_e32 v5, 1, v4
	v_mad_u64_u32 v[8:9], s[4:5], v4, s66, v[6:7]
	v_xor_b32_e32 v5, v5, v14
	v_bfi_b32 v7, -8, v8, v5
	v_ashrrev_i32_e32 v5, 31, v4
	v_cmp_lt_i32_e32 vcc, 15, v7
	v_lshl_add_u64 v[10:11], s[6:7], 0, v[4:5]
	v_lshlrev_b32_e32 v8, 3, v7
	s_and_saveexec_b64 s[4:5], vcc
	s_xor_b64 s[4:5], exec, s[4:5]
	v_lshlrev_b64 v[4:5], 7, v[10:11]
	v_lshl_add_u64 v[4:5], s[28:29], 0, v[4:5]
	v_add_u32_e32 v232, 0xffffff80, v8
	v_lshl_add_u64 v[4:5], v[232:233], 1, v[4:5]
	s_or_saveexec_b64 s[4:5], s[4:5]
	v_mov_b64_e32 v[164:165], 0x1000
	s_xor_b64 exec, exec, s[4:5]
	v_lshlrev_b64 v[4:5], 10, v[10:11]
	v_lshl_add_u64 v[4:5], s[38:39], 0, v[4:5]
	v_ashrrev_i32_e32 v9, 31, v8
	v_lshl_add_u64 v[4:5], v[8:9], 1, v[4:5]
	v_mov_b64_e32 v[164:165], 0x8000
	s_or_b64 exec, exec, s[4:5]
	v_add_u32_e32 v8, 0x400, v2
	v_mul_hi_i32 v7, v8, s96
	v_lshrrev_b32_e32 v9, 31, v7
	v_ashrrev_i32_e32 v7, 2, v7
	v_add_u32_e32 v10, v7, v9
	v_lshrrev_b32_e32 v7, 1, v10
	v_mad_u64_u32 v[8:9], s[4:5], v10, s66, v[8:9]
	v_xor_b32_e32 v7, v7, v14
	v_bfi_b32 v7, -8, v8, v7
	v_ashrrev_i32_e32 v11, 31, v10
	v_cmp_lt_i32_e32 vcc, 15, v7
	v_lshl_add_u64 v[12:13], s[6:7], 0, v[10:11]
	v_lshlrev_b32_e32 v10, 3, v7
	s_and_saveexec_b64 s[4:5], vcc
	s_xor_b64 s[4:5], exec, s[4:5]
	v_lshlrev_b64 v[8:9], 7, v[12:13]
	v_lshl_add_u64 v[8:9], s[28:29], 0, v[8:9]
	v_add_u32_e32 v232, 0xffffff80, v10
	v_lshl_add_u64 v[8:9], v[232:233], 1, v[8:9]
	s_or_saveexec_b64 s[4:5], s[4:5]
	s_lshl_b32 s54, s42, 7
	v_mov_b64_e32 v[166:167], 0x1000
	s_xor_b64 exec, exec, s[4:5]
	v_lshlrev_b64 v[8:9], 10, v[12:13]
	v_lshl_add_u64 v[8:9], s[38:39], 0, v[8:9]
	v_ashrrev_i32_e32 v11, 31, v10
	v_lshl_add_u64 v[8:9], v[10:11], 1, v[8:9]
	v_mov_b64_e32 v[166:167], 0x8000
	s_or_b64 exec, exec, s[4:5]
	v_ashrrev_i32_e32 v7, 3, v2
	v_lshrrev_b32_e32 v2, 4, v2
	v_xor_b32_e32 v2, v2, v14
	v_lshlrev_b32_e32 v2, 4, v2
	s_lshl_b32 s4, s41, 7
	v_and_b32_e32 v232, 0x70, v2
	v_ashrrev_i32_e32 v2, 3, v6
	v_add_u32_e32 v10, s4, v7
	v_add_u32_e32 v6, s4, v2
	v_ashrrev_i32_e32 v11, 31, v10
	v_ashrrev_i32_e32 v7, 31, v6
	s_lshl_b32 s4, s40, 10
	v_lshlrev_b64 v[10:11], 14, v[10:11]
	v_lshlrev_b64 v[6:7], 14, v[6:7]
	s_add_i32 s4, s4, 0
	s_mov_b32 s6, m0
	s_mov_b32 m0, s4
	s_nop 0
	global_load_lds_dwordx4 v[0:1], off
	s_mov_b32 m0, s6
	v_lshl_add_u64 v[10:11], s[14:15], 0, v[10:11]
	v_lshl_add_u64 v[6:7], s[14:15], 0, v[6:7]
	s_add_i32 s6, s4, 0x2000
	s_mov_b32 s7, m0
	s_mov_b32 m0, s6
	s_nop 0
	global_load_lds_dwordx4 v[4:5], off
	s_mov_b32 m0, s7
	v_lshl_add_u64 v[48:49], v[10:11], 0, v[232:233]
	v_lshl_add_u64 v[50:51], v[6:7], 0, v[232:233]
	s_add_i32 s6, s4, 0x4000
	s_mov_b32 s7, m0
	s_mov_b32 m0, s6
	s_nop 0
	global_load_lds_dwordx4 v[8:9], off
	s_mov_b32 m0, s7
	v_lshlrev_b32_e32 v232, 1, v162
	v_lshl_add_u64 v[0:1], v[0:1], 0, v[232:233]
	v_lshlrev_b32_e32 v52, 1, v164
	v_mov_b32_e32 v53, v233
	s_add_i32 s6, s4, 0x6000
	s_mov_b32 s7, m0
	s_mov_b32 m0, s6
	s_nop 0
	global_load_lds_dwordx4 v[0:1], off
	s_mov_b32 m0, s7
	v_lshrrev_b32_e32 v2, 1, v14
; #define LAS __attribute__((address_space(3)))
; #define MFMA32(a, b, c) __builtin_amdgcn_mfma_f32_32x32x16_bf16((a), (b), (c), 0, 0, 0)
; #define ATT_DMA_K(slotoff) do { _Pragma("unroll") for (int n = 0; n < NKI; ++n) glds16(kp[n], (unsigned)__builtin_amdgcn_readfirstlane(kdma + (slotoff) + n * 8192)); } while (0)
; #define ATT_DMA_V(slotoff) do { _Pragma("unroll") for (int n = 0; n < 2; ++n) glds16(vp[n], (unsigned)__builtin_amdgcn_readfirstlane(vdma + (slotoff) + n * 8192)); } while (0)
;     constexpr int NKS = MODE == 0 ? 12 : 4, RB = MODE == 0 ? 384 : 256;
;     f32x16 z;
; #pragma unroll
;     for (int i = 0; i < 16; ++i) z[i] = 0.f;
; #pragma unroll
;     for (int ks = 0; ks < NKS; ++ks) {
;         const LAS unsigned char* p = kslot + ((ka ^ ((ks & 3) * 32)) + (ks >> 2) * 128);
;         const bf16x8 a0 = *(const LAS bf16x8*)p, a1 = *(const LAS bf16x8*)(p + 32 * RB);
;         if (ks == 0) { s0 = MFMA32(a0, qf[0], z); s1 = MFMA32(a1, qf[0], z); }
;         else { s0 = MFMA32(a0, qf[ks], s0); s1 = MFMA32(a1, qf[ks], s1); }
;     }
; }
; template <int MODE>
; __device__ __forceinline__ void attn_phase(LAS unsigned char* lds, const bf16* Qp, const bf16* Kp, const bf16* KPEp, const bf16* Vtp, bf16* CAT, float lam, int vcu, int G) {
;     ...
;         const bf16* vp[2];
; #pragma unroll
;         for (int n = 0; n < 2; ++n) { const int P = 64 * (wave + 8 * n) + lane, dv = P >> 3, c = (P & 7) ^ ((dv >> 1) & 7); vp[n] = Vtp + ((size_t)(bh * 128 + dv)) * SEQ + c * 8; }
;         const unsigned kdma = lds0 + wave * 1024, vdma = lds0 + 3 * KB + wave * 1024;
;     ...
;         const int ka = MODE == 0 ? r * RB + ((hh ^ ((r >> 1) & 7)) * 16) : r * RB + (((map * 8 + hh) ^ (r & 15)) * 16);
;         const int va = r * 128 + ((hh ^ ((r >> 1) & 7)) * 16);
;         const LAS unsigned char* vring = lds + 3 * KB;
;         f32x16 o[4], S0, S1;
;         bf16x8 pf[4];
; #pragma unroll
;         for (int db = 0; db < 4; ++db)
; #pragma unroll
;             for (int i = 0; i < 16; ++i) o[db][i] = 0.f;
;         float mhat = 0.f, lrun = 0.f, fpend = 1.f; bool havepend = false;
;         ATT_DMA_K(0); ATT_ADV_K(); ATT_DMA_K(KB); ATT_ADV_K(); ATT_DMA_V(0); ATT_ADV_V();
;         asm volatile("s_waitcnt vmcnt(0) lgkmcnt(0)\n\ts_barrier" ::: "memory");
;         int kr = 0, kw = 2 * KB, vr = 2 * VB, vw = VB;
	v_lshl_add_u64 v[80:81], v[4:5], 0, v[52:53]
	v_lshlrev_b32_e32 v54, 1, v166
	v_mov_b32_e32 v55, v233
	s_add_i32 s6, s4, 0x8000
	s_mov_b32 s7, m0
	s_mov_b32 m0, s6
	s_nop 0
	global_load_lds_dwordx4 v[80:81], off
	s_mov_b32 m0, s7
	v_bitop3_b32 v2, v179, v2, 7 bitop3:0x78
	v_lshl_add_u64 v[82:83], v[8:9], 0, v[54:55]
	s_add_i32 s6, s4, 0xa000
	s_mov_b32 s7, m0
	s_mov_b32 m0, s6
	s_nop 0
	global_load_lds_dwordx4 v[82:83], off
	s_mov_b32 m0, s7
	s_add_i32 s5, s4, 0x12000
	v_lshlrev_b32_e32 v2, 4, v2
	v_mul_u32_u24_e32 v68, 0x180, v3
	s_mov_b32 s6, m0
	s_mov_b32 m0, s5
	s_nop 0
	global_load_lds_dwordx4 v[48:49], off
	s_mov_b32 m0, s6
	v_or_b32_e32 v163, v2, v68
	s_add_i32 s6, s4, 0x14000
	s_mov_b32 s7, m0
	s_mov_b32 m0, s6
	s_nop 0
	global_load_lds_dwordx4 v[50:51], off
	s_mov_b32 m0, s7
	v_mov_b32_e32 v168, v0
	v_mov_b32_e32 v169, v1
	v_mov_b32_e32 v170, v80
	v_mov_b32_e32 v171, v81
	v_mov_b32_e32 v172, v82
	v_mov_b32_e32 v173, v83
	v_subrev_u32_e32 v174, s14, v48
	v_subrev_u32_e32 v175, s14, v50
	v_lshlrev_b32_e32 v186, 1, v162
	v_mov_b32_e32 v187, 0
	v_lshlrev_b32_e32 v188, 1, v164
	v_mov_b32_e32 v189, 0
	v_lshlrev_b32_e32 v190, 1, v166
	v_mov_b32_e32 v191, 0
	v_xor_b32_e32 v165, 32, v163
	v_xor_b32_e32 v167, 64, v163
	v_xor_b32_e32 v180, 0x60, v163
	v_lshl_or_b32 v176, v3, 7, v2
	v_xor_b32_e32 v184, 0x0, v176
	v_xor_b32_e32 v183, 0x20, v176
	v_xor_b32_e32 v182, 0x40, v176
	v_xor_b32_e32 v181, 0x60, v176
	v_add_u32_e32 v184, 0x12000, v184
	v_add_u32_e32 v183, 0x12000, v183
	v_add_u32_e32 v182, 0x12000, v182
	v_add_u32_e32 v181, 0x12000, v181
	s_mov_b32 s45, m0
	s_mov_b32 s44, 0
	v_lshl_add_u64 v[168:169], v[168:169], 0, v[186:187]
	v_lshl_add_u64 v[170:171], v[170:171], 0, v[188:189]
	v_lshl_add_u64 v[172:173], v[172:173], 0, v[190:191]
	s_add_u32 s6, s14, 0x80
	s_addc_u32 s7, s15, 0
	s_waitcnt vmcnt(0) lgkmcnt(0)
	s_barrier
	ds_read_b128 v[196:199], v163
	ds_read_b128 v[200:203], v165
	ds_read_b128 v[204:207], v167
	ds_read_b128 v[208:211], v180
	s_waitcnt lgkmcnt(2)
	v_mfma_f32_32x32x16_bf16 v[64:79], v[196:199], v[96:99], 0
	ds_read_b128 v[212:215], v163 offset:128
	ds_read_b128 v[216:219], v165 offset:128
	v_mov_b64_e32 v[0:1], 0
	v_mov_b64_e32 v[2:3], 0
	v_mov_b64_e32 v[4:5], 0
	v_mov_b64_e32 v[6:7], 0
	v_mov_b64_e32 v[8:9], 0
	v_mov_b64_e32 v[10:11], 0
	v_mov_b64_e32 v[12:13], 0
	v_mov_b64_e32 v[14:15], 0
	v_mov_b64_e32 v[16:17], 0
	v_mov_b64_e32 v[18:19], 0
	v_mov_b64_e32 v[20:21], 0
	v_mov_b64_e32 v[22:23], 0
	v_mov_b64_e32 v[24:25], 0
	v_mov_b64_e32 v[26:27], 0
	v_mov_b64_e32 v[28:29], 0
	v_mov_b64_e32 v[30:31], 0
	v_mfma_f32_32x32x16_bf16 v[64:79], v[200:203], v[100:103], v[64:79]
	ds_read_b128 v[220:223], v167 offset:128
	ds_read_b128 v[224:227], v180 offset:128
	v_mov_b64_e32 v[32:33], 0
	v_mov_b64_e32 v[34:35], 0
	v_mov_b64_e32 v[36:37], 0
	v_mov_b64_e32 v[38:39], 0
	v_mov_b64_e32 v[40:41], 0
	v_mov_b64_e32 v[42:43], 0
	v_mov_b64_e32 v[44:45], 0
	v_mov_b64_e32 v[46:47], 0
	v_mov_b64_e32 v[48:49], 0
	v_mov_b64_e32 v[50:51], 0
	v_mov_b64_e32 v[52:53], 0
	v_mov_b64_e32 v[54:55], 0
	v_mov_b64_e32 v[56:57], 0
	v_mov_b64_e32 v[58:59], 0
	v_mov_b64_e32 v[60:61], 0
	v_mov_b64_e32 v[62:63], 0
	s_waitcnt lgkmcnt(4)
	v_mfma_f32_32x32x16_bf16 v[64:79], v[204:207], v[104:107], v[64:79]
	ds_read_b128 v[228:231], v163 offset:256
	ds_read_b128 v[196:199], v165 offset:256
	s_add_i32 m0, s4, 0xc000
	s_nop 0
	global_load_lds_dwordx4 v[168:169], off
	v_mfma_f32_32x32x16_bf16 v[64:79], v[208:211], v[108:111], v[64:79]
	ds_read_b128 v[200:203], v167 offset:256
	s_add_i32 m0, s4, 0xe000
	s_nop 0
	global_load_lds_dwordx4 v[170:171], off
	s_waitcnt lgkmcnt(5)
	v_mfma_f32_32x32x16_bf16 v[64:79], v[212:215], v[112:115], v[64:79]
	ds_read_b128 v[204:207], v180 offset:256
	s_add_i32 m0, s4, 0x10000
	s_nop 0
	global_load_lds_dwordx4 v[172:173], off
	v_mfma_f32_32x32x16_bf16 v[64:79], v[216:219], v[116:119], v[64:79]
	ds_read_b128 v[208:211], v163 offset:12288
	v_lshl_add_u64 v[168:169], v[168:169], 0, v[186:187]
	v_lshl_add_u64 v[170:171], v[170:171], 0, v[188:189]
	v_lshl_add_u64 v[172:173], v[172:173], 0, v[190:191]
	s_waitcnt lgkmcnt(5)
	v_mfma_f32_32x32x16_bf16 v[64:79], v[220:223], v[120:123], v[64:79]
	ds_read_b128 v[212:215], v165 offset:12288
	s_add_i32 m0, s4, 0x16000
	s_nop 0
	global_load_lds_dwordx4 v174, s[6:7]
	v_mfma_f32_32x32x16_bf16 v[64:79], v[224:227], v[124:127], v[64:79]
	ds_read_b128 v[216:219], v167 offset:12288
	s_add_i32 m0, s4, 0x18000
	s_nop 0
	global_load_lds_dwordx4 v175, s[6:7]
	s_waitcnt lgkmcnt(5)
	v_mfma_f32_32x32x16_bf16 v[64:79], v[228:231], v[128:131], v[64:79]
	ds_read_b128 v[220:223], v180 offset:12288
	s_add_u32 s6, s6, 0x80
	s_addc_u32 s7, s7, 0
	v_mfma_f32_32x32x16_bf16 v[64:79], v[196:199], v[132:135], v[64:79]
	ds_read_b128 v[224:227], v163 offset:12416
	s_waitcnt lgkmcnt(5)
	v_mfma_f32_32x32x16_bf16 v[64:79], v[200:203], v[136:139], v[64:79]
	ds_read_b128 v[228:231], v165 offset:12416
	v_mfma_f32_32x32x16_bf16 v[64:79], v[204:207], v[140:143], v[64:79]
	ds_read_b128 v[196:199], v167 offset:12416
	s_waitcnt lgkmcnt(5)
	v_mfma_f32_32x32x16_bf16 v[80:95], v[208:211], v[96:99], 0
	ds_read_b128 v[200:203], v180 offset:12416
	v_mfma_f32_32x32x16_bf16 v[80:95], v[212:215], v[100:103], v[80:95]
	ds_read_b128 v[204:207], v163 offset:12544
	s_waitcnt lgkmcnt(5)
	v_mfma_f32_32x32x16_bf16 v[80:95], v[216:219], v[104:107], v[80:95]
	ds_read_b128 v[208:211], v165 offset:12544
	v_mfma_f32_32x32x16_bf16 v[80:95], v[220:223], v[108:111], v[80:95]
	ds_read_b128 v[212:215], v167 offset:12544
	s_waitcnt lgkmcnt(5)
	v_mfma_f32_32x32x16_bf16 v[80:95], v[224:227], v[112:115], v[80:95]
	ds_read_b128 v[216:219], v180 offset:12544
	v_mfma_f32_32x32x16_bf16 v[80:95], v[228:231], v[116:119], v[80:95]
	s_waitcnt lgkmcnt(4)
; __device__ __forceinline__ bf16x8 pack8(f32x4 a, f32x4 b) { u32x4 w = {pk2(a[0], a[1]), pk2(a[2], a[3]), pk2(b[0], b[1]), pk2(b[2], b[3])}; return __builtin_bit_cast(bf16x8, w); }
; __device__ __forceinline__ float xor32_max(float v) { auto rr = __builtin_amdgcn_permlane32_swap(__float_as_uint(v), __float_as_uint(v), false, false); return fmaxf(__uint_as_float(rr[0]), __uint_as_float(rr[1])); }
; __device__ __forceinline__ float att_rowmax(const f32x16& s0, const f32x16& s1) {
;     float a = fmaxf(fmaxf(s0[0], s0[1]), s1[0]), b = fmaxf(fmaxf(s0[2], s0[3]), s1[1]);
;     a = fmaxf(fmaxf(a, s1[2]), s1[3]);
; #pragma unroll
;     for (int i = 4; i < 16; i += 4) { a = fmaxf(fmaxf(a, s0[i]), s0[i + 1]); b = fmaxf(fmaxf(b, s0[i + 2]), s0[i + 3]); a = fmaxf(fmaxf(a, s1[i]), s1[i + 1]); b = fmaxf(fmaxf(b, s1[i + 2]), s1[i + 3]); }
;     return xor32_max(fmaxf(a, b));
; }
; __device__ __forceinline__ void att_exp(f32x16& s0, f32x16& s1, float mhat, float& lrun, bf16x8 (&pf)[4]) {
;     float p0 = 0.f, p1 = 0.f;
; #pragma unroll
;     for (int i = 0; i < 16; ++i) { s0[i] = __builtin_amdgcn_exp2f(s0[i] - mhat); s1[i] = __builtin_amdgcn_exp2f(s1[i] - mhat); p0 += s0[i]; p1 += s1[i]; }
;     lrun += p0 + p1;
;     pf[0] = pack8((f32x4){s0[0], s0[1], s0[2], s0[3]}, (f32x4){s0[4], s0[5], s0[6], s0[7]});
;     pf[1] = pack8((f32x4){s0[8], s0[9], s0[10], s0[11]}, (f32x4){s0[12], s0[13], s0[14], s0[15]});
;     pf[2] = pack8((f32x4){s1[0], s1[1], s1[2], s1[3]}, (f32x4){s1[4], s1[5], s1[6], s1[7]});
;     pf[3] = pack8((f32x4){s1[8], s1[9], s1[10], s1[11]}, (f32x4){s1[12], s1[13], s1[14], s1[15]});
; }
; template <int MODE>
; __device__ __forceinline__ void attn_phase(LAS unsigned char* lds, const bf16* Qp, const bf16* Kp, const bf16* KPEp, const bf16* Vtp, bf16* CAT, float lam, int vcu, int G) {
;     ...
;         for (int i = 0; i < 128; ++i) {
;             att_qk<MODE>(S0, S1, lds + kr, ka, qf);
;             const float rm = att_rowmax(S0, S1);
;             if (i == 0) mhat = rm;
;             else if (__any(rm - mhat > THR)) { const float dl = fmaxf(rm - mhat, 0.f), f = __builtin_amdgcn_exp2f(-dl); lrun *= f; mhat += dl; fpend = f; havepend = true; }
;             if (i > 0) att_pv(o, vring + vr, va, pf);
;             att_exp(S0, S1, mhat, lrun, pf);
	v_mfma_f32_32x32x16_bf16 v[80:95], v[196:199], v[120:123], v[80:95]
	v_mfma_f32_32x32x16_bf16 v[80:95], v[200:203], v[124:127], v[80:95]
	s_waitcnt lgkmcnt(2)
	v_mfma_f32_32x32x16_bf16 v[80:95], v[204:207], v[128:131], v[80:95]
	v_mfma_f32_32x32x16_bf16 v[80:95], v[208:211], v[132:135], v[80:95]
	s_waitcnt lgkmcnt(0)
	v_mfma_f32_32x32x16_bf16 v[80:95], v[212:215], v[136:139], v[80:95]
	v_mfma_f32_32x32x16_bf16 v[80:95], v[216:219], v[140:143], v[80:95]
	s_nop 15
	v_max3_f32 v194, v64, v65, v66
	v_max3_f32 v195, v67, v68, v69
	v_max3_f32 v194, v194, v70, v71
	v_max3_f32 v195, v195, v72, v73
	v_max3_f32 v194, v194, v74, v75
	v_max3_f32 v195, v195, v76, v77
	v_max3_f32 v194, v194, v78, v79
	v_max3_f32 v194, v194, v80, v81
	v_max3_f32 v195, v195, v82, v83
	v_max3_f32 v194, v194, v84, v85
	v_max3_f32 v195, v195, v86, v87
	v_max3_f32 v194, v194, v88, v89
	v_max3_f32 v195, v195, v90, v91
	v_max3_f32 v194, v194, v92, v93
	v_max3_f32 v195, v195, v94, v95
	v_max_f32_e32 v194, v194, v195
	v_mov_b32_e32 v195, v194
	s_nop 1
	v_permlane32_swap_b32_e32 v194, v195
	v_max_f32_e32 v194, v194, v195
	v_sub_f32_e32 v236, 0, v194
	v_sub_f32_e32 v237, 0, v194
	v_sub_f32_e32 v238, 0, v194
	v_sub_f32_e32 v239, 0, v194
	v_sub_f32_e32 v240, 0, v194
	v_sub_f32_e32 v241, 0, v194
	v_sub_f32_e32 v242, 0, v194
	v_sub_f32_e32 v243, 0, v194
	v_sub_f32_e32 v244, 0, v194
	v_sub_f32_e32 v245, 0, v194
	v_sub_f32_e32 v246, 0, v194
	v_sub_f32_e32 v247, 0, v194
	v_sub_f32_e32 v248, 0, v194
	v_sub_f32_e32 v249, 0, v194
	v_sub_f32_e32 v250, 0, v194
	v_sub_f32_e32 v251, 0, v194
	v_sub_f32_e32 v64, v64, v194
	v_sub_f32_e32 v65, v65, v194
	v_sub_f32_e32 v66, v66, v194
	v_sub_f32_e32 v67, v67, v194
	v_sub_f32_e32 v68, v68, v194
	v_sub_f32_e32 v69, v69, v194
	v_sub_f32_e32 v70, v70, v194
	v_sub_f32_e32 v71, v71, v194
	v_sub_f32_e32 v72, v72, v194
	v_sub_f32_e32 v73, v73, v194
	v_sub_f32_e32 v74, v74, v194
	v_sub_f32_e32 v75, v75, v194
	v_sub_f32_e32 v76, v76, v194
	v_sub_f32_e32 v77, v77, v194
	v_sub_f32_e32 v78, v78, v194
	v_sub_f32_e32 v79, v79, v194
	v_sub_f32_e32 v80, v80, v194
	v_sub_f32_e32 v81, v81, v194
	v_sub_f32_e32 v82, v82, v194
	v_sub_f32_e32 v83, v83, v194
	v_sub_f32_e32 v84, v84, v194
	v_sub_f32_e32 v85, v85, v194
	v_sub_f32_e32 v86, v86, v194
	v_sub_f32_e32 v87, v87, v194
	v_sub_f32_e32 v88, v88, v194
	v_sub_f32_e32 v89, v89, v194
	v_sub_f32_e32 v90, v90, v194
	v_sub_f32_e32 v91, v91, v194
	v_sub_f32_e32 v92, v92, v194
	v_sub_f32_e32 v93, v93, v194
	v_sub_f32_e32 v94, v94, v194
	v_sub_f32_e32 v95, v95, v194
	v_mov_b32_e32 v192, 0
	v_mov_b32_e32 v193, 0
	v_exp_f32_e32 v64, v64
	v_exp_f32_e32 v65, v65
	v_add_f32_e32 v192, v192, v64
	v_add_f32_e32 v193, v193, v65
	v_exp_f32_e32 v66, v66
	v_exp_f32_e32 v67, v67
	v_add_f32_e32 v192, v192, v66
	v_add_f32_e32 v193, v193, v67
	v_exp_f32_e32 v68, v68
	v_exp_f32_e32 v69, v69
	v_add_f32_e32 v192, v192, v68
	v_add_f32_e32 v193, v193, v69
	v_exp_f32_e32 v70, v70
	v_exp_f32_e32 v71, v71
	v_add_f32_e32 v192, v192, v70
	v_add_f32_e32 v193, v193, v71
	v_exp_f32_e32 v72, v72
	v_exp_f32_e32 v73, v73
	v_add_f32_e32 v192, v192, v72
	v_add_f32_e32 v193, v193, v73
	v_exp_f32_e32 v74, v74
	v_exp_f32_e32 v75, v75
	v_add_f32_e32 v192, v192, v74
	v_add_f32_e32 v193, v193, v75
	v_exp_f32_e32 v76, v76
	v_exp_f32_e32 v77, v77
	v_add_f32_e32 v192, v192, v76
	v_add_f32_e32 v193, v193, v77
	v_exp_f32_e32 v78, v78
	v_exp_f32_e32 v79, v79
	v_add_f32_e32 v192, v192, v78
	v_add_f32_e32 v193, v193, v79
	v_cvt_pk_bf16_f32 v144, v64, v65
	v_cvt_pk_bf16_f32 v145, v66, v67
	v_cvt_pk_bf16_f32 v146, v68, v69
	v_cvt_pk_bf16_f32 v147, v70, v71
	v_cvt_pk_bf16_f32 v148, v72, v73
	v_cvt_pk_bf16_f32 v149, v74, v75
	v_cvt_pk_bf16_f32 v150, v76, v77
	v_cvt_pk_bf16_f32 v151, v78, v79
	s_mov_b32 s55, 0
	s_waitcnt vmcnt(5) lgkmcnt(0)
	s_barrier
.Lma_loop:
	v_exp_f32_e32 v80, v80
	v_exp_f32_e32 v81, v81
	v_add_f32_e32 v192, v192, v80
	v_add_f32_e32 v193, v193, v81
	ds_read_b128 v[196:199], v163 offset:24576
	ds_read_b128 v[200:203], v165 offset:24576
	ds_read_b128 v[204:207], v167 offset:24576
	ds_read_b128 v[208:211], v180 offset:24576
	s_waitcnt lgkmcnt(2)
	v_mfma_f32_32x32x16_bf16 v[64:79], v[196:199], v[96:99], v[236:251]
	ds_read_b128 v[212:215], v163 offset:24704
	ds_read_b128 v[216:219], v165 offset:24704
	v_exp_f32_e32 v82, v82
	v_exp_f32_e32 v83, v83
	v_add_f32_e32 v192, v192, v82
	v_add_f32_e32 v193, v193, v83
	v_mfma_f32_32x32x16_bf16 v[64:79], v[200:203], v[100:103], v[64:79]
	ds_read_b128 v[220:223], v167 offset:24704
	ds_read_b128 v[224:227], v180 offset:24704
	v_exp_f32_e32 v84, v84
	v_exp_f32_e32 v85, v85
	v_add_f32_e32 v192, v192, v84
	v_add_f32_e32 v193, v193, v85
	s_waitcnt lgkmcnt(4)
	v_mfma_f32_32x32x16_bf16 v[64:79], v[204:207], v[104:107], v[64:79]
	ds_read_b128 v[228:231], v163 offset:24832
	ds_read_b128 v[196:199], v165 offset:24832
	v_exp_f32_e32 v86, v86
	v_exp_f32_e32 v87, v87
	v_add_f32_e32 v192, v192, v86
	v_add_f32_e32 v193, v193, v87
	v_mfma_f32_32x32x16_bf16 v[64:79], v[208:211], v[108:111], v[64:79]
	ds_read_b128 v[200:203], v167 offset:24832
	v_exp_f32_e32 v88, v88
	v_exp_f32_e32 v89, v89
	v_add_f32_e32 v192, v192, v88
	v_add_f32_e32 v193, v193, v89
	s_waitcnt lgkmcnt(5)
	v_mfma_f32_32x32x16_bf16 v[64:79], v[212:215], v[112:115], v[64:79]
	ds_read_b128 v[204:207], v180 offset:24832
	v_exp_f32_e32 v90, v90
	v_exp_f32_e32 v91, v91
	v_add_f32_e32 v192, v192, v90
	v_add_f32_e32 v193, v193, v91
	v_cvt_pk_bf16_f32 v152, v80, v81
	v_cvt_pk_bf16_f32 v153, v82, v83
	v_mfma_f32_32x32x16_bf16 v[64:79], v[216:219], v[116:119], v[64:79]
	ds_read_b128 v[208:211], v163 offset:36864
	v_exp_f32_e32 v92, v92
	v_exp_f32_e32 v93, v93
	v_add_f32_e32 v192, v192, v92
	v_add_f32_e32 v193, v193, v93
	v_cvt_pk_bf16_f32 v154, v84, v85
	v_cvt_pk_bf16_f32 v155, v86, v87
	s_waitcnt lgkmcnt(5)
; #define LAS __attribute__((address_space(3)))
; #define MFMA32(a, b, c) __builtin_amdgcn_mfma_f32_32x32x16_bf16((a), (b), (c), 0, 0, 0)
;     constexpr int NKS = MODE == 0 ? 12 : 4, RB = MODE == 0 ? 384 : 256;
;     f32x16 z;
; #pragma unroll
;     for (int i = 0; i < 16; ++i) z[i] = 0.f;
; #pragma unroll
;     for (int ks = 0; ks < NKS; ++ks) {
;         const LAS unsigned char* p = kslot + ((ka ^ ((ks & 3) * 32)) + (ks >> 2) * 128);
;         const bf16x8 a0 = *(const LAS bf16x8*)p, a1 = *(const LAS bf16x8*)(p + 32 * RB);
;         if (ks == 0) { s0 = MFMA32(a0, qf[0], z); s1 = MFMA32(a1, qf[0], z); }
;         else { s0 = MFMA32(a0, qf[ks], s0); s1 = MFMA32(a1, qf[ks], s1); }
;     }
; }
; __device__ __forceinline__ float att_rowmax(const f32x16& s0, const f32x16& s1) {
;     float a = fmaxf(fmaxf(s0[0], s0[1]), s1[0]), b = fmaxf(fmaxf(s0[2], s0[3]), s1[1]);
;     a = fmaxf(fmaxf(a, s1[2]), s1[3]);
; #pragma unroll
;     for (int i = 4; i < 16; i += 4) { a = fmaxf(fmaxf(a, s0[i]), s0[i + 1]); b = fmaxf(fmaxf(b, s0[i + 2]), s0[i + 3]); a = fmaxf(fmaxf(a, s1[i]), s1[i + 1]); b = fmaxf(fmaxf(b, s1[i + 2]), s1[i + 3]); }
;     return xor32_max(fmaxf(a, b));
; }
; __device__ __forceinline__ void att_exp(f32x16& s0, f32x16& s1, float mhat, float& lrun, bf16x8 (&pf)[4]) {
;     float p0 = 0.f, p1 = 0.f;
; #pragma unroll
;     for (int i = 0; i < 16; ++i) { s0[i] = __builtin_amdgcn_exp2f(s0[i] - mhat); s1[i] = __builtin_amdgcn_exp2f(s1[i] - mhat); p0 += s0[i]; p1 += s1[i]; }
;     lrun += p0 + p1;
;     pf[0] = pack8((f32x4){s0[0], s0[1], s0[2], s0[3]}, (f32x4){s0[4], s0[5], s0[6], s0[7]});
;     pf[1] = pack8((f32x4){s0[8], s0[9], s0[10], s0[11]}, (f32x4){s0[12], s0[13], s0[14], s0[15]});
;     pf[2] = pack8((f32x4){s1[0], s1[1], s1[2], s1[3]}, (f32x4){s1[4], s1[5], s1[6], s1[7]});
;     pf[3] = pack8((f32x4){s1[8], s1[9], s1[10], s1[11]}, (f32x4){s1[12], s1[13], s1[14], s1[15]});
; }
; __device__ __forceinline__ void att_pv(f32x16 (&o)[4], const LAS unsigned char* vslot, int va, const bf16x8 (&pf)[4]) {
; #pragma unroll
;     for (int db = 0; db < 4; ++db)
; #pragma unroll
;         for (int kk = 0; kk < 4; ++kk) {
;             const bf16x8 v = *(const LAS bf16x8*)(vslot + ((va ^ (kk * 32)) + db * 4096));
;             o[db] = MFMA32(v, pf[kk], o[db]);
;         }
; }
	v_mfma_f32_32x32x16_bf16 v[64:79], v[220:223], v[120:123], v[64:79]
	ds_read_b128 v[212:215], v165 offset:36864
	v_exp_f32_e32 v94, v94
	v_exp_f32_e32 v95, v95
	v_add_f32_e32 v192, v192, v94
	v_add_f32_e32 v193, v193, v95
	v_mfma_f32_32x32x16_bf16 v[64:79], v[224:227], v[124:127], v[64:79]
	ds_read_b128 v[216:219], v167 offset:36864
	s_waitcnt lgkmcnt(5)
	v_mfma_f32_32x32x16_bf16 v[64:79], v[228:231], v[128:131], v[64:79]
	ds_read_b128 v[220:223], v180 offset:36864
	v_cvt_pk_bf16_f32 v156, v88, v89
	v_cvt_pk_bf16_f32 v157, v90, v91
	v_mfma_f32_32x32x16_bf16 v[64:79], v[196:199], v[132:135], v[64:79]
	ds_read_b128 v[224:227], v163 offset:36992
	v_cvt_pk_bf16_f32 v158, v92, v93
	v_cvt_pk_bf16_f32 v159, v94, v95
	s_waitcnt lgkmcnt(5)
	v_mfma_f32_32x32x16_bf16 v[64:79], v[200:203], v[136:139], v[64:79]
	ds_read_b128 v[228:231], v165 offset:36992
	v_mfma_f32_32x32x16_bf16 v[64:79], v[204:207], v[140:143], v[64:79]
	ds_read_b128 v[196:199], v167 offset:36992
	s_waitcnt lgkmcnt(5)
	v_mfma_f32_32x32x16_bf16 v[80:95], v[208:211], v[96:99], v[236:251]
	ds_read_b128 v[200:203], v180 offset:36992
	v_mfma_f32_32x32x16_bf16 v[80:95], v[212:215], v[100:103], v[80:95]
	ds_read_b128 v[204:207], v163 offset:37120
	s_add_i32 m0, s4, 0x0
	s_nop 0
	global_load_lds_dwordx4 v[168:169], off
	s_waitcnt lgkmcnt(5)
	v_mfma_f32_32x32x16_bf16 v[80:95], v[216:219], v[104:107], v[80:95]
	ds_read_b128 v[208:211], v165 offset:37120
	s_add_i32 m0, s4, 0x2000
	s_nop 0
	global_load_lds_dwordx4 v[170:171], off
	v_mfma_f32_32x32x16_bf16 v[80:95], v[220:223], v[108:111], v[80:95]
	ds_read_b128 v[212:215], v167 offset:37120
	s_add_i32 m0, s4, 0x4000
	v_max3_f32 v194, v64, v65, v66
	global_load_lds_dwordx4 v[172:173], off
	s_waitcnt lgkmcnt(5)
	v_mfma_f32_32x32x16_bf16 v[80:95], v[224:227], v[112:115], v[80:95]
	ds_read_b128 v[216:219], v180 offset:37120
	v_lshl_add_u64 v[168:169], v[168:169], 0, v[186:187]
	v_lshl_add_u64 v[170:171], v[170:171], 0, v[188:189]
	v_lshl_add_u64 v[172:173], v[172:173], 0, v[190:191]
	v_max3_f32 v195, v67, v68, v69
	v_mfma_f32_32x32x16_bf16 v[80:95], v[228:231], v[116:119], v[80:95]
	ds_read_b128 v[220:223], v184
	s_add_i32 m0, s4, 0x1a000
	v_max3_f32 v194, v194, v70, v71
	global_load_lds_dwordx4 v174, s[6:7]
	s_waitcnt lgkmcnt(5)
	v_mfma_f32_32x32x16_bf16 v[80:95], v[196:199], v[120:123], v[80:95]
	ds_read_b128 v[224:227], v184 offset:4096
	s_add_i32 m0, s4, 0x1c000
	v_max3_f32 v195, v195, v72, v73
	global_load_lds_dwordx4 v175, s[6:7]
	v_mfma_f32_32x32x16_bf16 v[80:95], v[200:203], v[124:127], v[80:95]
	ds_read_b128 v[228:231], v184 offset:8192
	s_add_u32 s6, s6, 0x80
	s_addc_u32 s7, s7, 0
	v_max3_f32 v194, v194, v74, v75
	v_max3_f32 v195, v195, v76, v77
	v_max3_f32 v194, v194, v78, v79
	s_waitcnt lgkmcnt(5)
	v_mfma_f32_32x32x16_bf16 v[80:95], v[204:207], v[128:131], v[80:95]
	ds_read_b128 v[196:199], v184 offset:12288
	v_mfma_f32_32x32x16_bf16 v[80:95], v[208:211], v[132:135], v[80:95]
	ds_read_b128 v[200:203], v183
	s_waitcnt lgkmcnt(5)
	v_mfma_f32_32x32x16_bf16 v[80:95], v[212:215], v[136:139], v[80:95]
	ds_read_b128 v[204:207], v183 offset:4096
	v_mfma_f32_32x32x16_bf16 v[80:95], v[216:219], v[140:143], v[80:95]
	ds_read_b128 v[208:211], v183 offset:8192
	s_waitcnt lgkmcnt(5)
	v_mfma_f32_32x32x16_bf16 v[48:63], v[220:223], v[144:147], v[48:63]
	ds_read_b128 v[212:215], v183 offset:12288
	v_mfma_f32_32x32x16_bf16 v[32:47], v[224:227], v[144:147], v[32:47]
	ds_read_b128 v[216:219], v182
	s_nop 5
	v_max3_f32 v194, v194, v80, v81
	v_max3_f32 v195, v195, v82, v83
	v_max3_f32 v194, v194, v84, v85
	v_max3_f32 v195, v195, v86, v87
	s_waitcnt lgkmcnt(5)
	v_mfma_f32_32x32x16_bf16 v[16:31], v[228:231], v[144:147], v[16:31]
	ds_read_b128 v[220:223], v182 offset:4096
	v_max3_f32 v194, v194, v88, v89
	v_max3_f32 v195, v195, v90, v91
	v_max3_f32 v194, v194, v92, v93
	v_max3_f32 v195, v195, v94, v95
	v_max_f32_e32 v194, v194, v195
	v_mov_b32_e32 v195, v194
	s_nop 1
	v_permlane32_swap_b32_e32 v194, v195
	v_max_f32_e32 v194, v194, v195
	v_cmp_lt_f32_e32 vcc, 0x41000000, v194
	v_mfma_f32_32x32x16_bf16 v[0:15], v[196:199], v[144:147], v[0:15]
	ds_read_b128 v[224:227], v182 offset:8192
	s_nop 1
	s_cmp_lg_u64 vcc, 0
	s_cbranch_scc1 .Lma_rareA_0
.Lma_backA_0:
	v_exp_f32_e32 v64, v64
	v_exp_f32_e32 v65, v65
	v_add_f32_e32 v192, v192, v64
	v_add_f32_e32 v193, v193, v65
	s_waitcnt lgkmcnt(5)
	v_mfma_f32_32x32x16_bf16 v[48:63], v[200:203], v[148:151], v[48:63]
	ds_read_b128 v[228:231], v182 offset:12288
	v_exp_f32_e32 v66, v66
	v_exp_f32_e32 v67, v67
	v_add_f32_e32 v192, v192, v66
	v_add_f32_e32 v193, v193, v67
	v_mfma_f32_32x32x16_bf16 v[32:47], v[204:207], v[148:151], v[32:47]
	ds_read_b128 v[196:199], v181
	v_exp_f32_e32 v68, v68
	v_exp_f32_e32 v69, v69
	v_add_f32_e32 v192, v192, v68
	v_add_f32_e32 v193, v193, v69
	s_waitcnt lgkmcnt(5)
	v_mfma_f32_32x32x16_bf16 v[16:31], v[208:211], v[148:151], v[16:31]
	ds_read_b128 v[200:203], v181 offset:4096
	v_exp_f32_e32 v70, v70
	v_exp_f32_e32 v71, v71
	v_add_f32_e32 v192, v192, v70
	v_add_f32_e32 v193, v193, v71
	v_cvt_pk_bf16_f32 v144, v64, v65
	v_cvt_pk_bf16_f32 v145, v66, v67
	v_mfma_f32_32x32x16_bf16 v[0:15], v[212:215], v[148:151], v[0:15]
	ds_read_b128 v[204:207], v181 offset:8192
	v_exp_f32_e32 v72, v72
	v_exp_f32_e32 v73, v73
	v_add_f32_e32 v192, v192, v72
	v_add_f32_e32 v193, v193, v73
	v_cvt_pk_bf16_f32 v146, v68, v69
	v_cvt_pk_bf16_f32 v147, v70, v71
	s_waitcnt lgkmcnt(5)
	v_mfma_f32_32x32x16_bf16 v[48:63], v[216:219], v[152:155], v[48:63]
	ds_read_b128 v[208:211], v181 offset:12288
	v_exp_f32_e32 v74, v74
	v_exp_f32_e32 v75, v75
	v_add_f32_e32 v192, v192, v74
	v_add_f32_e32 v193, v193, v75
	v_mfma_f32_32x32x16_bf16 v[32:47], v[220:223], v[152:155], v[32:47]
	v_exp_f32_e32 v76, v76
	v_exp_f32_e32 v77, v77
	v_add_f32_e32 v192, v192, v76
	v_add_f32_e32 v193, v193, v77
	s_waitcnt lgkmcnt(4)
	v_mfma_f32_32x32x16_bf16 v[16:31], v[224:227], v[152:155], v[16:31]
	v_exp_f32_e32 v78, v78
	v_exp_f32_e32 v79, v79
	v_add_f32_e32 v192, v192, v78
	v_add_f32_e32 v193, v193, v79
	v_mfma_f32_32x32x16_bf16 v[0:15], v[228:231], v[152:155], v[0:15]
	v_cvt_pk_bf16_f32 v148, v72, v73
	v_cvt_pk_bf16_f32 v149, v74, v75
	s_waitcnt lgkmcnt(2)
	v_mfma_f32_32x32x16_bf16 v[48:63], v[196:199], v[156:159], v[48:63]
	v_cvt_pk_bf16_f32 v150, v76, v77
	v_cvt_pk_bf16_f32 v151, v78, v79
	v_mfma_f32_32x32x16_bf16 v[32:47], v[200:203], v[156:159], v[32:47]
	s_waitcnt lgkmcnt(0)
	v_mfma_f32_32x32x16_bf16 v[16:31], v[204:207], v[156:159], v[16:31]
	v_mfma_f32_32x32x16_bf16 v[0:15], v[208:211], v[156:159], v[0:15]
	s_cmp_eq_u32 s44, 0
	s_cbranch_scc1 .Lma_skipB_0
; #define LAS __attribute__((address_space(3)))
;     constexpr int NKS = MODE == 0 ? 12 : 4, RB = MODE == 0 ? 384 : 256;
;     f32x16 z;
; #pragma unroll
;     for (int i = 0; i < 16; ++i) z[i] = 0.f;
; #pragma unroll
;     for (int ks = 0; ks < NKS; ++ks) {
;         const LAS unsigned char* p = kslot + ((ka ^ ((ks & 3) * 32)) + (ks >> 2) * 128);
;         const bf16x8 a0 = *(const LAS bf16x8*)p, a1 = *(const LAS bf16x8*)(p + 32 * RB);
;         if (ks == 0) { s0 = MFMA32(a0, qf[0], z); s1 = MFMA32(a1, qf[0], z); }
;         else { s0 = MFMA32(a0, qf[ks], s0); s1 = MFMA32(a1, qf[ks], s1); }
;     }
; }
; __device__ __forceinline__ float att_rowmax(const f32x16& s0, const f32x16& s1) {
;     float a = fmaxf(fmaxf(s0[0], s0[1]), s1[0]), b = fmaxf(fmaxf(s0[2], s0[3]), s1[1]);
;     a = fmaxf(fmaxf(a, s1[2]), s1[3]);
; #pragma unroll
;     for (int i = 4; i < 16; i += 4) { a = fmaxf(fmaxf(a, s0[i]), s0[i + 1]); b = fmaxf(fmaxf(b, s0[i + 2]), s0[i + 3]); a = fmaxf(fmaxf(a, s1[i]), s1[i + 1]); b = fmaxf(fmaxf(b, s1[i + 2]), s1[i + 3]); }
;     return xor32_max(fmaxf(a, b));
; }
; __device__ __forceinline__ void att_exp(f32x16& s0, f32x16& s1, float mhat, float& lrun, bf16x8 (&pf)[4]) {
;     float p0 = 0.f, p1 = 0.f;
; #pragma unroll
; template <int MODE>
; __device__ __forceinline__ void attn_phase(LAS unsigned char* lds, const bf16* Qp, const bf16* Kp, const bf16* KPEp, const bf16* Vtp, bf16* CAT, float lam, int vcu, int G) {
;     ...
;         for (int i = 0; i < 128; ++i) {
;             att_qk<MODE>(S0, S1, lds + kr, ka, qf);
;             const float rm = att_rowmax(S0, S1);
;             if (i == 0) mhat = rm;
;             else if (__any(rm - mhat > THR)) { const float dl = fmaxf(rm - mhat, 0.f), f = __builtin_amdgcn_exp2f(-dl); lrun *= f; mhat += dl; fpend = f; havepend = true; }
;             if (i > 0) att_pv(o, vring + vr, va, pf);
;             att_exp(S0, S1, mhat, lrun, pf);
;             ATT_RESC_O();
;             ATT_DMA_K(kw); ATT_DMA_V(vw);
;             if (i + 2 < 127) ATT_ADV_K();
;             if (i + 1 < 127) ATT_ADV_V();
;             kr = (kr == 2 * KB) ? 0 : kr + KB; kw = (kw == 2 * KB) ? 0 : kw + KB;
;             vr = (vr == 2 * VB) ? 0 : vr + VB; vw = (vw == 2 * VB) ? 0 : vw + VB;
;             asm volatile("s_waitcnt vmcnt(5) lgkmcnt(0)\n\ts_barrier" ::: "memory");
	s_nop 11
	v_mul_f32_e32 v0, v177, v0
	v_mul_f32_e32 v1, v177, v1
	v_mul_f32_e32 v2, v177, v2
	v_mul_f32_e32 v3, v177, v3
	v_mul_f32_e32 v4, v177, v4
	v_mul_f32_e32 v5, v177, v5
	v_mul_f32_e32 v6, v177, v6
	v_mul_f32_e32 v7, v177, v7
	v_mul_f32_e32 v8, v177, v8
	v_mul_f32_e32 v9, v177, v9
	v_mul_f32_e32 v10, v177, v10
	v_mul_f32_e32 v11, v177, v11
	v_mul_f32_e32 v12, v177, v12
	v_mul_f32_e32 v13, v177, v13
	v_mul_f32_e32 v14, v177, v14
	v_mul_f32_e32 v15, v177, v15
	v_mul_f32_e32 v16, v177, v16
	v_mul_f32_e32 v17, v177, v17
	v_mul_f32_e32 v18, v177, v18
	v_mul_f32_e32 v19, v177, v19
	v_mul_f32_e32 v20, v177, v20
	v_mul_f32_e32 v21, v177, v21
	v_mul_f32_e32 v22, v177, v22
	v_mul_f32_e32 v23, v177, v23
	v_mul_f32_e32 v24, v177, v24
	v_mul_f32_e32 v25, v177, v25
	v_mul_f32_e32 v26, v177, v26
	v_mul_f32_e32 v27, v177, v27
	v_mul_f32_e32 v28, v177, v28
	v_mul_f32_e32 v29, v177, v29
	v_mul_f32_e32 v30, v177, v30
	v_mul_f32_e32 v31, v177, v31
	v_mul_f32_e32 v32, v177, v32
	v_mul_f32_e32 v33, v177, v33
	v_mul_f32_e32 v34, v177, v34
	v_mul_f32_e32 v35, v177, v35
	v_mul_f32_e32 v36, v177, v36
	v_mul_f32_e32 v37, v177, v37
	v_mul_f32_e32 v38, v177, v38
	v_mul_f32_e32 v39, v177, v39
	v_mul_f32_e32 v40, v177, v40
	v_mul_f32_e32 v41, v177, v41
	v_mul_f32_e32 v42, v177, v42
	v_mul_f32_e32 v43, v177, v43
	v_mul_f32_e32 v44, v177, v44
	v_mul_f32_e32 v45, v177, v45
	v_mul_f32_e32 v46, v177, v46
	v_mul_f32_e32 v47, v177, v47
	v_mul_f32_e32 v48, v177, v48
	v_mul_f32_e32 v49, v177, v49
	v_mul_f32_e32 v50, v177, v50
	v_mul_f32_e32 v51, v177, v51
	v_mul_f32_e32 v52, v177, v52
	v_mul_f32_e32 v53, v177, v53
	v_mul_f32_e32 v54, v177, v54
	v_mul_f32_e32 v55, v177, v55
	v_mul_f32_e32 v56, v177, v56
	v_mul_f32_e32 v57, v177, v57
	v_mul_f32_e32 v58, v177, v58
	v_mul_f32_e32 v59, v177, v59
	v_mul_f32_e32 v60, v177, v60
	v_mul_f32_e32 v61, v177, v61
	v_mul_f32_e32 v62, v177, v62
	v_mul_f32_e32 v63, v177, v63
	s_mov_b32 s44, 0
.Lma_skipB_0:
	s_waitcnt vmcnt(5) lgkmcnt(0)
	s_barrier
	v_exp_f32_e32 v80, v80
	v_exp_f32_e32 v81, v81
	v_add_f32_e32 v192, v192, v80
	v_add_f32_e32 v193, v193, v81
	ds_read_b128 v[196:199], v163 offset:49152
	ds_read_b128 v[200:203], v165 offset:49152
	ds_read_b128 v[204:207], v167 offset:49152
	ds_read_b128 v[208:211], v180 offset:49152
	s_waitcnt lgkmcnt(2)
	v_mfma_f32_32x32x16_bf16 v[64:79], v[196:199], v[96:99], v[236:251]
	ds_read_b128 v[212:215], v163 offset:49280
	ds_read_b128 v[216:219], v165 offset:49280
	v_exp_f32_e32 v82, v82
	v_exp_f32_e32 v83, v83
	v_add_f32_e32 v192, v192, v82
	v_add_f32_e32 v193, v193, v83
	v_mfma_f32_32x32x16_bf16 v[64:79], v[200:203], v[100:103], v[64:79]
	ds_read_b128 v[220:223], v167 offset:49280
	ds_read_b128 v[224:227], v180 offset:49280
	v_exp_f32_e32 v84, v84
	v_exp_f32_e32 v85, v85
	v_add_f32_e32 v192, v192, v84
	v_add_f32_e32 v193, v193, v85
	s_waitcnt lgkmcnt(4)
	v_mfma_f32_32x32x16_bf16 v[64:79], v[204:207], v[104:107], v[64:79]
	ds_read_b128 v[228:231], v163 offset:49408
	ds_read_b128 v[196:199], v165 offset:49408
	v_exp_f32_e32 v86, v86
	v_exp_f32_e32 v87, v87
	v_add_f32_e32 v192, v192, v86
	v_add_f32_e32 v193, v193, v87
	v_mfma_f32_32x32x16_bf16 v[64:79], v[208:211], v[108:111], v[64:79]
	ds_read_b128 v[200:203], v167 offset:49408
	v_exp_f32_e32 v88, v88
	v_exp_f32_e32 v89, v89
	v_add_f32_e32 v192, v192, v88
	v_add_f32_e32 v193, v193, v89
	s_waitcnt lgkmcnt(5)
	v_mfma_f32_32x32x16_bf16 v[64:79], v[212:215], v[112:115], v[64:79]
	ds_read_b128 v[204:207], v180 offset:49408
	v_exp_f32_e32 v90, v90
	v_exp_f32_e32 v91, v91
	v_add_f32_e32 v192, v192, v90
	v_add_f32_e32 v193, v193, v91
	v_cvt_pk_bf16_f32 v152, v80, v81
	v_cvt_pk_bf16_f32 v153, v82, v83
	v_mfma_f32_32x32x16_bf16 v[64:79], v[216:219], v[116:119], v[64:79]
	ds_read_b128 v[208:211], v163 offset:61440
	v_exp_f32_e32 v92, v92
	v_exp_f32_e32 v93, v93
	v_add_f32_e32 v192, v192, v92
	v_add_f32_e32 v193, v193, v93
	v_cvt_pk_bf16_f32 v154, v84, v85
	v_cvt_pk_bf16_f32 v155, v86, v87
	s_waitcnt lgkmcnt(5)
	v_mfma_f32_32x32x16_bf16 v[64:79], v[220:223], v[120:123], v[64:79]
	ds_read_b128 v[212:215], v165 offset:61440
	v_exp_f32_e32 v94, v94
	v_exp_f32_e32 v95, v95
	v_add_f32_e32 v192, v192, v94
	v_add_f32_e32 v193, v193, v95
	v_mfma_f32_32x32x16_bf16 v[64:79], v[224:227], v[124:127], v[64:79]
	ds_read_b128 v[216:219], v167 offset:61440
	s_waitcnt lgkmcnt(5)
	v_mfma_f32_32x32x16_bf16 v[64:79], v[228:231], v[128:131], v[64:79]
	ds_read_b128 v[220:223], v180 offset:61440
	v_cvt_pk_bf16_f32 v156, v88, v89
	v_cvt_pk_bf16_f32 v157, v90, v91
	v_mfma_f32_32x32x16_bf16 v[64:79], v[196:199], v[132:135], v[64:79]
	ds_read_b128 v[224:227], v163 offset:61568
	v_cvt_pk_bf16_f32 v158, v92, v93
	v_cvt_pk_bf16_f32 v159, v94, v95
	s_waitcnt lgkmcnt(5)
	v_mfma_f32_32x32x16_bf16 v[64:79], v[200:203], v[136:139], v[64:79]
	ds_read_b128 v[228:231], v165 offset:61568
	v_mfma_f32_32x32x16_bf16 v[64:79], v[204:207], v[140:143], v[64:79]
	ds_read_b128 v[196:199], v167 offset:61568
	s_waitcnt lgkmcnt(5)
	v_mfma_f32_32x32x16_bf16 v[80:95], v[208:211], v[96:99], v[236:251]
	ds_read_b128 v[200:203], v180 offset:61568
	v_mfma_f32_32x32x16_bf16 v[80:95], v[212:215], v[100:103], v[80:95]
	ds_read_b128 v[204:207], v163 offset:61696
	s_add_i32 m0, s4, 0x6000
	s_nop 0
	global_load_lds_dwordx4 v[168:169], off
	s_waitcnt lgkmcnt(5)
	v_mfma_f32_32x32x16_bf16 v[80:95], v[216:219], v[104:107], v[80:95]
	ds_read_b128 v[208:211], v165 offset:61696
	s_add_i32 m0, s4, 0x8000
	s_nop 0
	global_load_lds_dwordx4 v[170:171], off
	v_mfma_f32_32x32x16_bf16 v[80:95], v[220:223], v[108:111], v[80:95]
	ds_read_b128 v[212:215], v167 offset:61696
	s_add_i32 m0, s4, 0xa000
	v_max3_f32 v194, v64, v65, v66
	global_load_lds_dwordx4 v[172:173], off
	s_waitcnt lgkmcnt(5)
; #define LAS __attribute__((address_space(3)))
; #define MFMA32(a, b, c) __builtin_amdgcn_mfma_f32_32x32x16_bf16((a), (b), (c), 0, 0, 0)
;     constexpr int NKS = MODE == 0 ? 12 : 4, RB = MODE == 0 ? 384 : 256;
;     f32x16 z;
; #pragma unroll
;     for (int i = 0; i < 16; ++i) z[i] = 0.f;
; #pragma unroll
;     for (int ks = 0; ks < NKS; ++ks) {
;         const LAS unsigned char* p = kslot + ((ka ^ ((ks & 3) * 32)) + (ks >> 2) * 128);
;         const bf16x8 a0 = *(const LAS bf16x8*)p, a1 = *(const LAS bf16x8*)(p + 32 * RB);
;         if (ks == 0) { s0 = MFMA32(a0, qf[0], z); s1 = MFMA32(a1, qf[0], z); }
;         else { s0 = MFMA32(a0, qf[ks], s0); s1 = MFMA32(a1, qf[ks], s1); }
;     }
; }
; __device__ __forceinline__ float att_rowmax(const f32x16& s0, const f32x16& s1) {
;     float a = fmaxf(fmaxf(s0[0], s0[1]), s1[0]), b = fmaxf(fmaxf(s0[2], s0[3]), s1[1]);
;     a = fmaxf(fmaxf(a, s1[2]), s1[3]);
; #pragma unroll
;     for (int i = 4; i < 16; i += 4) { a = fmaxf(fmaxf(a, s0[i]), s0[i + 1]); b = fmaxf(fmaxf(b, s0[i + 2]), s0[i + 3]); a = fmaxf(fmaxf(a, s1[i]), s1[i + 1]); b = fmaxf(fmaxf(b, s1[i + 2]), s1[i + 3]); }
;     return xor32_max(fmaxf(a, b));
; }
; __device__ __forceinline__ void att_exp(f32x16& s0, f32x16& s1, float mhat, float& lrun, bf16x8 (&pf)[4]) {
;     float p0 = 0.f, p1 = 0.f;
; #pragma unroll
;     for (int i = 0; i < 16; ++i) { s0[i] = __builtin_amdgcn_exp2f(s0[i] - mhat); s1[i] = __builtin_amdgcn_exp2f(s1[i] - mhat); p0 += s0[i]; p1 += s1[i]; }
;     lrun += p0 + p1;
;     pf[0] = pack8((f32x4){s0[0], s0[1], s0[2], s0[3]}, (f32x4){s0[4], s0[5], s0[6], s0[7]});
;     pf[1] = pack8((f32x4){s0[8], s0[9], s0[10], s0[11]}, (f32x4){s0[12], s0[13], s0[14], s0[15]});
;     pf[2] = pack8((f32x4){s1[0], s1[1], s1[2], s1[3]}, (f32x4){s1[4], s1[5], s1[6], s1[7]});
;     pf[3] = pack8((f32x4){s1[8], s1[9], s1[10], s1[11]}, (f32x4){s1[12], s1[13], s1[14], s1[15]});
; }
; __device__ __forceinline__ void att_pv(f32x16 (&o)[4], const LAS unsigned char* vslot, int va, const bf16x8 (&pf)[4]) {
; #pragma unroll
;     for (int db = 0; db < 4; ++db)
; #pragma unroll
;         for (int kk = 0; kk < 4; ++kk) {
;             const bf16x8 v = *(const LAS bf16x8*)(vslot + ((va ^ (kk * 32)) + db * 4096));
;             o[db] = MFMA32(v, pf[kk], o[db]);
;         }
; }
	v_mfma_f32_32x32x16_bf16 v[80:95], v[224:227], v[112:115], v[80:95]
	ds_read_b128 v[216:219], v180 offset:61696
	v_lshl_add_u64 v[168:169], v[168:169], 0, v[186:187]
	v_lshl_add_u64 v[170:171], v[170:171], 0, v[188:189]
	v_lshl_add_u64 v[172:173], v[172:173], 0, v[190:191]
	v_max3_f32 v195, v67, v68, v69
	v_mfma_f32_32x32x16_bf16 v[80:95], v[228:231], v[116:119], v[80:95]
	ds_read_b128 v[220:223], v184 offset:16384
	s_add_i32 m0, s4, 0x12000
	v_max3_f32 v194, v194, v70, v71
	global_load_lds_dwordx4 v174, s[6:7]
	s_waitcnt lgkmcnt(5)
	v_mfma_f32_32x32x16_bf16 v[80:95], v[196:199], v[120:123], v[80:95]
	ds_read_b128 v[224:227], v184 offset:20480
	s_add_i32 m0, s4, 0x14000
	v_max3_f32 v195, v195, v72, v73
	global_load_lds_dwordx4 v175, s[6:7]
	v_mfma_f32_32x32x16_bf16 v[80:95], v[200:203], v[124:127], v[80:95]
	ds_read_b128 v[228:231], v184 offset:24576
	s_add_u32 s6, s6, 0x80
	s_addc_u32 s7, s7, 0
	v_max3_f32 v194, v194, v74, v75
	v_max3_f32 v195, v195, v76, v77
	v_max3_f32 v194, v194, v78, v79
	s_waitcnt lgkmcnt(5)
	v_mfma_f32_32x32x16_bf16 v[80:95], v[204:207], v[128:131], v[80:95]
	ds_read_b128 v[196:199], v184 offset:28672
	v_mfma_f32_32x32x16_bf16 v[80:95], v[208:211], v[132:135], v[80:95]
	ds_read_b128 v[200:203], v183 offset:16384
	s_waitcnt lgkmcnt(5)
	v_mfma_f32_32x32x16_bf16 v[80:95], v[212:215], v[136:139], v[80:95]
	ds_read_b128 v[204:207], v183 offset:20480
	v_mfma_f32_32x32x16_bf16 v[80:95], v[216:219], v[140:143], v[80:95]
	ds_read_b128 v[208:211], v183 offset:24576
	s_waitcnt lgkmcnt(5)
	v_mfma_f32_32x32x16_bf16 v[48:63], v[220:223], v[144:147], v[48:63]
	ds_read_b128 v[212:215], v183 offset:28672
	v_mfma_f32_32x32x16_bf16 v[32:47], v[224:227], v[144:147], v[32:47]
	ds_read_b128 v[216:219], v182 offset:16384
	s_nop 5
	v_max3_f32 v194, v194, v80, v81
	v_max3_f32 v195, v195, v82, v83
	v_max3_f32 v194, v194, v84, v85
	v_max3_f32 v195, v195, v86, v87
	s_waitcnt lgkmcnt(5)
	v_mfma_f32_32x32x16_bf16 v[16:31], v[228:231], v[144:147], v[16:31]
	ds_read_b128 v[220:223], v182 offset:20480
	v_max3_f32 v194, v194, v88, v89
	v_max3_f32 v195, v195, v90, v91
	v_max3_f32 v194, v194, v92, v93
	v_max3_f32 v195, v195, v94, v95
	v_max_f32_e32 v194, v194, v195
	v_mov_b32_e32 v195, v194
	s_nop 1
	v_permlane32_swap_b32_e32 v194, v195
	v_max_f32_e32 v194, v194, v195
	v_cmp_lt_f32_e32 vcc, 0x41000000, v194
	v_mfma_f32_32x32x16_bf16 v[0:15], v[196:199], v[144:147], v[0:15]
	ds_read_b128 v[224:227], v182 offset:24576
	s_nop 1
	s_cmp_lg_u64 vcc, 0
	s_cbranch_scc1 .Lma_rareA_1
.Lma_backA_1:
	v_exp_f32_e32 v64, v64
	v_exp_f32_e32 v65, v65
	v_add_f32_e32 v192, v192, v64
	v_add_f32_e32 v193, v193, v65
	s_waitcnt lgkmcnt(5)
	v_mfma_f32_32x32x16_bf16 v[48:63], v[200:203], v[148:151], v[48:63]
	ds_read_b128 v[228:231], v182 offset:28672
	v_exp_f32_e32 v66, v66
	v_exp_f32_e32 v67, v67
	v_add_f32_e32 v192, v192, v66
	v_add_f32_e32 v193, v193, v67
	v_mfma_f32_32x32x16_bf16 v[32:47], v[204:207], v[148:151], v[32:47]
	ds_read_b128 v[196:199], v181 offset:16384
	v_exp_f32_e32 v68, v68
	v_exp_f32_e32 v69, v69
	v_add_f32_e32 v192, v192, v68
	v_add_f32_e32 v193, v193, v69
	s_waitcnt lgkmcnt(5)
	v_mfma_f32_32x32x16_bf16 v[16:31], v[208:211], v[148:151], v[16:31]
	ds_read_b128 v[200:203], v181 offset:20480
	v_exp_f32_e32 v70, v70
	v_exp_f32_e32 v71, v71
	v_add_f32_e32 v192, v192, v70
	v_add_f32_e32 v193, v193, v71
	v_cvt_pk_bf16_f32 v144, v64, v65
	v_cvt_pk_bf16_f32 v145, v66, v67
	v_mfma_f32_32x32x16_bf16 v[0:15], v[212:215], v[148:151], v[0:15]
	ds_read_b128 v[204:207], v181 offset:24576
	v_exp_f32_e32 v72, v72
	v_exp_f32_e32 v73, v73
	v_add_f32_e32 v192, v192, v72
	v_add_f32_e32 v193, v193, v73
	v_cvt_pk_bf16_f32 v146, v68, v69
	v_cvt_pk_bf16_f32 v147, v70, v71
	s_waitcnt lgkmcnt(5)
	v_mfma_f32_32x32x16_bf16 v[48:63], v[216:219], v[152:155], v[48:63]
	ds_read_b128 v[208:211], v181 offset:28672
	v_exp_f32_e32 v74, v74
	v_exp_f32_e32 v75, v75
	v_add_f32_e32 v192, v192, v74
	v_add_f32_e32 v193, v193, v75
	v_mfma_f32_32x32x16_bf16 v[32:47], v[220:223], v[152:155], v[32:47]
	v_exp_f32_e32 v76, v76
	v_exp_f32_e32 v77, v77
	v_add_f32_e32 v192, v192, v76
	v_add_f32_e32 v193, v193, v77
	s_waitcnt lgkmcnt(4)
	v_mfma_f32_32x32x16_bf16 v[16:31], v[224:227], v[152:155], v[16:31]
	v_exp_f32_e32 v78, v78
	v_exp_f32_e32 v79, v79
	v_add_f32_e32 v192, v192, v78
	v_add_f32_e32 v193, v193, v79
	v_mfma_f32_32x32x16_bf16 v[0:15], v[228:231], v[152:155], v[0:15]
	v_cvt_pk_bf16_f32 v148, v72, v73
	v_cvt_pk_bf16_f32 v149, v74, v75
	s_waitcnt lgkmcnt(2)
	v_mfma_f32_32x32x16_bf16 v[48:63], v[196:199], v[156:159], v[48:63]
	v_cvt_pk_bf16_f32 v150, v76, v77
	v_cvt_pk_bf16_f32 v151, v78, v79
	v_mfma_f32_32x32x16_bf16 v[32:47], v[200:203], v[156:159], v[32:47]
	s_waitcnt lgkmcnt(0)
	v_mfma_f32_32x32x16_bf16 v[16:31], v[204:207], v[156:159], v[16:31]
	v_mfma_f32_32x32x16_bf16 v[0:15], v[208:211], v[156:159], v[0:15]
	s_cmp_eq_u32 s44, 0
	s_cbranch_scc1 .Lma_skipB_1
	s_nop 11
	v_mul_f32_e32 v0, v177, v0
	v_mul_f32_e32 v1, v177, v1
	v_mul_f32_e32 v2, v177, v2
	v_mul_f32_e32 v3, v177, v3
	v_mul_f32_e32 v4, v177, v4
	v_mul_f32_e32 v5, v177, v5
	v_mul_f32_e32 v6, v177, v6
	v_mul_f32_e32 v7, v177, v7
	v_mul_f32_e32 v8, v177, v8
	v_mul_f32_e32 v9, v177, v9
	v_mul_f32_e32 v10, v177, v10
	v_mul_f32_e32 v11, v177, v11
	v_mul_f32_e32 v12, v177, v12
	v_mul_f32_e32 v13, v177, v13
	v_mul_f32_e32 v14, v177, v14
	v_mul_f32_e32 v15, v177, v15
	v_mul_f32_e32 v16, v177, v16
	v_mul_f32_e32 v17, v177, v17
	v_mul_f32_e32 v18, v177, v18
	v_mul_f32_e32 v19, v177, v19
	v_mul_f32_e32 v20, v177, v20
	v_mul_f32_e32 v21, v177, v21
	v_mul_f32_e32 v22, v177, v22
	v_mul_f32_e32 v23, v177, v23
	v_mul_f32_e32 v24, v177, v24
	v_mul_f32_e32 v25, v177, v25
	v_mul_f32_e32 v26, v177, v26
	v_mul_f32_e32 v27, v177, v27
	v_mul_f32_e32 v28, v177, v28
	v_mul_f32_e32 v29, v177, v29
	v_mul_f32_e32 v30, v177, v30
	v_mul_f32_e32 v31, v177, v31
	v_mul_f32_e32 v32, v177, v32
	v_mul_f32_e32 v33, v177, v33
	v_mul_f32_e32 v34, v177, v34
	v_mul_f32_e32 v35, v177, v35
	v_mul_f32_e32 v36, v177, v36
	v_mul_f32_e32 v37, v177, v37
	v_mul_f32_e32 v38, v177, v38
	v_mul_f32_e32 v39, v177, v39
	v_mul_f32_e32 v40, v177, v40
	v_mul_f32_e32 v41, v177, v41
	v_mul_f32_e32 v42, v177, v42
	v_mul_f32_e32 v43, v177, v43
	v_mul_f32_e32 v44, v177, v44
	v_mul_f32_e32 v45, v177, v45
	v_mul_f32_e32 v46, v177, v46
	v_mul_f32_e32 v47, v177, v47
	v_mul_f32_e32 v48, v177, v48
	v_mul_f32_e32 v49, v177, v49
	v_mul_f32_e32 v50, v177, v50
	v_mul_f32_e32 v51, v177, v51
	v_mul_f32_e32 v52, v177, v52
	v_mul_f32_e32 v53, v177, v53
	v_mul_f32_e32 v54, v177, v54
	v_mul_f32_e32 v55, v177, v55
	v_mul_f32_e32 v56, v177, v56
	v_mul_f32_e32 v57, v177, v57
	v_mul_f32_e32 v58, v177, v58
	v_mul_f32_e32 v59, v177, v59
	v_mul_f32_e32 v60, v177, v60
	v_mul_f32_e32 v61, v177, v61
	v_mul_f32_e32 v62, v177, v62
	v_mul_f32_e32 v63, v177, v63
	s_mov_b32 s44, 0
; #define LAS __attribute__((address_space(3)))
; #define MFMA32(a, b, c) __builtin_amdgcn_mfma_f32_32x32x16_bf16((a), (b), (c), 0, 0, 0)
;     constexpr int NKS = MODE == 0 ? 12 : 4, RB = MODE == 0 ? 384 : 256;
;     f32x16 z;
; #pragma unroll
;     for (int i = 0; i < 16; ++i) z[i] = 0.f;
; #pragma unroll
;     for (int ks = 0; ks < NKS; ++ks) {
;         const LAS unsigned char* p = kslot + ((ka ^ ((ks & 3) * 32)) + (ks >> 2) * 128);
;         const bf16x8 a0 = *(const LAS bf16x8*)p, a1 = *(const LAS bf16x8*)(p + 32 * RB);
;         if (ks == 0) { s0 = MFMA32(a0, qf[0], z); s1 = MFMA32(a1, qf[0], z); }
;         else { s0 = MFMA32(a0, qf[ks], s0); s1 = MFMA32(a1, qf[ks], s1); }
;     }
; }
; __device__ __forceinline__ float att_rowmax(const f32x16& s0, const f32x16& s1) {
;     float a = fmaxf(fmaxf(s0[0], s0[1]), s1[0]), b = fmaxf(fmaxf(s0[2], s0[3]), s1[1]);
;     a = fmaxf(fmaxf(a, s1[2]), s1[3]);
; #pragma unroll
;     for (int i = 4; i < 16; i += 4) { a = fmaxf(fmaxf(a, s0[i]), s0[i + 1]); b = fmaxf(fmaxf(b, s0[i + 2]), s0[i + 3]); a = fmaxf(fmaxf(a, s1[i]), s1[i + 1]); b = fmaxf(fmaxf(b, s1[i + 2]), s1[i + 3]); }
;     return xor32_max(fmaxf(a, b));
; }
; __device__ __forceinline__ void att_exp(f32x16& s0, f32x16& s1, float mhat, float& lrun, bf16x8 (&pf)[4]) {
;     float p0 = 0.f, p1 = 0.f;
; #pragma unroll
;     for (int i = 0; i < 16; ++i) { s0[i] = __builtin_amdgcn_exp2f(s0[i] - mhat); s1[i] = __builtin_amdgcn_exp2f(s1[i] - mhat); p0 += s0[i]; p1 += s1[i]; }
;     lrun += p0 + p1;
;     pf[0] = pack8((f32x4){s0[0], s0[1], s0[2], s0[3]}, (f32x4){s0[4], s0[5], s0[6], s0[7]});
;     pf[1] = pack8((f32x4){s0[8], s0[9], s0[10], s0[11]}, (f32x4){s0[12], s0[13], s0[14], s0[15]});
;     pf[2] = pack8((f32x4){s1[0], s1[1], s1[2], s1[3]}, (f32x4){s1[4], s1[5], s1[6], s1[7]});
;     pf[3] = pack8((f32x4){s1[8], s1[9], s1[10], s1[11]}, (f32x4){s1[12], s1[13], s1[14], s1[15]});
; }
; __device__ __forceinline__ void att_pv(f32x16 (&o)[4], const LAS unsigned char* vslot, int va, const bf16x8 (&pf)[4]) {
; #pragma unroll
;     for (int db = 0; db < 4; ++db)
; #pragma unroll
;         for (int kk = 0; kk < 4; ++kk) {
;             const bf16x8 v = *(const LAS bf16x8*)(vslot + ((va ^ (kk * 32)) + db * 4096));
;             o[db] = MFMA32(v, pf[kk], o[db]);
;         }
; }
.Lma_skipB_1:
	s_waitcnt vmcnt(5) lgkmcnt(0)
	s_barrier
	v_exp_f32_e32 v80, v80
	v_exp_f32_e32 v81, v81
	v_add_f32_e32 v192, v192, v80
	v_add_f32_e32 v193, v193, v81
	ds_read_b128 v[196:199], v163
	ds_read_b128 v[200:203], v165
	ds_read_b128 v[204:207], v167
	ds_read_b128 v[208:211], v180
	s_waitcnt lgkmcnt(2)
	v_mfma_f32_32x32x16_bf16 v[64:79], v[196:199], v[96:99], v[236:251]
	ds_read_b128 v[212:215], v163 offset:128
	ds_read_b128 v[216:219], v165 offset:128
	v_exp_f32_e32 v82, v82
	v_exp_f32_e32 v83, v83
	v_add_f32_e32 v192, v192, v82
	v_add_f32_e32 v193, v193, v83
	v_mfma_f32_32x32x16_bf16 v[64:79], v[200:203], v[100:103], v[64:79]
	ds_read_b128 v[220:223], v167 offset:128
	ds_read_b128 v[224:227], v180 offset:128
	v_exp_f32_e32 v84, v84
	v_exp_f32_e32 v85, v85
	v_add_f32_e32 v192, v192, v84
	v_add_f32_e32 v193, v193, v85
	s_waitcnt lgkmcnt(4)
	v_mfma_f32_32x32x16_bf16 v[64:79], v[204:207], v[104:107], v[64:79]
	ds_read_b128 v[228:231], v163 offset:256
	ds_read_b128 v[196:199], v165 offset:256
	v_exp_f32_e32 v86, v86
	v_exp_f32_e32 v87, v87
	v_add_f32_e32 v192, v192, v86
	v_add_f32_e32 v193, v193, v87
	v_mfma_f32_32x32x16_bf16 v[64:79], v[208:211], v[108:111], v[64:79]
	ds_read_b128 v[200:203], v167 offset:256
	v_exp_f32_e32 v88, v88
	v_exp_f32_e32 v89, v89
	v_add_f32_e32 v192, v192, v88
	v_add_f32_e32 v193, v193, v89
	s_waitcnt lgkmcnt(5)
	v_mfma_f32_32x32x16_bf16 v[64:79], v[212:215], v[112:115], v[64:79]
	ds_read_b128 v[204:207], v180 offset:256
	v_exp_f32_e32 v90, v90
	v_exp_f32_e32 v91, v91
	v_add_f32_e32 v192, v192, v90
	v_add_f32_e32 v193, v193, v91
	v_cvt_pk_bf16_f32 v152, v80, v81
	v_cvt_pk_bf16_f32 v153, v82, v83
	v_mfma_f32_32x32x16_bf16 v[64:79], v[216:219], v[116:119], v[64:79]
	ds_read_b128 v[208:211], v163 offset:12288
	v_exp_f32_e32 v92, v92
	v_exp_f32_e32 v93, v93
	v_add_f32_e32 v192, v192, v92
	v_add_f32_e32 v193, v193, v93
	v_cvt_pk_bf16_f32 v154, v84, v85
	v_cvt_pk_bf16_f32 v155, v86, v87
	s_waitcnt lgkmcnt(5)
	v_mfma_f32_32x32x16_bf16 v[64:79], v[220:223], v[120:123], v[64:79]
	ds_read_b128 v[212:215], v165 offset:12288
	v_exp_f32_e32 v94, v94
	v_exp_f32_e32 v95, v95
	v_add_f32_e32 v192, v192, v94
	v_add_f32_e32 v193, v193, v95
	v_mfma_f32_32x32x16_bf16 v[64:79], v[224:227], v[124:127], v[64:79]
	ds_read_b128 v[216:219], v167 offset:12288
	s_waitcnt lgkmcnt(5)
	v_mfma_f32_32x32x16_bf16 v[64:79], v[228:231], v[128:131], v[64:79]
	ds_read_b128 v[220:223], v180 offset:12288
	v_cvt_pk_bf16_f32 v156, v88, v89
	v_cvt_pk_bf16_f32 v157, v90, v91
	v_mfma_f32_32x32x16_bf16 v[64:79], v[196:199], v[132:135], v[64:79]
	ds_read_b128 v[224:227], v163 offset:12416
	v_cvt_pk_bf16_f32 v158, v92, v93
	v_cvt_pk_bf16_f32 v159, v94, v95
	s_waitcnt lgkmcnt(5)
	v_mfma_f32_32x32x16_bf16 v[64:79], v[200:203], v[136:139], v[64:79]
	ds_read_b128 v[228:231], v165 offset:12416
	v_mfma_f32_32x32x16_bf16 v[64:79], v[204:207], v[140:143], v[64:79]
	ds_read_b128 v[196:199], v167 offset:12416
	s_waitcnt lgkmcnt(5)
	v_mfma_f32_32x32x16_bf16 v[80:95], v[208:211], v[96:99], v[236:251]
	ds_read_b128 v[200:203], v180 offset:12416
	v_mfma_f32_32x32x16_bf16 v[80:95], v[212:215], v[100:103], v[80:95]
	ds_read_b128 v[204:207], v163 offset:12544
	s_add_i32 m0, s4, 0xc000
	s_nop 0
	global_load_lds_dwordx4 v[168:169], off
	s_waitcnt lgkmcnt(5)
	v_mfma_f32_32x32x16_bf16 v[80:95], v[216:219], v[104:107], v[80:95]
	ds_read_b128 v[208:211], v165 offset:12544
	s_add_i32 m0, s4, 0xe000
	s_nop 0
	global_load_lds_dwordx4 v[170:171], off
	v_mfma_f32_32x32x16_bf16 v[80:95], v[220:223], v[108:111], v[80:95]
	ds_read_b128 v[212:215], v167 offset:12544
	s_add_i32 m0, s4, 0x10000
	v_max3_f32 v194, v64, v65, v66
	global_load_lds_dwordx4 v[172:173], off
	s_waitcnt lgkmcnt(5)
	v_mfma_f32_32x32x16_bf16 v[80:95], v[224:227], v[112:115], v[80:95]
	ds_read_b128 v[216:219], v180 offset:12544
	v_lshl_add_u64 v[168:169], v[168:169], 0, v[186:187]
	v_lshl_add_u64 v[170:171], v[170:171], 0, v[188:189]
	v_lshl_add_u64 v[172:173], v[172:173], 0, v[190:191]
	v_max3_f32 v195, v67, v68, v69
	v_mfma_f32_32x32x16_bf16 v[80:95], v[228:231], v[116:119], v[80:95]
	ds_read_b128 v[220:223], v184 offset:32768
	s_add_i32 m0, s4, 0x16000
	v_max3_f32 v194, v194, v70, v71
	global_load_lds_dwordx4 v174, s[6:7]
	s_waitcnt lgkmcnt(5)
	v_mfma_f32_32x32x16_bf16 v[80:95], v[196:199], v[120:123], v[80:95]
	ds_read_b128 v[224:227], v184 offset:36864
	s_add_i32 m0, s4, 0x18000
	v_max3_f32 v195, v195, v72, v73
	global_load_lds_dwordx4 v175, s[6:7]
	v_mfma_f32_32x32x16_bf16 v[80:95], v[200:203], v[124:127], v[80:95]
	ds_read_b128 v[228:231], v184 offset:40960
	s_add_u32 s6, s6, 0x80
	s_addc_u32 s7, s7, 0
	v_max3_f32 v194, v194, v74, v75
	v_max3_f32 v195, v195, v76, v77
	v_max3_f32 v194, v194, v78, v79
	s_waitcnt lgkmcnt(5)
	v_mfma_f32_32x32x16_bf16 v[80:95], v[204:207], v[128:131], v[80:95]
	ds_read_b128 v[196:199], v184 offset:45056
	v_mfma_f32_32x32x16_bf16 v[80:95], v[208:211], v[132:135], v[80:95]
	ds_read_b128 v[200:203], v183 offset:32768
	s_waitcnt lgkmcnt(5)
	v_mfma_f32_32x32x16_bf16 v[80:95], v[212:215], v[136:139], v[80:95]
	ds_read_b128 v[204:207], v183 offset:36864
	v_mfma_f32_32x32x16_bf16 v[80:95], v[216:219], v[140:143], v[80:95]
	ds_read_b128 v[208:211], v183 offset:40960
	s_waitcnt lgkmcnt(5)
	v_mfma_f32_32x32x16_bf16 v[48:63], v[220:223], v[144:147], v[48:63]
	ds_read_b128 v[212:215], v183 offset:45056
	v_mfma_f32_32x32x16_bf16 v[32:47], v[224:227], v[144:147], v[32:47]
	ds_read_b128 v[216:219], v182 offset:32768
	s_nop 5
	v_max3_f32 v194, v194, v80, v81
	v_max3_f32 v195, v195, v82, v83
	v_max3_f32 v194, v194, v84, v85
	v_max3_f32 v195, v195, v86, v87
	s_waitcnt lgkmcnt(5)
	v_mfma_f32_32x32x16_bf16 v[16:31], v[228:231], v[144:147], v[16:31]
	ds_read_b128 v[220:223], v182 offset:36864
	v_max3_f32 v194, v194, v88, v89
	v_max3_f32 v195, v195, v90, v91
	v_max3_f32 v194, v194, v92, v93
	v_max3_f32 v195, v195, v94, v95
	v_max_f32_e32 v194, v194, v195
	v_mov_b32_e32 v195, v194
	s_nop 1
	v_permlane32_swap_b32_e32 v194, v195
	v_max_f32_e32 v194, v194, v195
	v_cmp_lt_f32_e32 vcc, 0x41000000, v194
	v_mfma_f32_32x32x16_bf16 v[0:15], v[196:199], v[144:147], v[0:15]
	ds_read_b128 v[224:227], v182 offset:40960
	s_nop 1
	s_cmp_lg_u64 vcc, 0
	s_cbranch_scc1 .Lma_rareA_2
; #define LAS __attribute__((address_space(3)))
; #define MFMA32(a, b, c) __builtin_amdgcn_mfma_f32_32x32x16_bf16((a), (b), (c), 0, 0, 0)
; __device__ __forceinline__ void att_exp(f32x16& s0, f32x16& s1, float mhat, float& lrun, bf16x8 (&pf)[4]) {
;     float p0 = 0.f, p1 = 0.f;
; #pragma unroll
;     for (int i = 0; i < 16; ++i) { s0[i] = __builtin_amdgcn_exp2f(s0[i] - mhat); s1[i] = __builtin_amdgcn_exp2f(s1[i] - mhat); p0 += s0[i]; p1 += s1[i]; }
;     lrun += p0 + p1;
;     pf[0] = pack8((f32x4){s0[0], s0[1], s0[2], s0[3]}, (f32x4){s0[4], s0[5], s0[6], s0[7]});
;     pf[1] = pack8((f32x4){s0[8], s0[9], s0[10], s0[11]}, (f32x4){s0[12], s0[13], s0[14], s0[15]});
;     pf[2] = pack8((f32x4){s1[0], s1[1], s1[2], s1[3]}, (f32x4){s1[4], s1[5], s1[6], s1[7]});
;     pf[3] = pack8((f32x4){s1[8], s1[9], s1[10], s1[11]}, (f32x4){s1[12], s1[13], s1[14], s1[15]});
; }
; __device__ __forceinline__ void att_pv(f32x16 (&o)[4], const LAS unsigned char* vslot, int va, const bf16x8 (&pf)[4]) {
; #pragma unroll
;     for (int db = 0; db < 4; ++db)
; #pragma unroll
;         for (int kk = 0; kk < 4; ++kk) {
;             const bf16x8 v = *(const LAS bf16x8*)(vslot + ((va ^ (kk * 32)) + db * 4096));
;             o[db] = MFMA32(v, pf[kk], o[db]);
;         }
; }
; template <int MODE>
; __device__ __forceinline__ void attn_phase(LAS unsigned char* lds, const bf16* Qp, const bf16* Kp, const bf16* KPEp, const bf16* Vtp, bf16* CAT, float lam, int vcu, int G) {
;     ...
;         for (int i = 0; i < 128; ++i) {
;             att_qk<MODE>(S0, S1, lds + kr, ka, qf);
;             const float rm = att_rowmax(S0, S1);
;             if (i == 0) mhat = rm;
;             else if (__any(rm - mhat > THR)) { const float dl = fmaxf(rm - mhat, 0.f), f = __builtin_amdgcn_exp2f(-dl); lrun *= f; mhat += dl; fpend = f; havepend = true; }
;             if (i > 0) att_pv(o, vring + vr, va, pf);
;             att_exp(S0, S1, mhat, lrun, pf);
;             ATT_RESC_O();
;             ATT_DMA_K(kw); ATT_DMA_V(vw);
;             if (i + 2 < 127) ATT_ADV_K();
;             if (i + 1 < 127) ATT_ADV_V();
;             kr = (kr == 2 * KB) ? 0 : kr + KB; kw = (kw == 2 * KB) ? 0 : kw + KB;
;             vr = (vr == 2 * VB) ? 0 : vr + VB; vw = (vw == 2 * VB) ? 0 : vw + VB;
;             asm volatile("s_waitcnt vmcnt(5) lgkmcnt(0)\n\ts_barrier" ::: "memory");
.Lma_backA_2:
	v_exp_f32_e32 v64, v64
	v_exp_f32_e32 v65, v65
	v_add_f32_e32 v192, v192, v64
	v_add_f32_e32 v193, v193, v65
	s_waitcnt lgkmcnt(5)
	v_mfma_f32_32x32x16_bf16 v[48:63], v[200:203], v[148:151], v[48:63]
	ds_read_b128 v[228:231], v182 offset:45056
	v_exp_f32_e32 v66, v66
	v_exp_f32_e32 v67, v67
	v_add_f32_e32 v192, v192, v66
	v_add_f32_e32 v193, v193, v67
	v_mfma_f32_32x32x16_bf16 v[32:47], v[204:207], v[148:151], v[32:47]
	ds_read_b128 v[196:199], v181 offset:32768
	v_exp_f32_e32 v68, v68
	v_exp_f32_e32 v69, v69
	v_add_f32_e32 v192, v192, v68
	v_add_f32_e32 v193, v193, v69
	s_waitcnt lgkmcnt(5)
	v_mfma_f32_32x32x16_bf16 v[16:31], v[208:211], v[148:151], v[16:31]
	ds_read_b128 v[200:203], v181 offset:36864
	v_exp_f32_e32 v70, v70
	v_exp_f32_e32 v71, v71
	v_add_f32_e32 v192, v192, v70
	v_add_f32_e32 v193, v193, v71
	v_cvt_pk_bf16_f32 v144, v64, v65
	v_cvt_pk_bf16_f32 v145, v66, v67
	v_mfma_f32_32x32x16_bf16 v[0:15], v[212:215], v[148:151], v[0:15]
	ds_read_b128 v[204:207], v181 offset:40960
	v_exp_f32_e32 v72, v72
	v_exp_f32_e32 v73, v73
	v_add_f32_e32 v192, v192, v72
	v_add_f32_e32 v193, v193, v73
	v_cvt_pk_bf16_f32 v146, v68, v69
	v_cvt_pk_bf16_f32 v147, v70, v71
	s_waitcnt lgkmcnt(5)
	v_mfma_f32_32x32x16_bf16 v[48:63], v[216:219], v[152:155], v[48:63]
	ds_read_b128 v[208:211], v181 offset:45056
	v_exp_f32_e32 v74, v74
	v_exp_f32_e32 v75, v75
	v_add_f32_e32 v192, v192, v74
	v_add_f32_e32 v193, v193, v75
	v_mfma_f32_32x32x16_bf16 v[32:47], v[220:223], v[152:155], v[32:47]
	v_exp_f32_e32 v76, v76
	v_exp_f32_e32 v77, v77
	v_add_f32_e32 v192, v192, v76
	v_add_f32_e32 v193, v193, v77
	s_waitcnt lgkmcnt(4)
	v_mfma_f32_32x32x16_bf16 v[16:31], v[224:227], v[152:155], v[16:31]
	v_exp_f32_e32 v78, v78
	v_exp_f32_e32 v79, v79
	v_add_f32_e32 v192, v192, v78
	v_add_f32_e32 v193, v193, v79
	v_mfma_f32_32x32x16_bf16 v[0:15], v[228:231], v[152:155], v[0:15]
	v_cvt_pk_bf16_f32 v148, v72, v73
	v_cvt_pk_bf16_f32 v149, v74, v75
	s_waitcnt lgkmcnt(2)
	v_mfma_f32_32x32x16_bf16 v[48:63], v[196:199], v[156:159], v[48:63]
	v_cvt_pk_bf16_f32 v150, v76, v77
	v_cvt_pk_bf16_f32 v151, v78, v79
	v_mfma_f32_32x32x16_bf16 v[32:47], v[200:203], v[156:159], v[32:47]
	s_waitcnt lgkmcnt(0)
	v_mfma_f32_32x32x16_bf16 v[16:31], v[204:207], v[156:159], v[16:31]
	v_mfma_f32_32x32x16_bf16 v[0:15], v[208:211], v[156:159], v[0:15]
	s_cmp_eq_u32 s44, 0
	s_cbranch_scc1 .Lma_skipB_2
	s_nop 11
	v_mul_f32_e32 v0, v177, v0
	v_mul_f32_e32 v1, v177, v1
	v_mul_f32_e32 v2, v177, v2
	v_mul_f32_e32 v3, v177, v3
	v_mul_f32_e32 v4, v177, v4
	v_mul_f32_e32 v5, v177, v5
	v_mul_f32_e32 v6, v177, v6
	v_mul_f32_e32 v7, v177, v7
	v_mul_f32_e32 v8, v177, v8
	v_mul_f32_e32 v9, v177, v9
	v_mul_f32_e32 v10, v177, v10
	v_mul_f32_e32 v11, v177, v11
	v_mul_f32_e32 v12, v177, v12
	v_mul_f32_e32 v13, v177, v13
	v_mul_f32_e32 v14, v177, v14
	v_mul_f32_e32 v15, v177, v15
	v_mul_f32_e32 v16, v177, v16
	v_mul_f32_e32 v17, v177, v17
	v_mul_f32_e32 v18, v177, v18
	v_mul_f32_e32 v19, v177, v19
	v_mul_f32_e32 v20, v177, v20
	v_mul_f32_e32 v21, v177, v21
	v_mul_f32_e32 v22, v177, v22
	v_mul_f32_e32 v23, v177, v23
	v_mul_f32_e32 v24, v177, v24
	v_mul_f32_e32 v25, v177, v25
	v_mul_f32_e32 v26, v177, v26
	v_mul_f32_e32 v27, v177, v27
	v_mul_f32_e32 v28, v177, v28
	v_mul_f32_e32 v29, v177, v29
	v_mul_f32_e32 v30, v177, v30
	v_mul_f32_e32 v31, v177, v31
	v_mul_f32_e32 v32, v177, v32
	v_mul_f32_e32 v33, v177, v33
	v_mul_f32_e32 v34, v177, v34
	v_mul_f32_e32 v35, v177, v35
	v_mul_f32_e32 v36, v177, v36
	v_mul_f32_e32 v37, v177, v37
	v_mul_f32_e32 v38, v177, v38
	v_mul_f32_e32 v39, v177, v39
	v_mul_f32_e32 v40, v177, v40
	v_mul_f32_e32 v41, v177, v41
	v_mul_f32_e32 v42, v177, v42
	v_mul_f32_e32 v43, v177, v43
	v_mul_f32_e32 v44, v177, v44
	v_mul_f32_e32 v45, v177, v45
	v_mul_f32_e32 v46, v177, v46
	v_mul_f32_e32 v47, v177, v47
	v_mul_f32_e32 v48, v177, v48
	v_mul_f32_e32 v49, v177, v49
	v_mul_f32_e32 v50, v177, v50
	v_mul_f32_e32 v51, v177, v51
	v_mul_f32_e32 v52, v177, v52
	v_mul_f32_e32 v53, v177, v53
	v_mul_f32_e32 v54, v177, v54
	v_mul_f32_e32 v55, v177, v55
	v_mul_f32_e32 v56, v177, v56
	v_mul_f32_e32 v57, v177, v57
	v_mul_f32_e32 v58, v177, v58
	v_mul_f32_e32 v59, v177, v59
	v_mul_f32_e32 v60, v177, v60
	v_mul_f32_e32 v61, v177, v61
	v_mul_f32_e32 v62, v177, v62
	v_mul_f32_e32 v63, v177, v63
	s_mov_b32 s44, 0
; #define LAS __attribute__((address_space(3)))
;     constexpr int NKS = MODE == 0 ? 12 : 4, RB = MODE == 0 ? 384 : 256;
;     f32x16 z;
; #pragma unroll
;     for (int i = 0; i < 16; ++i) z[i] = 0.f;
; #pragma unroll
;     for (int ks = 0; ks < NKS; ++ks) {
;         const LAS unsigned char* p = kslot + ((ka ^ ((ks & 3) * 32)) + (ks >> 2) * 128);
;         const bf16x8 a0 = *(const LAS bf16x8*)p, a1 = *(const LAS bf16x8*)(p + 32 * RB);
;         if (ks == 0) { s0 = MFMA32(a0, qf[0], z); s1 = MFMA32(a1, qf[0], z); }
;         else { s0 = MFMA32(a0, qf[ks], s0); s1 = MFMA32(a1, qf[ks], s1); }
;     }
; }
; __device__ __forceinline__ float att_rowmax(const f32x16& s0, const f32x16& s1) {
;     float a = fmaxf(fmaxf(s0[0], s0[1]), s1[0]), b = fmaxf(fmaxf(s0[2], s0[3]), s1[1]);
;     a = fmaxf(fmaxf(a, s1[2]), s1[3]);
; #pragma unroll
;     for (int i = 4; i < 16; i += 4) { a = fmaxf(fmaxf(a, s0[i]), s0[i + 1]); b = fmaxf(fmaxf(b, s0[i + 2]), s0[i + 3]); a = fmaxf(fmaxf(a, s1[i]), s1[i + 1]); b = fmaxf(fmaxf(b, s1[i + 2]), s1[i + 3]); }
;     return xor32_max(fmaxf(a, b));
; }
; __device__ __forceinline__ void att_exp(f32x16& s0, f32x16& s1, float mhat, float& lrun, bf16x8 (&pf)[4]) {
;     float p0 = 0.f, p1 = 0.f;
; #pragma unroll
; template <int MODE>
; __device__ __forceinline__ void attn_phase(LAS unsigned char* lds, const bf16* Qp, const bf16* Kp, const bf16* KPEp, const bf16* Vtp, bf16* CAT, float lam, int vcu, int G) {
;     ...
;         for (int i = 0; i < 128; ++i) {
;             att_qk<MODE>(S0, S1, lds + kr, ka, qf);
;             const float rm = att_rowmax(S0, S1);
;             if (i == 0) mhat = rm;
;             else if (__any(rm - mhat > THR)) { const float dl = fmaxf(rm - mhat, 0.f), f = __builtin_amdgcn_exp2f(-dl); lrun *= f; mhat += dl; fpend = f; havepend = true; }
;             if (i > 0) att_pv(o, vring + vr, va, pf);
;             att_exp(S0, S1, mhat, lrun, pf);
;             ATT_RESC_O();
;             ATT_DMA_K(kw); ATT_DMA_V(vw);
;             if (i + 2 < 127) ATT_ADV_K();
;             if (i + 1 < 127) ATT_ADV_V();
;             kr = (kr == 2 * KB) ? 0 : kr + KB; kw = (kw == 2 * KB) ? 0 : kw + KB;
;             vr = (vr == 2 * VB) ? 0 : vr + VB; vw = (vw == 2 * VB) ? 0 : vw + VB;
;             asm volatile("s_waitcnt vmcnt(5) lgkmcnt(0)\n\ts_barrier" ::: "memory");
.Lma_skipB_2:
	s_add_i32 s55, s55, 1
	s_cmpk_lt_u32 s55, 42
	s_waitcnt vmcnt(5) lgkmcnt(0)
	s_barrier
	s_cbranch_scc1 .Lma_loop
	v_exp_f32_e32 v80, v80
	v_exp_f32_e32 v81, v81
	v_add_f32_e32 v192, v192, v80
	v_add_f32_e32 v193, v193, v81
	ds_read_b128 v[196:199], v163 offset:24576
	ds_read_b128 v[200:203], v165 offset:24576
	ds_read_b128 v[204:207], v167 offset:24576
	ds_read_b128 v[208:211], v180 offset:24576
	s_waitcnt lgkmcnt(2)
	v_mfma_f32_32x32x16_bf16 v[64:79], v[196:199], v[96:99], v[236:251]
	ds_read_b128 v[212:215], v163 offset:24704
	ds_read_b128 v[216:219], v165 offset:24704
	v_exp_f32_e32 v82, v82
	v_exp_f32_e32 v83, v83
	v_add_f32_e32 v192, v192, v82
	v_add_f32_e32 v193, v193, v83
	v_mfma_f32_32x32x16_bf16 v[64:79], v[200:203], v[100:103], v[64:79]
	ds_read_b128 v[220:223], v167 offset:24704
	ds_read_b128 v[224:227], v180 offset:24704
	v_exp_f32_e32 v84, v84
	v_exp_f32_e32 v85, v85
	v_add_f32_e32 v192, v192, v84
	v_add_f32_e32 v193, v193, v85
	s_waitcnt lgkmcnt(4)
	v_mfma_f32_32x32x16_bf16 v[64:79], v[204:207], v[104:107], v[64:79]
	ds_read_b128 v[228:231], v163 offset:24832
	ds_read_b128 v[196:199], v165 offset:24832
	v_exp_f32_e32 v86, v86
	v_exp_f32_e32 v87, v87
	v_add_f32_e32 v192, v192, v86
	v_add_f32_e32 v193, v193, v87
	v_mfma_f32_32x32x16_bf16 v[64:79], v[208:211], v[108:111], v[64:79]
	ds_read_b128 v[200:203], v167 offset:24832
	v_exp_f32_e32 v88, v88
	v_exp_f32_e32 v89, v89
	v_add_f32_e32 v192, v192, v88
	v_add_f32_e32 v193, v193, v89
	s_waitcnt lgkmcnt(5)
	v_mfma_f32_32x32x16_bf16 v[64:79], v[212:215], v[112:115], v[64:79]
	ds_read_b128 v[204:207], v180 offset:24832
	v_exp_f32_e32 v90, v90
	v_exp_f32_e32 v91, v91
	v_add_f32_e32 v192, v192, v90
	v_add_f32_e32 v193, v193, v91
	v_cvt_pk_bf16_f32 v152, v80, v81
	v_cvt_pk_bf16_f32 v153, v82, v83
	v_mfma_f32_32x32x16_bf16 v[64:79], v[216:219], v[116:119], v[64:79]
	ds_read_b128 v[208:211], v163 offset:36864
	v_exp_f32_e32 v92, v92
	v_exp_f32_e32 v93, v93
	v_add_f32_e32 v192, v192, v92
	v_add_f32_e32 v193, v193, v93
	v_cvt_pk_bf16_f32 v154, v84, v85
	v_cvt_pk_bf16_f32 v155, v86, v87
	s_waitcnt lgkmcnt(5)
	v_mfma_f32_32x32x16_bf16 v[64:79], v[220:223], v[120:123], v[64:79]
	ds_read_b128 v[212:215], v165 offset:36864
	v_exp_f32_e32 v94, v94
	v_exp_f32_e32 v95, v95
	v_add_f32_e32 v192, v192, v94
	v_add_f32_e32 v193, v193, v95
	v_mfma_f32_32x32x16_bf16 v[64:79], v[224:227], v[124:127], v[64:79]
	ds_read_b128 v[216:219], v167 offset:36864
	s_waitcnt lgkmcnt(5)
	v_mfma_f32_32x32x16_bf16 v[64:79], v[228:231], v[128:131], v[64:79]
	ds_read_b128 v[220:223], v180 offset:36864
	v_cvt_pk_bf16_f32 v156, v88, v89
	v_cvt_pk_bf16_f32 v157, v90, v91
	v_mfma_f32_32x32x16_bf16 v[64:79], v[196:199], v[132:135], v[64:79]
	ds_read_b128 v[224:227], v163 offset:36992
	v_cvt_pk_bf16_f32 v158, v92, v93
	v_cvt_pk_bf16_f32 v159, v94, v95
	s_waitcnt lgkmcnt(5)
	v_mfma_f32_32x32x16_bf16 v[64:79], v[200:203], v[136:139], v[64:79]
	ds_read_b128 v[228:231], v165 offset:36992
	v_mfma_f32_32x32x16_bf16 v[64:79], v[204:207], v[140:143], v[64:79]
	ds_read_b128 v[196:199], v167 offset:36992
	s_waitcnt lgkmcnt(5)
	v_mfma_f32_32x32x16_bf16 v[80:95], v[208:211], v[96:99], v[236:251]
	ds_read_b128 v[200:203], v180 offset:36992
	v_mfma_f32_32x32x16_bf16 v[80:95], v[212:215], v[100:103], v[80:95]
	ds_read_b128 v[204:207], v163 offset:37120
	s_add_i32 m0, s4, 0x0
	s_nop 0
	global_load_lds_dwordx4 v[168:169], off
	s_waitcnt lgkmcnt(5)
	v_mfma_f32_32x32x16_bf16 v[80:95], v[216:219], v[104:107], v[80:95]
	ds_read_b128 v[208:211], v165 offset:37120
	s_add_i32 m0, s4, 0x2000
	s_nop 0
	global_load_lds_dwordx4 v[170:171], off
	v_mfma_f32_32x32x16_bf16 v[80:95], v[220:223], v[108:111], v[80:95]
	ds_read_b128 v[212:215], v167 offset:37120
	s_add_i32 m0, s4, 0x4000
	v_max3_f32 v194, v64, v65, v66
	global_load_lds_dwordx4 v[172:173], off
	s_waitcnt lgkmcnt(5)
	v_mfma_f32_32x32x16_bf16 v[80:95], v[224:227], v[112:115], v[80:95]
	ds_read_b128 v[216:219], v180 offset:37120
	v_lshl_add_u64 v[168:169], v[168:169], 0, v[186:187]
	v_lshl_add_u64 v[170:171], v[170:171], 0, v[188:189]
	v_lshl_add_u64 v[172:173], v[172:173], 0, v[190:191]
	v_max3_f32 v195, v67, v68, v69
	v_mfma_f32_32x32x16_bf16 v[80:95], v[228:231], v[116:119], v[80:95]
	ds_read_b128 v[220:223], v184
	s_add_i32 m0, s4, 0x1a000
	v_max3_f32 v194, v194, v70, v71
	global_load_lds_dwordx4 v174, s[6:7]
	s_waitcnt lgkmcnt(5)
	v_mfma_f32_32x32x16_bf16 v[80:95], v[196:199], v[120:123], v[80:95]
	ds_read_b128 v[224:227], v184 offset:4096
	s_add_i32 m0, s4, 0x1c000
	v_max3_f32 v195, v195, v72, v73
	global_load_lds_dwordx4 v175, s[6:7]
	v_mfma_f32_32x32x16_bf16 v[80:95], v[200:203], v[124:127], v[80:95]
	ds_read_b128 v[228:231], v184 offset:8192
	s_add_u32 s6, s6, 0x80
	s_addc_u32 s7, s7, 0
	v_max3_f32 v194, v194, v74, v75
	v_max3_f32 v195, v195, v76, v77
	v_max3_f32 v194, v194, v78, v79
	s_waitcnt lgkmcnt(5)
	v_mfma_f32_32x32x16_bf16 v[80:95], v[204:207], v[128:131], v[80:95]
	ds_read_b128 v[196:199], v184 offset:12288
	v_mfma_f32_32x32x16_bf16 v[80:95], v[208:211], v[132:135], v[80:95]
	ds_read_b128 v[200:203], v183
	s_waitcnt lgkmcnt(5)
	v_mfma_f32_32x32x16_bf16 v[80:95], v[212:215], v[136:139], v[80:95]
	ds_read_b128 v[204:207], v183 offset:4096
	v_mfma_f32_32x32x16_bf16 v[80:95], v[216:219], v[140:143], v[80:95]
	ds_read_b128 v[208:211], v183 offset:8192
	s_waitcnt lgkmcnt(5)
	v_mfma_f32_32x32x16_bf16 v[48:63], v[220:223], v[144:147], v[48:63]
	ds_read_b128 v[212:215], v183 offset:12288
	v_mfma_f32_32x32x16_bf16 v[32:47], v[224:227], v[144:147], v[32:47]
	ds_read_b128 v[216:219], v182
	s_nop 5
	v_max3_f32 v194, v194, v80, v81
	v_max3_f32 v195, v195, v82, v83
	v_max3_f32 v194, v194, v84, v85
	v_max3_f32 v195, v195, v86, v87
	s_waitcnt lgkmcnt(5)
	v_mfma_f32_32x32x16_bf16 v[16:31], v[228:231], v[144:147], v[16:31]
	ds_read_b128 v[220:223], v182 offset:4096
	v_max3_f32 v194, v194, v88, v89
	v_max3_f32 v195, v195, v90, v91
	v_max3_f32 v194, v194, v92, v93
	v_max3_f32 v195, v195, v94, v95
	v_max_f32_e32 v194, v194, v195
	v_mov_b32_e32 v195, v194
	s_nop 1
	v_permlane32_swap_b32_e32 v194, v195
	v_max_f32_e32 v194, v194, v195
	v_cmp_lt_f32_e32 vcc, 0x41000000, v194
	v_mfma_f32_32x32x16_bf16 v[0:15], v[196:199], v[144:147], v[0:15]
	ds_read_b128 v[224:227], v182 offset:8192
	s_nop 1
	s_cmp_lg_u64 vcc, 0
	s_cbranch_scc1 .Lma_rareA_3

; __device__ __forceinline__ float xor32_add(float v) { auto rr = __builtin_amdgcn_permlane32_swap(__float_as_uint(v), __float_as_uint(v), false, false); return __uint_as_float(rr[0]) + __uint_as_float(rr[1]); }
; #define ATT_DMA_K(slotoff) do { _Pragma("unroll") for (int n = 0; n < NKI; ++n) glds16(kp[n], (unsigned)__builtin_amdgcn_readfirstlane(kdma + (slotoff) + n * 8192)); } while (0)
; #define ATT_DMA_V(slotoff) do { _Pragma("unroll") for (int n = 0; n < 2; ++n) glds16(vp[n], (unsigned)__builtin_amdgcn_readfirstlane(vdma + (slotoff) + n * 8192)); } while (0)
; #define ATT_ADV_K() do { _Pragma("unroll") for (int n = 0; n < NKI; ++n) kp[n] += kadv[n]; } while (0)
; #define ATT_ADV_V() do { _Pragma("unroll") for (int n = 0; n < 2; ++n) vp[n] += 64; } while (0)
; #define ATT_RESC_O() do { if (havepend) { _Pragma("unroll") for (int db = 0; db < 4; ++db) _Pragma("unroll") for (int i = 0; i < 16; ++i) o[db][i] *= fpend; havepend = false; } } while (0)
; template <int MODE>
; __device__ __forceinline__ void attn_phase(LAS unsigned char* lds, const bf16* Qp, const bf16* Kp, const bf16* KPEp, const bf16* Vtp, bf16* CAT, float lam, int vcu, int G) {
;     ...
;             else if (__any(rm - mhat > THR)) { const float dl = fmaxf(rm - mhat, 0.f), f = __builtin_amdgcn_exp2f(-dl); lrun *= f; mhat += dl; fpend = f; havepend = true; }
;             if (i > 0) att_pv(o, vring + vr, va, pf);
;             att_exp(S0, S1, mhat, lrun, pf);
;             ATT_RESC_O();
;             ATT_DMA_K(kw); ATT_DMA_V(vw);
;             if (i + 2 < 127) ATT_ADV_K();
;             if (i + 1 < 127) ATT_ADV_V();
;             kr = (kr == 2 * KB) ? 0 : kr + KB; kw = (kw == 2 * KB) ? 0 : kw + KB;
;             vr = (vr == 2 * VB) ? 0 : vr + VB; vw = (vw == 2 * VB) ? 0 : vw + VB;
;             asm volatile("s_waitcnt vmcnt(5) lgkmcnt(0)\n\ts_barrier" ::: "memory");
;         }
;         }
;         att_pv(o, vring + vr, va, pf);
;         asm volatile("s_waitcnt vmcnt(0) lgkmcnt(0)\n\ts_barrier" ::: "memory");
;     ...
;         lrun = xor32_add(lrun);
.Lma_skipB_3:
	s_waitcnt vmcnt(5) lgkmcnt(0)
	s_barrier
	v_exp_f32_e32 v80, v80
	v_exp_f32_e32 v81, v81
	v_add_f32_e32 v192, v192, v80
	v_add_f32_e32 v193, v193, v81
	v_exp_f32_e32 v82, v82
	v_exp_f32_e32 v83, v83
	v_add_f32_e32 v192, v192, v82
	v_add_f32_e32 v193, v193, v83
	v_exp_f32_e32 v84, v84
	v_exp_f32_e32 v85, v85
	v_add_f32_e32 v192, v192, v84
	v_add_f32_e32 v193, v193, v85
	v_exp_f32_e32 v86, v86
	v_exp_f32_e32 v87, v87
	v_add_f32_e32 v192, v192, v86
	v_add_f32_e32 v193, v193, v87
	v_exp_f32_e32 v88, v88
	v_exp_f32_e32 v89, v89
	v_add_f32_e32 v192, v192, v88
	v_add_f32_e32 v193, v193, v89
	v_exp_f32_e32 v90, v90
	v_exp_f32_e32 v91, v91
	v_add_f32_e32 v192, v192, v90
	v_add_f32_e32 v193, v193, v91
	v_exp_f32_e32 v92, v92
	v_exp_f32_e32 v93, v93
	v_add_f32_e32 v192, v192, v92
	v_add_f32_e32 v193, v193, v93
	v_exp_f32_e32 v94, v94
	v_exp_f32_e32 v95, v95
	v_add_f32_e32 v192, v192, v94
	v_add_f32_e32 v193, v193, v95
	v_cvt_pk_bf16_f32 v152, v80, v81
	v_cvt_pk_bf16_f32 v153, v82, v83
	v_cvt_pk_bf16_f32 v154, v84, v85
	v_cvt_pk_bf16_f32 v155, v86, v87
	v_cvt_pk_bf16_f32 v156, v88, v89
	v_cvt_pk_bf16_f32 v157, v90, v91
	v_cvt_pk_bf16_f32 v158, v92, v93
	v_cvt_pk_bf16_f32 v159, v94, v95
	s_nop 1
	ds_read_b128 v[196:199], v184 offset:16384
	ds_read_b128 v[200:203], v184 offset:20480
	ds_read_b128 v[204:207], v184 offset:24576
	ds_read_b128 v[208:211], v184 offset:28672
	s_waitcnt lgkmcnt(2)
	v_mfma_f32_32x32x16_bf16 v[48:63], v[196:199], v[144:147], v[48:63]
	ds_read_b128 v[212:215], v183 offset:16384
	ds_read_b128 v[216:219], v183 offset:20480
	v_mfma_f32_32x32x16_bf16 v[32:47], v[200:203], v[144:147], v[32:47]
	ds_read_b128 v[220:223], v183 offset:24576
	ds_read_b128 v[224:227], v183 offset:28672
	s_waitcnt lgkmcnt(4)
	v_mfma_f32_32x32x16_bf16 v[16:31], v[204:207], v[144:147], v[16:31]
	ds_read_b128 v[228:231], v182 offset:16384
	ds_read_b128 v[196:199], v182 offset:20480
	v_mfma_f32_32x32x16_bf16 v[0:15], v[208:211], v[144:147], v[0:15]
	ds_read_b128 v[200:203], v182 offset:24576
	s_waitcnt lgkmcnt(5)
	v_mfma_f32_32x32x16_bf16 v[48:63], v[212:215], v[148:151], v[48:63]
	ds_read_b128 v[204:207], v182 offset:28672
	v_mfma_f32_32x32x16_bf16 v[32:47], v[216:219], v[148:151], v[32:47]
	ds_read_b128 v[208:211], v181 offset:16384
	s_waitcnt lgkmcnt(5)
	v_mfma_f32_32x32x16_bf16 v[16:31], v[220:223], v[148:151], v[16:31]
	ds_read_b128 v[212:215], v181 offset:20480
	v_mfma_f32_32x32x16_bf16 v[0:15], v[224:227], v[148:151], v[0:15]
	ds_read_b128 v[216:219], v181 offset:24576
	s_waitcnt lgkmcnt(5)
	v_mfma_f32_32x32x16_bf16 v[48:63], v[228:231], v[152:155], v[48:63]
	ds_read_b128 v[220:223], v181 offset:28672
	v_mfma_f32_32x32x16_bf16 v[32:47], v[196:199], v[152:155], v[32:47]
	s_waitcnt lgkmcnt(4)
	v_mfma_f32_32x32x16_bf16 v[16:31], v[200:203], v[152:155], v[16:31]
	v_mfma_f32_32x32x16_bf16 v[0:15], v[204:207], v[152:155], v[0:15]
	s_waitcnt lgkmcnt(2)
	v_mfma_f32_32x32x16_bf16 v[48:63], v[208:211], v[156:159], v[48:63]
	v_mfma_f32_32x32x16_bf16 v[32:47], v[212:215], v[156:159], v[32:47]
	s_waitcnt lgkmcnt(0)
	v_mfma_f32_32x32x16_bf16 v[16:31], v[216:219], v[156:159], v[16:31]
	v_mfma_f32_32x32x16_bf16 v[0:15], v[220:223], v[156:159], v[0:15]
	s_waitcnt vmcnt(0) lgkmcnt(0)
	s_barrier
	v_add_f32_e32 v185, v192, v193
	v_lshlrev_b32_e32 v232, 3, v179
	s_mov_b32 m0, s45
	s_lshl_b32 s36, s54, 1
	s_add_i32 s17, s17, s52
	s_cmpk_gt_i32 s17, 0x1ff
	s_branch .Lma_epi
.Lma_rareA_0:
	v_max_f32_e32 v176, 0, v194
	v_exp_f32_e64 v177, -v176
	s_mov_b32 s44, 1
	v_sub_f32_e32 v236, v236, v176
	v_sub_f32_e32 v237, v237, v176
	v_sub_f32_e32 v238, v238, v176
	v_sub_f32_e32 v239, v239, v176
	v_sub_f32_e32 v240, v240, v176
	v_sub_f32_e32 v241, v241, v176
	v_sub_f32_e32 v242, v242, v176
	v_sub_f32_e32 v243, v243, v176
	v_sub_f32_e32 v244, v244, v176
	v_sub_f32_e32 v245, v245, v176
	v_sub_f32_e32 v246, v246, v176
	v_sub_f32_e32 v247, v247, v176
	v_sub_f32_e32 v248, v248, v176
	v_sub_f32_e32 v249, v249, v176
	v_sub_f32_e32 v250, v250, v176
	v_sub_f32_e32 v251, v251, v176
	v_sub_f32_e32 v64, v64, v176
	v_sub_f32_e32 v65, v65, v176
	v_sub_f32_e32 v66, v66, v176
	v_sub_f32_e32 v67, v67, v176
	v_sub_f32_e32 v68, v68, v176
	v_sub_f32_e32 v69, v69, v176
	v_sub_f32_e32 v70, v70, v176
	v_sub_f32_e32 v71, v71, v176
	v_sub_f32_e32 v72, v72, v176
	v_sub_f32_e32 v73, v73, v176
	v_sub_f32_e32 v74, v74, v176
	v_sub_f32_e32 v75, v75, v176
	v_sub_f32_e32 v76, v76, v176
	v_sub_f32_e32 v77, v77, v176
	v_sub_f32_e32 v78, v78, v176
	v_sub_f32_e32 v79, v79, v176
	v_sub_f32_e32 v80, v80, v176
	v_sub_f32_e32 v81, v81, v176
	v_sub_f32_e32 v82, v82, v176
	v_sub_f32_e32 v83, v83, v176
	v_sub_f32_e32 v84, v84, v176
	v_sub_f32_e32 v85, v85, v176
	v_sub_f32_e32 v86, v86, v176
	v_sub_f32_e32 v87, v87, v176
	v_sub_f32_e32 v88, v88, v176
	v_sub_f32_e32 v89, v89, v176
	v_sub_f32_e32 v90, v90, v176
	v_sub_f32_e32 v91, v91, v176
	v_sub_f32_e32 v92, v92, v176
	v_sub_f32_e32 v93, v93, v176
	v_sub_f32_e32 v94, v94, v176
	v_sub_f32_e32 v95, v95, v176
	v_mul_f32_e32 v192, v192, v177
	v_mul_f32_e32 v193, v193, v177
	s_branch .Lma_backA_0
